# v33 + drop m0 save/restore around the 224 GEMM LDS-DMA loads
# baseline (speedup 1.0000x reference)
; #define PG8_STAGEX(pb, gbase) glds16_s(voffX, (const void*)(gbase), ldsbase + (unsigned)(XOFF + (pb) * 4096) + ldsx)
; __device__ __forceinline__ void glds16_s(unsigned voff, const void* sbase, unsigned lds_dst) { unsigned keep;
; template <class Epi, class Sched, bool HM = false>
; __device__ __forceinline__ void gemm_phase(PG8_LAS unsigned char* lds, const Gemm g, const Sched& S, const Epi& E) {
;     ...
;     for (int i = 0; i < 2; ++i) { int R, C; stage_rc(tid * 16 + i * 8192, R, C); const int Rb = Epi::PERM ? ((R & ~31) + perm32(R & 31)) : R;
;         voffA[i] = (unsigned)(R * g.lda + C) * 2u; voffB[i] = (unsigned)(Rb * g.ldb + C) * 2u; }
;     const unsigned voffX = (unsigned)((4 * (wid & 3) + (lane >> 4)) * g.lda + 8 * (lane & 15)) * 2u;
;     const size_t kstep = (size_t)(BK * 2);
;     const size_t hstepA = (size_t)HALF * g.lda * 2, hstepB = (size_t)HALF * g.ldb * 2;
;     const size_t tstepA = (size_t)(HM ? HALF : g.pms) * g.lda * 2, tstepB = 2 * hstepB, xstep = 2 * hstepA; const bool hasx = g.pms != BM;
;     const unsigned ldsw = (unsigned)wid * 1024u, ldsx = (unsigned)(wid & 3) * 1024u;
;     const unsigned ldsbase = (unsigned)__builtin_amdgcn_readfirstlane((int)(unsigned)(__UINTPTR_TYPE__)lds);
;     const int aoff = lds_byte(wr * 64 + fr, fq * 8), boff = lds_byte(wc * 32 + fr, fq * 8);
;     const int xoff = XOFF + fr * 256 + fq * 16;
;     ...
;     Unit cur, nxt; int ui = 0;
;     if (!S.next(0, cur)) return;
;     f32x4 acc[2][2][4][2]; f32x4 accx[2];
; #pragma unroll
;     for (int a = 0; a < 2; ++a)
; #pragma unroll
;         for (int b = 0; b < 2; ++b)
; #pragma unroll
;             for (int m = 0; m < 4; ++m)
; #pragma unroll
;                 for (int n = 0; n < 2; ++n) acc[a][b][m][n] = (f32x4){0.f, 0.f, 0.f, 0.f};
;     accx[0] = (f32x4){0.f, 0.f, 0.f, 0.f}; accx[1] = accx[0];
;     bf16x8 At[4][2], B0[2][2], B1[2][2], Ax[2];
;     const char* cA = PG8_APTR(cur); const char* cB = PG8_BPTR(cur);
;     S.a_ready(cur);
;     PG8_STAGE(PG8_SB(0, 0), cB, voffB); PG8_STAGE(PG8_SB(0, 1), cB + hstepB, voffB); PG8_STAGE(PG8_SA(0, 0), cA, voffA); PG8_STAGEX(0, cA + xstep); PG8_STAGE(PG8_SA(0, 1), cA + hstepA, voffA);
;     if (wr == 1) PG8_BAR;
;     PG8_WAIT_V(2); PG8_BAR;
;     PG8_STAGE(PG8_SB(1, 0), cB + kstep, voffB); PG8_STAGE(PG8_SA(1, 0), cA + kstep, voffA); PG8_STAGE(PG8_SB(1, 1), cB + hstepB + kstep, voffB);
;     PG8_WAIT_V(6); PG8_BAR;
.LBB0_237:
	s_mov_b64 s[0:1], s[30:31]
	s_mov_b64 s[4:5], s[30:31]
	s_mov_b64 s[8:9], s[30:31]
	s_waitcnt vmcnt(0)
	v_mov_b32_e32 v4, v0
	s_andn2_b64 vcc, exec, s[96:97]
	v_readfirstlane_b32 s20, v4
	s_cbranch_vccnz .LBB0_236
	v_bfe_i32 v7, v4, 27, 1
	v_lshlrev_b32_e32 v5, 4, v4
	v_lshrrev_b32_e32 v7, 22, v7
	v_add_u32_e32 v7, v5, v7
	v_and_b32_e32 v7, 0xfffffc00, v7
	v_sub_u32_e32 v7, v5, v7
	v_ashrrev_i32_e32 v6, 31, v4
	v_lshrrev_b32_e32 v8, 4, v7
	v_lshrrev_b32_e32 v6, 26, v6
	v_bitop3_b32 v7, v8, v7, 32 bitop3:0x6c
	v_add_u32_e32 v6, v4, v6
	v_ashrrev_i32_e32 v9, 31, v7
	v_ashrrev_i32_e32 v6, 6, v6
	v_lshrrev_b32_e32 v9, 26, v9
	v_lshlrev_b32_e32 v8, 3, v6
	v_add_u32_e32 v9, v7, v9
	v_and_b32_e32 v8, -16, v8
	v_ashrrev_i32_e32 v10, 6, v9
	v_and_b32_e32 v9, 0xc0, v9
	s_add_u32 s13, s0, 0x1a1e4000
	v_add_u32_e32 v8, v10, v8
	v_sub_u32_e32 v7, v7, v9
	s_addc_u32 s14, s1, 0
	v_lshlrev_b32_e32 v6, 5, v6
	v_ashrrev_i16_sdwa v7, v1, sext(v7) dst_sel:DWORD dst_unused:UNUSED_PAD src0_sel:DWORD src1_sel:BYTE_0
	v_lshlrev_b32_e32 v9, 1, v8
	v_lshrrev_b32_e32 v11, 2, v8
	v_and_b32_e32 v10, 3, v10
	s_mov_b32 s1, 0x3fffe0
	v_and_b32_e32 v6, 32, v6
	v_bfe_i32 v7, v7, 0, 16
	v_and_b32_e32 v9, 24, v9
	v_and_b32_e32 v11, 4, v11
	v_and_or_b32 v10, v8, s1, v10
	v_or3_b32 v9, v10, v11, v9
	v_add_lshl_u32 v6, v6, v7, 1
	v_add_u32_e32 v5, 0x2000, v5
	v_lshl_add_u32 v225, v8, 12, v6
	v_lshl_add_u32 v226, v9, 10, v6
	v_ashrrev_i32_e32 v6, 31, v5
	v_lshrrev_b32_e32 v6, 22, v6
	v_add_u32_e32 v6, v5, v6
	v_ashrrev_i32_e32 v6, 10, v6
	v_mul_i32_i24_e32 v7, 0x400, v6
	v_sub_u32_e32 v5, v5, v7
	v_lshrrev_b32_e32 v7, 4, v5
	v_bitop3_b32 v5, v7, v5, 32 bitop3:0x6c
	v_ashrrev_i32_e32 v8, 31, v5
	v_lshrrev_b32_e32 v8, 26, v8
	s_add_u32 s15, s4, 0x15aa0000
	v_lshlrev_b32_e32 v7, 3, v6
	v_add_u32_e32 v8, v5, v8
	s_addc_u32 s16, s5, 0
	s_ashr_i32 s0, s20, 6
	v_and_b32_e32 v7, -16, v7
	v_ashrrev_i32_e32 v9, 6, v8
	v_and_b32_e32 v8, 0xc0, v8
	s_and_b32 s21, s0, 3
	v_add_u32_e32 v7, v9, v7
	v_sub_u32_e32 v5, v5, v8
	v_and_b32_e32 v9, 3, v9
	v_lshlrev_b32_e32 v6, 5, v6
	v_ashrrev_i16_sdwa v5, v1, sext(v5) dst_sel:DWORD dst_unused:UNUSED_PAD src0_sel:DWORD src1_sel:BYTE_0
	v_lshlrev_b32_e32 v8, 1, v7
	v_lshrrev_b32_e32 v10, 2, v7
	v_and_or_b32 v9, v7, s1, v9
	s_ashr_i32 s22, s20, 8
	s_lshl_b32 s1, s21, 14
	s_lshl_b32 s0, s0, 10
	s_lshl_b32 s23, s21, 10
	v_readlane_b32 s4, v254, 34
	v_and_b32_e32 v6, 32, v6
	v_bfe_i32 v5, v5, 0, 16
	v_and_b32_e32 v8, 24, v8
	v_and_b32_e32 v10, 4, v10
	v_readlane_b32 s5, v254, 35
	s_add_u32 s4, s15, s4
	v_bfe_u32 v2, v4, 4, 2
	v_or3_b32 v8, v9, v10, v8
	v_add_lshl_u32 v5, v6, v5, 1
	v_and_b32_e32 v4, 15, v4
	s_addc_u32 s5, s16, s5
	s_add_i32 s17, s0, 0
	v_lshl_add_u32 v227, v7, 12, v5
	v_lshl_add_u32 v228, v8, 10, v5
	v_lshlrev_b32_e32 v5, 4, v4
	v_lshlrev_b32_e32 v6, 12, v2
	s_add_i32 s18, s17, 0x10000
	s_mov_b32 m0, s18
	s_nop 0
	global_load_lds_dwordx4 v226, s[4:5]
	v_or3_b32 v229, s1, v6, v5
	v_lshrrev_b32_e32 v232, 8, v229
	v_and_b32_e32 v232, 0xf0, v232
	v_xor_b32_e32 v229, v229, v232
	s_add_i32 s19, s17, 0x12000
	s_mov_b32 m0, s19
	s_nop 0
	global_load_lds_dwordx4 v228, s[4:5]
	v_readlane_b32 s1, v254, 23
	s_mul_i32 s0, s1, s10
	s_add_u32 s6, s13, s0
	s_mul_hi_i32 s0, s1, s10
	s_addc_u32 s7, s14, s0
	s_add_u32 s0, s4, 0x20000
	s_addc_u32 s1, s5, 0
	s_add_i32 s24, s17, 0x14000
	s_mov_b32 m0, s24
	s_nop 0
	global_load_lds_dwordx4 v226, s[0:1]
	s_add_i32 s25, s17, 0x16000
	s_mov_b32 m0, s25
	s_nop 0
	global_load_lds_dwordx4 v228, s[0:1]
	v_readlane_b32 s0, v254, 32
	v_readlane_b32 s1, v254, 33
	s_add_u32 s6, s6, s0
	s_addc_u32 s7, s7, s1
	s_mov_b32 m0, s17
	s_nop 0
	global_load_lds_dwordx4 v225, s[6:7]
	s_add_i32 s28, s17, 0x2000
	s_mov_b32 m0, s28
	s_nop 0
	global_load_lds_dwordx4 v227, s[6:7]
	s_add_u32 s0, s6, 0x100000
	s_addc_u32 s1, s7, 0
	s_add_i32 s29, s23, 0
	s_add_i32 s23, s29, 0x20400
	s_mov_b32 m0, s23
	s_nop 0
	global_load_lds_dwordx4 v229, s[0:1]
	s_add_u32 s0, s6, 0x80000
	s_addc_u32 s1, s7, 0
	s_add_i32 s30, s17, 0x4000
	s_mov_b32 m0, s30
	s_nop 0
	global_load_lds_dwordx4 v225, s[0:1]
	s_add_i32 s31, s17, 0x6000
	s_mov_b32 m0, s31
	s_nop 0
	global_load_lds_dwordx4 v227, s[0:1]
	s_cmp_eq_u32 s22, 1
	s_cselect_b64 s[0:1], -1, 0
	s_cmp_lg_u32 s22, 1
	s_cbranch_scc1 .LBB0_240
	s_barrier
.LBB0_240:
	s_add_u32 s46, s8, 0x35e04000
	v_lshlrev_b32_e32 v5, 3, v2
	v_lshlrev_b32_e32 v2, 4, v2
	v_lshlrev_b32_e32 v7, 2, v4
	s_addc_u32 s47, s9, 0
	v_lshl_or_b32 v6, v4, 6, v2
	s_lshl_b32 s8, s22, 13
	v_and_b32_e32 v7, 32, v7
	v_bitop3_b32 v8, v6, s8, v7 bitop3:0xde
	s_lshl_b32 s8, s21, 12
	v_bitop3_b32 v6, v6, s8, v7 bitop3:0xde
	s_add_u32 s8, s4, 0x80
	s_waitcnt vmcnt(2)
	s_barrier
	s_addc_u32 s9, s5, 0
	s_add_i32 s36, s17, 0x18000
	s_mov_b32 m0, s36
	s_nop 0
	global_load_lds_dwordx4 v226, s[8:9]
	s_add_i32 s37, s17, 0x1a000
	s_mov_b32 m0, s37
	s_nop 0
	global_load_lds_dwordx4 v228, s[8:9]
	s_add_u32 s8, s6, 0x80
	s_addc_u32 s9, s7, 0
	s_add_i32 s51, s17, 0x8000
	s_mov_b32 m0, s51
	s_nop 0
	global_load_lds_dwordx4 v225, s[8:9]
	s_add_i32 s52, s17, 0xa000
	s_mov_b32 m0, s52
	s_nop 0
	global_load_lds_dwordx4 v227, s[8:9]
	s_add_u32 s8, s4, 0x20080
	s_addc_u32 s9, s5, 0
	s_add_i32 s57, s17, 0x1c000
	s_mov_b32 m0, s57
	s_nop 0
	global_load_lds_dwordx4 v226, s[8:9]
	s_add_i32 s58, s17, 0x1e000
	s_add_i32 s59, s17, 0xc000
	s_mov_b32 m0, s58
	s_nop 0
	global_load_lds_dwordx4 v228, s[8:9]
	s_cmpk_lt_u32 s20, 0x100
	s_waitcnt vmcnt(6)
	s_cselect_b64 s[74:75], -1, 0
	s_cmpk_gt_u32 s20, 0xff
	v_lshl_or_b32 v231, s21, 5, v5
	v_lshl_add_u32 v5, v4, 8, 0
	s_mov_b32 s8, 0x20400
	s_cselect_b64 s[76:77], -1, 0
	s_lshl_b32 s78, s22, 2
	v_lshl_or_b32 v230, s22, 6, v4
	v_lshlrev_b32_e32 v232, 4, v4
	v_xor_b32_e32 v232, v232, v2
	v_add3_u32 v232, v5, v232, s8
	v_or_b32_e32 v233, 0x100, v4
	s_ashr_i32 s79, s78, 31
	s_add_i32 s83, s17, 0xe000
	s_mov_b32 s88, 0
	v_add_u32_e32 v234, 0, v6
	v_add_u32_e32 v235, 0, v8
	v_readlane_b32 s60, v254, 40
	v_readlane_b32 s61, v254, 23
	s_barrier
	s_branch .LBB0_243

; #define PG8_STAGE(bufoff, gbase, voff) do { _Pragma("unroll") for (int _i = 0; _i < 2; ++_i) glds16_s((voff)[_i], (const void*)(gbase), ldsbase + (unsigned)((bufoff) + _i * 8192) + ldsw); } while (0)
; #define PG8_LDA(dst, b, h) do { _Pragma("unroll") for (int m = 0; m < 4; ++m) _Pragma("unroll") for (int k = 0; k < 2; ++k) dst[m][k] = *(const PG8_LAS bf16x8*)(lds + PG8_SA(b, h) + aoff + m * 2048 + k * 1024); } while (0)
; #define PG8_MMA(ai, bj, At, Bt) do { __builtin_amdgcn_s_setprio(1); _Pragma("unroll") for (int m = 0; m < 4; ++m) _Pragma("unroll") for (int n = 0; n < 2; ++n) _Pragma("unroll") for (int k = 0; k < 2; ++k) \
;         acc[ai][bj][m][n] = __builtin_amdgcn_mfma_f32_16x16x32_bf16(Bt[n][k], At[m][k], acc[ai][bj][m][n], 0, 0, 0); __builtin_amdgcn_s_setprio(0); } while (0)
; #define PG8_WAIT_V(n) asm volatile("s_waitcnt vmcnt(" #n ")" ::: "memory")
; #define PG8_WAIT_L(n) asm volatile("s_waitcnt lgkmcnt(" #n ")" ::: "memory")
; #define PG8_BAR __builtin_amdgcn_s_barrier()
; #define PG8_SCHED __builtin_amdgcn_sched_barrier(0)
; template <class Epi, class Sched, bool HM = false>
; __device__ __forceinline__ void gemm_phase(PG8_LAS unsigned char* lds, const Gemm g, const Sched& S, const Epi& E) {
;     ...
;             if (!HM) PG8_LDA(At, 1, 1); PG8_STAGE(PG8_SB(1, 0), b3, voffB); PG8_STAGE(PG8_SB(1, 1), b3 + hstepB, voffB); PG8_STAGE(PG8_SA(1, 0), a3, voffA);
;             PG8_WAIT_V(8); PG8_WAIT_L(0); PG8_BAR; if (!HM) { PG8_MMA(1, 0, At, B0); PG8_MMA(1, 1, At, B1); } PG8_BAR; PG8_SCHED;
;         }
.LBB0_254:
.LBB0_255:
	s_barrier
	ds_read_b128 v[182:185], v235 offset:49152
	ds_read_b128 v[186:189], v235 offset:50176
	ds_read_b128 v[190:193], v235 offset:51200
	ds_read_b128 v[194:197], v235 offset:52224
	ds_read_b128 v[198:201], v235 offset:53248
	ds_read_b128 v[202:205], v235 offset:54272
	ds_read_b128 v[206:209], v235 offset:55296
	ds_read_b128 v[210:213], v235 offset:56320
	s_mov_b32 m0, s36
	s_nop 0
	global_load_lds_dwordx4 v226, s[6:7]
	s_nop 0
	s_mov_b32 m0, s37
	s_nop 0
	global_load_lds_dwordx4 v228, s[6:7]
	s_add_u32 s6, s6, 0x20000
	s_addc_u32 s7, s7, 0
	s_mov_b32 m0, s57
	s_nop 0
	global_load_lds_dwordx4 v226, s[6:7]
	s_nop 0
	s_mov_b32 m0, s58
	s_nop 0
	global_load_lds_dwordx4 v228, s[6:7]
	s_mov_b32 m0, s51
	s_nop 0
	global_load_lds_dwordx4 v225, s[4:5]
	s_nop 0
	s_mov_b32 m0, s52
	s_nop 0
	global_load_lds_dwordx4 v227, s[4:5]
	s_waitcnt vmcnt(8)
	s_waitcnt lgkmcnt(0)
	s_barrier
	s_setprio 1
	s_waitcnt lgkmcnt(7)
	v_mfma_f32_16x16x32_bf16 v[82:85], v[166:169], v[182:185], v[82:85]
	v_mfma_f32_16x16x32_bf16 v[78:81], v[174:177], v[182:185], v[78:81]
	s_waitcnt lgkmcnt(5)
	v_mfma_f32_16x16x32_bf16 v[74:77], v[166:169], v[190:193], v[74:77]
	v_mfma_f32_16x16x32_bf16 v[66:69], v[174:177], v[190:193], v[66:69]
	s_waitcnt lgkmcnt(3)
	v_mfma_f32_16x16x32_bf16 v[58:61], v[166:169], v[198:201], v[58:61]
	v_mfma_f32_16x16x32_bf16 v[50:53], v[174:177], v[198:201], v[50:53]
	s_waitcnt lgkmcnt(1)
	v_mfma_f32_16x16x32_bf16 v[42:45], v[166:169], v[206:209], v[42:45]
	v_mfma_f32_16x16x32_bf16 v[34:37], v[174:177], v[206:209], v[34:37]
	v_mfma_f32_16x16x32_bf16 v[82:85], v[170:173], v[186:189], v[82:85]
	v_mfma_f32_16x16x32_bf16 v[78:81], v[178:181], v[186:189], v[78:81]
	v_mfma_f32_16x16x32_bf16 v[74:77], v[170:173], v[194:197], v[74:77]
	v_mfma_f32_16x16x32_bf16 v[66:69], v[178:181], v[194:197], v[66:69]
	v_mfma_f32_16x16x32_bf16 v[58:61], v[170:173], v[202:205], v[58:61]
	v_mfma_f32_16x16x32_bf16 v[50:53], v[178:181], v[202:205], v[50:53]
	s_waitcnt lgkmcnt(0)
	v_mfma_f32_16x16x32_bf16 v[42:45], v[170:173], v[210:213], v[42:45]
	v_mfma_f32_16x16x32_bf16 v[34:37], v[178:181], v[210:213], v[34:37]
	s_setprio 0
	s_setprio 1
	v_mfma_f32_16x16x32_bf16 v[70:73], v[150:153], v[182:185], v[70:73]
	v_mfma_f32_16x16x32_bf16 v[62:65], v[158:161], v[182:185], v[62:65]
	v_mfma_f32_16x16x32_bf16 v[54:57], v[150:153], v[190:193], v[54:57]
	v_mfma_f32_16x16x32_bf16 v[46:49], v[158:161], v[190:193], v[46:49]
	v_mfma_f32_16x16x32_bf16 v[38:41], v[150:153], v[198:201], v[38:41]
	v_mfma_f32_16x16x32_bf16 v[30:33], v[158:161], v[198:201], v[30:33]
	v_mfma_f32_16x16x32_bf16 v[26:29], v[150:153], v[206:209], v[26:29]
	v_mfma_f32_16x16x32_bf16 v[22:25], v[158:161], v[206:209], v[22:25]
	v_mfma_f32_16x16x32_bf16 v[70:73], v[154:157], v[186:189], v[70:73]
	v_mfma_f32_16x16x32_bf16 v[62:65], v[162:165], v[186:189], v[62:65]
	v_mfma_f32_16x16x32_bf16 v[54:57], v[154:157], v[194:197], v[54:57]
	v_mfma_f32_16x16x32_bf16 v[46:49], v[162:165], v[194:197], v[46:49]
	v_mfma_f32_16x16x32_bf16 v[38:41], v[154:157], v[202:205], v[38:41]
	v_mfma_f32_16x16x32_bf16 v[30:33], v[162:165], v[202:205], v[30:33]
	v_mfma_f32_16x16x32_bf16 v[26:29], v[154:157], v[210:213], v[26:29]
	v_mfma_f32_16x16x32_bf16 v[22:25], v[162:165], v[210:213], v[22:25]
	s_setprio 0
	s_barrier
	s_add_i32 s23, s23, 2
	s_addk_i32 s22, 0x1000
	s_add_u32 s95, s95, 0x100
	s_addc_u32 s38, s38, 0
	s_add_u32 s27, s27, 0x100
	s_addc_u32 s39, s39, 0
	s_cmp_gt_u32 s23, 5
	s_cbranch_scc1 .LBB0_271

; #define PG8_STAGE(bufoff, gbase, voff) do { _Pragma("unroll") for (int _i = 0; _i < 2; ++_i) glds16_s((voff)[_i], (const void*)(gbase), ldsbase + (unsigned)((bufoff) + _i * 8192) + ldsw); } while (0)
; #define PG8_STAGEX(pb, gbase) glds16_s(voffX, (const void*)(gbase), ldsbase + (unsigned)(XOFF + (pb) * 4096) + ldsx)
; #define PG8_LDA(dst, b, h) do { _Pragma("unroll") for (int m = 0; m < 4; ++m) _Pragma("unroll") for (int k = 0; k < 2; ++k) dst[m][k] = *(const PG8_LAS bf16x8*)(lds + PG8_SA(b, h) + aoff + m * 2048 + k * 1024); } while (0)
; #define PG8_LDB(dst, b, h) do { _Pragma("unroll") for (int n = 0; n < 2; ++n) _Pragma("unroll") for (int k = 0; k < 2; ++k) dst[n][k] = *(const PG8_LAS bf16x8*)(lds + PG8_SB(b, h) + boff + n * 2048 + k * 1024); } while (0)
; #define PG8_LDX(pb, tp) do { _Pragma("unroll") for (int k = 0; k < 2; ++k) Ax[k] = *(const PG8_LAS bf16x8*)(lds + xoff + (pb) * 4096 + (tp) * 128 + k * 64); } while (0)
; #define PG8_MMA(ai, bj, At, Bt) do { __builtin_amdgcn_s_setprio(1); _Pragma("unroll") for (int m = 0; m < 4; ++m) _Pragma("unroll") for (int n = 0; n < 2; ++n) _Pragma("unroll") for (int k = 0; k < 2; ++k) \
;         acc[ai][bj][m][n] = __builtin_amdgcn_mfma_f32_16x16x32_bf16(Bt[n][k], At[m][k], acc[ai][bj][m][n], 0, 0, 0); __builtin_amdgcn_s_setprio(0); } while (0)
; #define PG8_WAIT_V(n) asm volatile("s_waitcnt vmcnt(" #n ")" ::: "memory")
; #define PG8_WAIT_L(n) asm volatile("s_waitcnt lgkmcnt(" #n ")" ::: "memory")
; #define PG8_BAR __builtin_amdgcn_s_barrier()
; #define PG8_SCHED __builtin_amdgcn_sched_barrier(0)
; template <class Epi, class Sched, bool HM = false>
; __device__ __forceinline__ void gemm_phase(PG8_LAS unsigned char* lds, const Gemm g, const Sched& S, const Epi& E) {
;     ...
;             PG8_LDB(B0, 0, 0); PG8_LDB(B1, 0, 1); PG8_SCHED; PG8_LDA(At, 0, 0); if (hasx) PG8_LDX(pb, 0); PG8_STAGE(PG8_SA(1, 1), a1 + hstepA, voffA); PG8_STAGEX(pb ^ 1, a2 + xstep);
;             PG8_WAIT_V(9); PG8_WAIT_L(0); PG8_BAR; PG8_MMA(0, 0, At, B0); PG8_MMA(0, 1, At, B1); if (hasx) PG8_MMAX(); PG8_BAR; PG8_SCHED;
.LBB0_258:
	s_add_u32 s34, s34, 0x80000
	s_addc_u32 s35, s35, 0
	s_mov_b32 m0, s59
	s_nop 0
	global_load_lds_dwordx4 v225, s[34:35]
	s_nop 0
	s_mov_b32 m0, s83
	s_nop 0
	global_load_lds_dwordx4 v227, s[34:35]
	s_add_u32 s34, s92, 0x100000
	s_addc_u32 s35, s93, 0
	s_xor_b32 s20, s20, 0x21400
	s_add_i32 s20, s29, s20
	s_mov_b32 m0, s20
	s_nop 0
	global_load_lds_dwordx4 v229, s[34:35]
	s_waitcnt vmcnt(9)
	s_waitcnt lgkmcnt(0)
	s_barrier
	s_setprio 1
	s_waitcnt lgkmcnt(7)
	v_mfma_f32_16x16x32_bf16 v[146:149], v[166:169], v[206:209], v[146:149]
	v_mfma_f32_16x16x32_bf16 v[142:145], v[174:177], v[206:209], v[142:145]
	s_waitcnt lgkmcnt(5)
	v_mfma_f32_16x16x32_bf16 v[138:141], v[166:169], v[198:201], v[138:141]
	v_mfma_f32_16x16x32_bf16 v[130:133], v[174:177], v[198:201], v[130:133]
	s_waitcnt lgkmcnt(3)
	v_mfma_f32_16x16x32_bf16 v[122:125], v[166:169], v[190:193], v[122:125]
	v_mfma_f32_16x16x32_bf16 v[114:117], v[174:177], v[190:193], v[114:117]
	s_waitcnt lgkmcnt(1)
	v_mfma_f32_16x16x32_bf16 v[106:109], v[166:169], v[182:185], v[106:109]
	v_mfma_f32_16x16x32_bf16 v[98:101], v[174:177], v[182:185], v[98:101]
	v_mfma_f32_16x16x32_bf16 v[146:149], v[170:173], v[210:213], v[146:149]
	v_mfma_f32_16x16x32_bf16 v[142:145], v[178:181], v[210:213], v[142:145]
	v_mfma_f32_16x16x32_bf16 v[138:141], v[170:173], v[202:205], v[138:141]
	v_mfma_f32_16x16x32_bf16 v[130:133], v[178:181], v[202:205], v[130:133]
	v_mfma_f32_16x16x32_bf16 v[122:125], v[170:173], v[194:197], v[122:125]
	v_mfma_f32_16x16x32_bf16 v[114:117], v[178:181], v[194:197], v[114:117]
	s_waitcnt lgkmcnt(0)
	v_mfma_f32_16x16x32_bf16 v[106:109], v[170:173], v[186:189], v[106:109]
	v_mfma_f32_16x16x32_bf16 v[98:101], v[178:181], v[186:189], v[98:101]
	s_setprio 0
	s_setprio 1
	v_mfma_f32_16x16x32_bf16 v[134:137], v[150:153], v[206:209], v[134:137]
	v_mfma_f32_16x16x32_bf16 v[126:129], v[158:161], v[206:209], v[126:129]
	v_mfma_f32_16x16x32_bf16 v[118:121], v[150:153], v[198:201], v[118:121]
	v_mfma_f32_16x16x32_bf16 v[110:113], v[158:161], v[198:201], v[110:113]
	v_mfma_f32_16x16x32_bf16 v[102:105], v[150:153], v[190:193], v[102:105]
	v_mfma_f32_16x16x32_bf16 v[94:97], v[158:161], v[190:193], v[94:97]
	v_mfma_f32_16x16x32_bf16 v[90:93], v[150:153], v[182:185], v[90:93]
	v_mfma_f32_16x16x32_bf16 v[86:89], v[158:161], v[182:185], v[86:89]
	v_mfma_f32_16x16x32_bf16 v[134:137], v[154:157], v[210:213], v[134:137]
	v_mfma_f32_16x16x32_bf16 v[126:129], v[162:165], v[210:213], v[126:129]
	v_mfma_f32_16x16x32_bf16 v[118:121], v[154:157], v[202:205], v[118:121]
	v_mfma_f32_16x16x32_bf16 v[110:113], v[162:165], v[202:205], v[110:113]
	v_mfma_f32_16x16x32_bf16 v[102:105], v[154:157], v[194:197], v[102:105]
	v_mfma_f32_16x16x32_bf16 v[94:97], v[162:165], v[194:197], v[94:97]
	v_mfma_f32_16x16x32_bf16 v[90:93], v[154:157], v[186:189], v[90:93]
	v_mfma_f32_16x16x32_bf16 v[86:89], v[162:165], v[186:189], v[86:89]
	s_setprio 0
	v_cndmask_b32_e64 v4, 0, 1, s[76:77]
	s_and_b64 vcc, exec, s[42:43]
	v_cmp_ne_u32_e64 s[44:45], 1, v4
	s_cbranch_vccnz .LBB0_264
	s_and_b64 vcc, exec, s[44:45]
	s_mov_b64 s[20:21], -1
	s_cbranch_vccnz .LBB0_261
	v_mfma_f32_16x16x32_bf16 v[18:21], v[174:177], v[6:9], v[18:21]
	s_mov_b64 s[20:21], 0
	v_mfma_f32_16x16x32_bf16 v[14:17], v[158:161], v[6:9], v[14:17]
	v_mfma_f32_16x16x32_bf16 v[18:21], v[178:181], v[10:13], v[18:21]
	v_mfma_f32_16x16x32_bf16 v[14:17], v[162:165], v[10:13], v[14:17]

; #define PG8_STAGE(bufoff, gbase, voff) do { _Pragma("unroll") for (int _i = 0; _i < 2; ++_i) glds16_s((voff)[_i], (const void*)(gbase), ldsbase + (unsigned)((bufoff) + _i * 8192) + ldsw); } while (0)
; #define PG8_LDA(dst, b, h) do { _Pragma("unroll") for (int m = 0; m < 4; ++m) _Pragma("unroll") for (int k = 0; k < 2; ++k) dst[m][k] = *(const PG8_LAS bf16x8*)(lds + PG8_SA(b, h) + aoff + m * 2048 + k * 1024); } while (0)
; #define PG8_LDB(dst, b, h) do { _Pragma("unroll") for (int n = 0; n < 2; ++n) _Pragma("unroll") for (int k = 0; k < 2; ++k) dst[n][k] = *(const PG8_LAS bf16x8*)(lds + PG8_SB(b, h) + boff + n * 2048 + k * 1024); } while (0)
; #define PG8_LDX(pb, tp) do { _Pragma("unroll") for (int k = 0; k < 2; ++k) Ax[k] = *(const PG8_LAS bf16x8*)(lds + xoff + (pb) * 4096 + (tp) * 128 + k * 64); } while (0)
; #define PG8_MMA(ai, bj, At, Bt) do { __builtin_amdgcn_s_setprio(1); _Pragma("unroll") for (int m = 0; m < 4; ++m) _Pragma("unroll") for (int n = 0; n < 2; ++n) _Pragma("unroll") for (int k = 0; k < 2; ++k) \
;         acc[ai][bj][m][n] = __builtin_amdgcn_mfma_f32_16x16x32_bf16(Bt[n][k], At[m][k], acc[ai][bj][m][n], 0, 0, 0); __builtin_amdgcn_s_setprio(0); } while (0)
; #define PG8_WAIT_V(n) asm volatile("s_waitcnt vmcnt(" #n ")" ::: "memory")
; #define PG8_WAIT_L(n) asm volatile("s_waitcnt lgkmcnt(" #n ")" ::: "memory")
; #define PG8_BAR __builtin_amdgcn_s_barrier()
; #define PG8_SCHED __builtin_amdgcn_sched_barrier(0)
; template <class Epi, class Sched, bool HM = false>
; __device__ __forceinline__ void gemm_phase(PG8_LAS unsigned char* lds, const Gemm g, const Sched& S, const Epi& E) {
;     ...
;             if (!HM) PG8_LDA(At, 0, 1); PG8_STAGE(PG8_SB(0, 0), b2, voffB); PG8_STAGE(PG8_SB(0, 1), b2 + hstepB, voffB); PG8_STAGE(PG8_SA(0, 0), a2, voffA);
;             PG8_WAIT_V(9); PG8_WAIT_L(0); PG8_BAR; if (!HM) { PG8_MMA(1, 0, At, B0); PG8_MMA(1, 1, At, B1); } PG8_BAR; PG8_SCHED;
;             PG8_LDB(B0, 1, 0); PG8_LDB(B1, 1, 1); PG8_SCHED; PG8_LDA(At, 1, 0); if (hasx) PG8_LDX(pb, 1); PG8_STAGE(PG8_SA(0, 1), a2 + hstepA, voffA);
.LBB0_263:
.LBB0_264:
	s_barrier
	ds_read_b128 v[182:185], v235 offset:16384
	ds_read_b128 v[186:189], v235 offset:17408
	ds_read_b128 v[190:193], v235 offset:18432
	ds_read_b128 v[194:197], v235 offset:19456
	ds_read_b128 v[198:201], v235 offset:20480
	ds_read_b128 v[202:205], v235 offset:21504
	ds_read_b128 v[206:209], v235 offset:22528
	ds_read_b128 v[210:213], v235 offset:23552
	s_mov_b32 m0, s18
	s_nop 0
	global_load_lds_dwordx4 v226, s[8:9]
	s_nop 0
	s_mov_b32 m0, s19
	s_nop 0
	global_load_lds_dwordx4 v228, s[8:9]
	s_add_u32 s8, s8, 0x20000
	s_addc_u32 s9, s9, 0
	s_mov_b32 m0, s24
	s_nop 0
	global_load_lds_dwordx4 v226, s[8:9]
	s_nop 0
	s_mov_b32 m0, s25
	s_nop 0
	global_load_lds_dwordx4 v228, s[8:9]
	s_mov_b32 m0, s17
	s_nop 0
	global_load_lds_dwordx4 v225, s[92:93]
	s_nop 0
	s_mov_b32 m0, s28
	s_nop 0
	global_load_lds_dwordx4 v227, s[92:93]
	s_waitcnt vmcnt(9)
	s_waitcnt lgkmcnt(0)
	s_barrier
	s_setprio 1
	s_waitcnt lgkmcnt(7)
	v_mfma_f32_16x16x32_bf16 v[82:85], v[166:169], v[182:185], v[82:85]
	v_mfma_f32_16x16x32_bf16 v[78:81], v[174:177], v[182:185], v[78:81]
	s_waitcnt lgkmcnt(5)
	v_mfma_f32_16x16x32_bf16 v[74:77], v[166:169], v[190:193], v[74:77]
	v_mfma_f32_16x16x32_bf16 v[66:69], v[174:177], v[190:193], v[66:69]
	s_waitcnt lgkmcnt(3)
	v_mfma_f32_16x16x32_bf16 v[58:61], v[166:169], v[198:201], v[58:61]
	v_mfma_f32_16x16x32_bf16 v[50:53], v[174:177], v[198:201], v[50:53]
	s_waitcnt lgkmcnt(1)
	v_mfma_f32_16x16x32_bf16 v[42:45], v[166:169], v[206:209], v[42:45]
	v_mfma_f32_16x16x32_bf16 v[34:37], v[174:177], v[206:209], v[34:37]
	v_mfma_f32_16x16x32_bf16 v[82:85], v[170:173], v[186:189], v[82:85]
	v_mfma_f32_16x16x32_bf16 v[78:81], v[178:181], v[186:189], v[78:81]
	v_mfma_f32_16x16x32_bf16 v[74:77], v[170:173], v[194:197], v[74:77]
	v_mfma_f32_16x16x32_bf16 v[66:69], v[178:181], v[194:197], v[66:69]
	v_mfma_f32_16x16x32_bf16 v[58:61], v[170:173], v[202:205], v[58:61]
	v_mfma_f32_16x16x32_bf16 v[50:53], v[178:181], v[202:205], v[50:53]
	s_waitcnt lgkmcnt(0)
	v_mfma_f32_16x16x32_bf16 v[42:45], v[170:173], v[210:213], v[42:45]
	v_mfma_f32_16x16x32_bf16 v[34:37], v[178:181], v[210:213], v[34:37]
	s_setprio 0
	s_setprio 1
	v_mfma_f32_16x16x32_bf16 v[70:73], v[150:153], v[182:185], v[70:73]
	v_mfma_f32_16x16x32_bf16 v[62:65], v[158:161], v[182:185], v[62:65]
	v_mfma_f32_16x16x32_bf16 v[54:57], v[150:153], v[190:193], v[54:57]
	v_mfma_f32_16x16x32_bf16 v[46:49], v[158:161], v[190:193], v[46:49]
	v_mfma_f32_16x16x32_bf16 v[38:41], v[150:153], v[198:201], v[38:41]
	v_mfma_f32_16x16x32_bf16 v[30:33], v[158:161], v[198:201], v[30:33]
	v_mfma_f32_16x16x32_bf16 v[26:29], v[150:153], v[206:209], v[26:29]
	v_mfma_f32_16x16x32_bf16 v[22:25], v[158:161], v[206:209], v[22:25]
	v_mfma_f32_16x16x32_bf16 v[70:73], v[154:157], v[186:189], v[70:73]
	v_mfma_f32_16x16x32_bf16 v[62:65], v[162:165], v[186:189], v[62:65]
	v_mfma_f32_16x16x32_bf16 v[54:57], v[154:157], v[194:197], v[54:57]
	v_mfma_f32_16x16x32_bf16 v[46:49], v[162:165], v[194:197], v[46:49]
	v_mfma_f32_16x16x32_bf16 v[38:41], v[154:157], v[202:205], v[38:41]
	v_mfma_f32_16x16x32_bf16 v[30:33], v[162:165], v[202:205], v[30:33]
	v_mfma_f32_16x16x32_bf16 v[26:29], v[154:157], v[210:213], v[26:29]
	v_mfma_f32_16x16x32_bf16 v[22:25], v[162:165], v[210:213], v[22:25]
	s_setprio 0
	s_barrier
	v_add_u32_e32 v4, 0x18000, v234
	ds_read_b128 v[166:169], v4
	ds_read_b128 v[170:173], v4 offset:1024
	ds_read_b128 v[174:177], v4 offset:2048
	ds_read_b128 v[178:181], v4 offset:3072
	v_add_u32_e32 v4, 0x1c000, v234
	ds_read_b128 v[150:153], v4
	ds_read_b128 v[154:157], v4 offset:1024
	ds_read_b128 v[158:161], v4 offset:2048
	ds_read_b128 v[162:165], v4 offset:3072
	ds_read_b128 v[206:209], v235 offset:32768
	ds_read_b128 v[210:213], v235 offset:33792
	ds_read_b128 v[198:201], v235 offset:34816
	ds_read_b128 v[202:205], v235 offset:35840
	ds_read_b128 v[190:193], v235 offset:36864
	ds_read_b128 v[194:197], v235 offset:37888
	ds_read_b128 v[182:185], v235 offset:38912
	ds_read_b128 v[186:189], v235 offset:39936
	s_and_b64 vcc, exec, s[42:43]
	s_cbranch_vccnz .LBB0_266
	v_xor_b32_e32 v6, 0x80, v2
	ds_read_b128 v[6:9], v6
	v_xor_b32_e32 v10, 0xc0, v2
	ds_read_b128 v[10:13], v10
; #define PG8_STAGE(bufoff, gbase, voff) do { _Pragma("unroll") for (int _i = 0; _i < 2; ++_i) glds16_s((voff)[_i], (const void*)(gbase), ldsbase + (unsigned)((bufoff) + _i * 8192) + ldsw); } while (0)
; #define PG8_LDA(dst, b, h) do { _Pragma("unroll") for (int m = 0; m < 4; ++m) _Pragma("unroll") for (int k = 0; k < 2; ++k) dst[m][k] = *(const PG8_LAS bf16x8*)(lds + PG8_SA(b, h) + aoff + m * 2048 + k * 1024); } while (0)
; #define PG8_LDB(dst, b, h) do { _Pragma("unroll") for (int n = 0; n < 2; ++n) _Pragma("unroll") for (int k = 0; k < 2; ++k) dst[n][k] = *(const PG8_LAS bf16x8*)(lds + PG8_SB(b, h) + boff + n * 2048 + k * 1024); } while (0)
; #define PG8_LDX(pb, tp) do { _Pragma("unroll") for (int k = 0; k < 2; ++k) Ax[k] = *(const PG8_LAS bf16x8*)(lds + xoff + (pb) * 4096 + (tp) * 128 + k * 64); } while (0)
; #define PG8_MMA(ai, bj, At, Bt) do { __builtin_amdgcn_s_setprio(1); _Pragma("unroll") for (int m = 0; m < 4; ++m) _Pragma("unroll") for (int n = 0; n < 2; ++n) _Pragma("unroll") for (int k = 0; k < 2; ++k) \
;         acc[ai][bj][m][n] = __builtin_amdgcn_mfma_f32_16x16x32_bf16(Bt[n][k], At[m][k], acc[ai][bj][m][n], 0, 0, 0); __builtin_amdgcn_s_setprio(0); } while (0)
; #define PG8_WAIT_V(n) asm volatile("s_waitcnt vmcnt(" #n ")" ::: "memory")
; #define PG8_WAIT_L(n) asm volatile("s_waitcnt lgkmcnt(" #n ")" ::: "memory")
; #define PG8_BAR __builtin_amdgcn_s_barrier()
; #define PG8_SCHED __builtin_amdgcn_sched_barrier(0)
; template <class Epi, class Sched, bool HM = false>
; __device__ __forceinline__ void gemm_phase(PG8_LAS unsigned char* lds, const Gemm g, const Sched& S, const Epi& E) {
;     ...
;             PG8_LDB(B0, 1, 0); PG8_LDB(B1, 1, 1); PG8_SCHED; PG8_LDA(At, 1, 0); if (hasx) PG8_LDX(pb, 1); PG8_STAGE(PG8_SA(0, 1), a2 + hstepA, voffA);
;             PG8_WAIT_V(9); PG8_WAIT_L(0); PG8_BAR; PG8_MMA(0, 0, At, B0); PG8_MMA(0, 1, At, B1); if (hasx) PG8_MMAX(); PG8_BAR; PG8_SCHED;
.LBB0_266:
	s_add_u32 s8, s92, 0x80000
	s_addc_u32 s9, s93, 0
	s_mov_b32 m0, s30
	s_nop 0
	global_load_lds_dwordx4 v225, s[8:9]
	s_nop 0
	s_mov_b32 m0, s31
	s_nop 0
	global_load_lds_dwordx4 v227, s[8:9]
	s_waitcnt vmcnt(9)
	s_waitcnt lgkmcnt(0)
	s_barrier
	s_setprio 1
	s_waitcnt lgkmcnt(7)
	v_mfma_f32_16x16x32_bf16 v[146:149], v[166:169], v[206:209], v[146:149]
	v_mfma_f32_16x16x32_bf16 v[142:145], v[174:177], v[206:209], v[142:145]
	s_waitcnt lgkmcnt(5)
	v_mfma_f32_16x16x32_bf16 v[138:141], v[166:169], v[198:201], v[138:141]
	v_mfma_f32_16x16x32_bf16 v[130:133], v[174:177], v[198:201], v[130:133]
	s_waitcnt lgkmcnt(3)
	v_mfma_f32_16x16x32_bf16 v[122:125], v[166:169], v[190:193], v[122:125]
	v_mfma_f32_16x16x32_bf16 v[114:117], v[174:177], v[190:193], v[114:117]
	s_waitcnt lgkmcnt(1)
	v_mfma_f32_16x16x32_bf16 v[106:109], v[166:169], v[182:185], v[106:109]
	v_mfma_f32_16x16x32_bf16 v[98:101], v[174:177], v[182:185], v[98:101]
	v_mfma_f32_16x16x32_bf16 v[146:149], v[170:173], v[210:213], v[146:149]
	v_mfma_f32_16x16x32_bf16 v[142:145], v[178:181], v[210:213], v[142:145]
	v_mfma_f32_16x16x32_bf16 v[138:141], v[170:173], v[202:205], v[138:141]
	v_mfma_f32_16x16x32_bf16 v[130:133], v[178:181], v[202:205], v[130:133]
	v_mfma_f32_16x16x32_bf16 v[122:125], v[170:173], v[194:197], v[122:125]
	v_mfma_f32_16x16x32_bf16 v[114:117], v[178:181], v[194:197], v[114:117]
	s_waitcnt lgkmcnt(0)
	v_mfma_f32_16x16x32_bf16 v[106:109], v[170:173], v[186:189], v[106:109]
	v_mfma_f32_16x16x32_bf16 v[98:101], v[178:181], v[186:189], v[98:101]
	s_setprio 0
	s_setprio 1
	v_mfma_f32_16x16x32_bf16 v[134:137], v[150:153], v[206:209], v[134:137]
	v_mfma_f32_16x16x32_bf16 v[126:129], v[158:161], v[206:209], v[126:129]
	v_mfma_f32_16x16x32_bf16 v[118:121], v[150:153], v[198:201], v[118:121]
	v_mfma_f32_16x16x32_bf16 v[110:113], v[158:161], v[198:201], v[110:113]
	v_mfma_f32_16x16x32_bf16 v[102:105], v[150:153], v[190:193], v[102:105]
	v_mfma_f32_16x16x32_bf16 v[94:97], v[158:161], v[190:193], v[94:97]
	v_mfma_f32_16x16x32_bf16 v[90:93], v[150:153], v[182:185], v[90:93]
	v_mfma_f32_16x16x32_bf16 v[86:89], v[158:161], v[182:185], v[86:89]
	v_mfma_f32_16x16x32_bf16 v[134:137], v[154:157], v[210:213], v[134:137]
	v_mfma_f32_16x16x32_bf16 v[126:129], v[162:165], v[210:213], v[126:129]
	v_mfma_f32_16x16x32_bf16 v[118:121], v[154:157], v[202:205], v[118:121]
	v_mfma_f32_16x16x32_bf16 v[110:113], v[162:165], v[202:205], v[110:113]
	v_mfma_f32_16x16x32_bf16 v[102:105], v[154:157], v[194:197], v[102:105]
	v_mfma_f32_16x16x32_bf16 v[94:97], v[162:165], v[194:197], v[94:97]
	v_mfma_f32_16x16x32_bf16 v[90:93], v[154:157], v[186:189], v[90:93]
	v_mfma_f32_16x16x32_bf16 v[86:89], v[162:165], v[186:189], v[86:89]
	s_setprio 0
	s_and_b64 vcc, exec, s[42:43]
	s_cbranch_vccnz .LBB0_255
	s_and_b64 vcc, exec, s[44:45]
	s_mov_b64 s[8:9], -1
	s_cbranch_vccnz .LBB0_269
	v_mfma_f32_16x16x32_bf16 v[18:21], v[174:177], v[6:9], v[18:21]
	s_mov_b64 s[8:9], 0
	v_mfma_f32_16x16x32_bf16 v[14:17], v[158:161], v[6:9], v[14:17]
	v_mfma_f32_16x16x32_bf16 v[18:21], v[178:181], v[10:13], v[18:21]
	v_mfma_f32_16x16x32_bf16 v[14:17], v[162:165], v[10:13], v[14:17]

; #define PG8_STAGE(bufoff, gbase, voff) do { _Pragma("unroll") for (int _i = 0; _i < 2; ++_i) glds16_s((voff)[_i], (const void*)(gbase), ldsbase + (unsigned)((bufoff) + _i * 8192) + ldsw); } while (0)
; template <class Epi, class Sched, bool HM = false>
; __device__ __forceinline__ void gemm_phase(PG8_LAS unsigned char* lds, const Gemm g, const Sched& S, const Epi& E) {
;     ...
;     for (int i = 0; i < 2; ++i) { int R, C; stage_rc(tid * 16 + i * 8192, R, C); const int Rb = Epi::PERM ? ((R & ~31) + perm32(R & 31)) : R;
;         voffA[i] = (unsigned)(R * g.lda + C) * 2u; voffB[i] = (unsigned)(Rb * g.ldb + C) * 2u; }
;     const unsigned voffX = (unsigned)((4 * (wid & 3) + (lane >> 4)) * g.lda + 8 * (lane & 15)) * 2u;
;     const size_t kstep = (size_t)(BK * 2);
;     const size_t hstepA = (size_t)HALF * g.lda * 2, hstepB = (size_t)HALF * g.ldb * 2;
;     const size_t tstepA = (size_t)(HM ? HALF : g.pms) * g.lda * 2, tstepB = 2 * hstepB, xstep = 2 * hstepA; const bool hasx = g.pms != BM;
;     const unsigned ldsw = (unsigned)wid * 1024u, ldsx = (unsigned)(wid & 3) * 1024u;
;     const unsigned ldsbase = (unsigned)__builtin_amdgcn_readfirstlane((int)(unsigned)(__UINTPTR_TYPE__)lds);
;     const int aoff = lds_byte(wr * 64 + fr, fq * 8), boff = lds_byte(wc * 32 + fr, fq * 8);
;     const int xoff = XOFF + fr * 256 + fq * 16;
;     ...
;     Unit cur, nxt; int ui = 0;
;     if (!S.next(0, cur)) return;
;     f32x4 acc[2][2][4][2]; f32x4 accx[2];
; #pragma unroll
;     for (int a = 0; a < 2; ++a)
; #pragma unroll
;         for (int b = 0; b < 2; ++b)
; #pragma unroll
;             for (int m = 0; m < 4; ++m)
; #pragma unroll
;                 for (int n = 0; n < 2; ++n) acc[a][b][m][n] = (f32x4){0.f, 0.f, 0.f, 0.f};
;     accx[0] = (f32x4){0.f, 0.f, 0.f, 0.f}; accx[1] = accx[0];
;     bf16x8 At[4][2], B0[2][2], B1[2][2], Ax[2];
;     const char* cA = PG8_APTR(cur); const char* cB = PG8_BPTR(cur);
;     S.a_ready(cur);
;     PG8_STAGE(PG8_SB(0, 0), cB, voffB); PG8_STAGE(PG8_SB(0, 1), cB + hstepB, voffB); PG8_STAGE(PG8_SA(0, 0), cA, voffA); PG8_STAGEX(0, cA + xstep); PG8_STAGE(PG8_SA(0, 1), cA + hstepA, voffA);
;     if (wr == 1) PG8_BAR;
;     PG8_WAIT_V(2); PG8_BAR;
;     PG8_STAGE(PG8_SB(1, 0), cB + kstep, voffB); PG8_STAGE(PG8_SA(1, 0), cA + kstep, voffA); PG8_STAGE(PG8_SB(1, 1), cB + hstepB + kstep, voffB);
;     PG8_WAIT_V(6); PG8_BAR;
.LBB0_515:
	s_mov_b64 s[0:1], s[30:31]
	s_mov_b64 s[4:5], s[30:31]
	s_mov_b64 s[8:9], s[30:31]
	s_waitcnt vmcnt(0)
	v_mov_b32_e32 v4, v0
	s_andn2_b64 vcc, exec, s[96:97]
	v_readfirstlane_b32 s20, v4
	s_cbranch_vccnz .LBB0_514
	v_bfe_i32 v7, v4, 27, 1
	v_lshlrev_b32_e32 v5, 4, v4
	v_lshrrev_b32_e32 v7, 22, v7
	v_add_u32_e32 v7, v5, v7
	v_and_b32_e32 v7, 0xfffffc00, v7
	v_sub_u32_e32 v7, v5, v7
	v_ashrrev_i32_e32 v6, 31, v4
	v_lshrrev_b32_e32 v8, 4, v7
	v_lshrrev_b32_e32 v6, 26, v6
	v_bitop3_b32 v7, v8, v7, 32 bitop3:0x6c
	s_add_u32 s14, s0, 0x1a1e4000
	v_add_u32_e32 v6, v4, v6
	v_ashrrev_i32_e32 v9, 31, v7
	s_addc_u32 s15, s1, 0
	v_ashrrev_i32_e32 v6, 6, v6
	v_lshrrev_b32_e32 v9, 26, v9
	s_add_u32 s0, s4, s12
	v_lshlrev_b32_e32 v8, 3, v6
	v_add_u32_e32 v9, v7, v9
	s_addc_u32 s1, s5, 0
	v_and_b32_e32 v8, -16, v8
	v_ashrrev_i32_e32 v10, 6, v9
	v_and_b32_e32 v9, 0xc0, v9
	s_add_u32 s16, s0, 0x42a0000
	v_add_u32_e32 v8, v10, v8
	v_sub_u32_e32 v7, v7, v9
	s_addc_u32 s17, s1, 0
	v_lshlrev_b32_e32 v6, 5, v6
	v_ashrrev_i16_sdwa v7, v1, sext(v7) dst_sel:DWORD dst_unused:UNUSED_PAD src0_sel:DWORD src1_sel:BYTE_0
	v_lshlrev_b32_e32 v9, 1, v8
	v_lshrrev_b32_e32 v11, 2, v8
	v_and_b32_e32 v10, 3, v10
	s_mov_b32 s1, 0xfffe0
	v_and_b32_e32 v6, 32, v6
	v_bfe_i32 v7, v7, 0, 16
	v_and_b32_e32 v9, 24, v9
	v_and_b32_e32 v11, 4, v11
	v_and_or_b32 v10, v8, s1, v10
	v_or3_b32 v9, v10, v11, v9
	v_add_lshl_u32 v6, v6, v7, 1
	v_add_u32_e32 v5, 0x2000, v5
	v_lshl_add_u32 v225, v8, 12, v6
	v_lshl_add_u32 v226, v9, 12, v6
	v_ashrrev_i32_e32 v6, 31, v5
	v_lshrrev_b32_e32 v6, 22, v6
	v_add_u32_e32 v6, v5, v6
	v_ashrrev_i32_e32 v6, 10, v6
	v_mul_i32_i24_e32 v7, 0x400, v6
	v_sub_u32_e32 v5, v5, v7
	v_lshrrev_b32_e32 v7, 4, v5
	v_bitop3_b32 v5, v7, v5, 32 bitop3:0x6c
	v_ashrrev_i32_e32 v8, 31, v5
	v_lshrrev_b32_e32 v8, 26, v8
	v_lshlrev_b32_e32 v7, 3, v6
	v_add_u32_e32 v8, v5, v8
	s_ashr_i32 s0, s20, 6
	v_and_b32_e32 v7, -16, v7
	v_ashrrev_i32_e32 v9, 6, v8
	v_and_b32_e32 v8, 0xc0, v8
	s_and_b32 s21, s0, 3
	v_add_u32_e32 v7, v9, v7
	v_sub_u32_e32 v5, v5, v8
	v_and_b32_e32 v9, 3, v9
	v_lshlrev_b32_e32 v6, 5, v6
	v_ashrrev_i16_sdwa v5, v1, sext(v5) dst_sel:DWORD dst_unused:UNUSED_PAD src0_sel:DWORD src1_sel:BYTE_0
	v_lshlrev_b32_e32 v8, 1, v7
	v_lshrrev_b32_e32 v10, 2, v7
	v_and_or_b32 v9, v7, s1, v9
	s_ashr_i32 s22, s20, 8
	s_lshl_b32 s1, s21, 14
	s_lshl_b32 s0, s0, 10
	s_lshl_b32 s23, s21, 10
	v_readlane_b32 s4, v254, 41
	v_and_b32_e32 v6, 32, v6
	v_bfe_i32 v5, v5, 0, 16
	v_and_b32_e32 v8, 24, v8
	v_and_b32_e32 v10, 4, v10
	v_readlane_b32 s5, v254, 42
	s_add_u32 s4, s16, s4
	v_bfe_u32 v2, v4, 4, 2
	v_or3_b32 v8, v9, v10, v8
	v_add_lshl_u32 v5, v6, v5, 1
	v_and_b32_e32 v4, 15, v4
	s_addc_u32 s5, s17, s5
	s_add_i32 s18, s0, 0
	v_lshl_add_u32 v227, v7, 12, v5
	v_lshl_add_u32 v228, v8, 12, v5
	v_lshlrev_b32_e32 v5, 4, v4
	v_lshlrev_b32_e32 v6, 12, v2
	s_add_i32 s19, s18, 0x10000
	s_mov_b32 m0, s19
	s_nop 0
	global_load_lds_dwordx4 v226, s[4:5]
	v_or3_b32 v229, s1, v6, v5
	v_lshrrev_b32_e32 v232, 8, v229
	v_and_b32_e32 v232, 0xf0, v232
	v_xor_b32_e32 v229, v229, v232
	s_add_i32 s24, s18, 0x12000
	s_mov_b32 m0, s24
	s_nop 0
	global_load_lds_dwordx4 v228, s[4:5]
	v_readlane_b32 s1, v254, 23
	s_mul_i32 s0, s1, s10
	s_add_u32 s6, s14, s0
	s_mul_hi_i32 s0, s1, s10
	s_addc_u32 s7, s15, s0
	s_add_u32 s0, s4, 0x80000
	s_addc_u32 s1, s5, 0
	s_add_i32 s25, s18, 0x14000
	s_mov_b32 m0, s25
	s_nop 0
	global_load_lds_dwordx4 v226, s[0:1]
	s_add_i32 s28, s18, 0x16000
	s_mov_b32 m0, s28
	s_nop 0
	global_load_lds_dwordx4 v228, s[0:1]
	v_readlane_b32 s0, v254, 38
	v_readlane_b32 s1, v254, 39
	s_add_u32 s6, s6, s0
	s_addc_u32 s7, s7, s1
	s_mov_b32 m0, s18
	s_nop 0
	global_load_lds_dwordx4 v225, s[6:7]
	s_add_i32 s29, s18, 0x2000
	s_mov_b32 m0, s29
	s_nop 0
	global_load_lds_dwordx4 v227, s[6:7]
	s_add_u32 s0, s6, 0x100000
	s_addc_u32 s1, s7, 0
	s_add_i32 s30, s23, 0
	s_add_i32 s23, s30, 0x20400
	s_mov_b32 m0, s23
	s_nop 0
	global_load_lds_dwordx4 v229, s[0:1]
	s_add_u32 s0, s6, 0x80000
	s_addc_u32 s1, s7, 0
	s_add_i32 s31, s18, 0x4000
	s_mov_b32 m0, s31
	s_nop 0
	global_load_lds_dwordx4 v225, s[0:1]
	s_add_i32 s36, s18, 0x6000
	s_mov_b32 m0, s36
	s_nop 0
	global_load_lds_dwordx4 v227, s[0:1]
	s_cmp_eq_u32 s22, 1
	s_cselect_b64 s[0:1], -1, 0
	s_cmp_lg_u32 s22, 1
	s_cbranch_scc1 .LBB0_518
	s_barrier
.LBB0_518:
	s_add_u32 s46, s8, 0x2de84000
	v_lshlrev_b32_e32 v5, 3, v2
	v_lshlrev_b32_e32 v2, 4, v2
	v_lshlrev_b32_e32 v7, 2, v4
	s_addc_u32 s47, s9, 0
	v_lshl_or_b32 v6, v4, 6, v2
	s_lshl_b32 s8, s22, 13
	v_and_b32_e32 v7, 32, v7
	v_bitop3_b32 v8, v6, s8, v7 bitop3:0xde
	s_lshl_b32 s8, s21, 12
	v_bitop3_b32 v6, v6, s8, v7 bitop3:0xde
	s_add_u32 s8, s4, 0x80
	s_waitcnt vmcnt(2)
	s_barrier
	s_addc_u32 s9, s5, 0
	s_add_i32 s37, s18, 0x18000
	s_mov_b32 m0, s37
	s_nop 0
	global_load_lds_dwordx4 v226, s[8:9]
	s_add_i32 s51, s18, 0x1a000
	s_mov_b32 m0, s51
	s_nop 0
	global_load_lds_dwordx4 v228, s[8:9]
	s_add_u32 s8, s6, 0x80
	s_addc_u32 s9, s7, 0
	s_add_i32 s52, s18, 0x8000
	s_mov_b32 m0, s52
	s_nop 0
	global_load_lds_dwordx4 v225, s[8:9]
	s_add_i32 s57, s18, 0xa000
	s_mov_b32 m0, s57
	s_nop 0
	global_load_lds_dwordx4 v227, s[8:9]
	s_add_u32 s8, s4, 0x80080
	s_addc_u32 s9, s5, 0
	s_add_i32 s58, s18, 0x1c000
	s_mov_b32 m0, s58
	s_nop 0
	global_load_lds_dwordx4 v226, s[8:9]
	s_add_i32 s59, s18, 0x1e000
	s_add_i32 s83, s18, 0xc000
	s_mov_b32 m0, s59
	s_nop 0
	global_load_lds_dwordx4 v228, s[8:9]
	s_cmpk_lt_u32 s20, 0x100
	s_waitcnt vmcnt(6)
	s_cselect_b64 s[76:77], -1, 0
	s_cmpk_gt_u32 s20, 0xff
	v_lshl_or_b32 v231, s21, 5, v5
	v_lshl_add_u32 v5, v4, 8, 0
	s_mov_b32 s8, 0x20400
	s_cselect_b64 s[78:79], -1, 0
	s_lshl_b32 s84, s22, 2
	v_lshl_or_b32 v230, s22, 6, v4
	v_lshlrev_b32_e32 v232, 4, v4
	v_xor_b32_e32 v232, v232, v2
	v_add3_u32 v232, v5, v232, s8
	v_or_b32_e32 v233, 0x100, v4
	s_ashr_i32 s85, s84, 31
	s_add_i32 s88, s18, 0xe000
	s_mov_b32 s89, 0
	v_add_u32_e32 v234, 0, v6
	v_add_u32_e32 v235, 0, v8
	v_readlane_b32 s60, v254, 40
	v_readlane_b32 s61, v254, 23
	s_barrier
	s_branch .LBB0_521

; #define PG8_STAGE(bufoff, gbase, voff) do { _Pragma("unroll") for (int _i = 0; _i < 2; ++_i) glds16_s((voff)[_i], (const void*)(gbase), ldsbase + (unsigned)((bufoff) + _i * 8192) + ldsw); } while (0)
; #define PG8_LDA(dst, b, h) do { _Pragma("unroll") for (int m = 0; m < 4; ++m) _Pragma("unroll") for (int k = 0; k < 2; ++k) dst[m][k] = *(const PG8_LAS bf16x8*)(lds + PG8_SA(b, h) + aoff + m * 2048 + k * 1024); } while (0)
; #define PG8_MMA(ai, bj, At, Bt) do { __builtin_amdgcn_s_setprio(1); _Pragma("unroll") for (int m = 0; m < 4; ++m) _Pragma("unroll") for (int n = 0; n < 2; ++n) _Pragma("unroll") for (int k = 0; k < 2; ++k) \
;         acc[ai][bj][m][n] = __builtin_amdgcn_mfma_f32_16x16x32_bf16(Bt[n][k], At[m][k], acc[ai][bj][m][n], 0, 0, 0); __builtin_amdgcn_s_setprio(0); } while (0)
; #define PG8_WAIT_V(n) asm volatile("s_waitcnt vmcnt(" #n ")" ::: "memory")
; #define PG8_WAIT_L(n) asm volatile("s_waitcnt lgkmcnt(" #n ")" ::: "memory")
; #define PG8_BAR __builtin_amdgcn_s_barrier()
; #define PG8_SCHED __builtin_amdgcn_sched_barrier(0)
; template <class Epi, class Sched, bool HM = false>
; __device__ __forceinline__ void gemm_phase(PG8_LAS unsigned char* lds, const Gemm g, const Sched& S, const Epi& E) {
;     ...
;             if (!HM) PG8_LDA(At, 1, 1); PG8_STAGE(PG8_SB(1, 0), b3, voffB); PG8_STAGE(PG8_SB(1, 1), b3 + hstepB, voffB); PG8_STAGE(PG8_SA(1, 0), a3, voffA);
;             PG8_WAIT_V(8); PG8_WAIT_L(0); PG8_BAR; if (!HM) { PG8_MMA(1, 0, At, B0); PG8_MMA(1, 1, At, B1); } PG8_BAR; PG8_SCHED;
;         }
.LBB0_532:
.LBB0_533:
	s_barrier
	ds_read_b128 v[182:185], v235 offset:49152
	ds_read_b128 v[186:189], v235 offset:50176
	ds_read_b128 v[190:193], v235 offset:51200
	ds_read_b128 v[194:197], v235 offset:52224
	ds_read_b128 v[198:201], v235 offset:53248
	ds_read_b128 v[202:205], v235 offset:54272
	ds_read_b128 v[206:209], v235 offset:55296
	ds_read_b128 v[210:213], v235 offset:56320
	s_mov_b32 m0, s37
	s_nop 0
	global_load_lds_dwordx4 v226, s[6:7]
	s_nop 0
	s_mov_b32 m0, s51
	s_nop 0
	global_load_lds_dwordx4 v228, s[6:7]
	s_add_u32 s6, s6, 0x80000
	s_addc_u32 s7, s7, 0
	s_mov_b32 m0, s58
	s_nop 0
	global_load_lds_dwordx4 v226, s[6:7]
	s_nop 0
	s_mov_b32 m0, s59
	s_nop 0
	global_load_lds_dwordx4 v228, s[6:7]
	s_mov_b32 m0, s52
	s_nop 0
	global_load_lds_dwordx4 v225, s[4:5]
	s_nop 0
	s_mov_b32 m0, s57
	s_nop 0
	global_load_lds_dwordx4 v227, s[4:5]
	s_waitcnt vmcnt(8)
	s_waitcnt lgkmcnt(0)
	s_barrier
	s_setprio 1
	s_waitcnt lgkmcnt(7)
	v_mfma_f32_16x16x32_bf16 v[82:85], v[166:169], v[182:185], v[82:85]
	v_mfma_f32_16x16x32_bf16 v[78:81], v[174:177], v[182:185], v[78:81]
	s_waitcnt lgkmcnt(5)
	v_mfma_f32_16x16x32_bf16 v[74:77], v[166:169], v[190:193], v[74:77]
	v_mfma_f32_16x16x32_bf16 v[66:69], v[174:177], v[190:193], v[66:69]
	s_waitcnt lgkmcnt(3)
	v_mfma_f32_16x16x32_bf16 v[58:61], v[166:169], v[198:201], v[58:61]
	v_mfma_f32_16x16x32_bf16 v[50:53], v[174:177], v[198:201], v[50:53]
	s_waitcnt lgkmcnt(1)
	v_mfma_f32_16x16x32_bf16 v[42:45], v[166:169], v[206:209], v[42:45]
	v_mfma_f32_16x16x32_bf16 v[34:37], v[174:177], v[206:209], v[34:37]
	v_mfma_f32_16x16x32_bf16 v[82:85], v[170:173], v[186:189], v[82:85]
	v_mfma_f32_16x16x32_bf16 v[78:81], v[178:181], v[186:189], v[78:81]
	v_mfma_f32_16x16x32_bf16 v[74:77], v[170:173], v[194:197], v[74:77]
	v_mfma_f32_16x16x32_bf16 v[66:69], v[178:181], v[194:197], v[66:69]
	v_mfma_f32_16x16x32_bf16 v[58:61], v[170:173], v[202:205], v[58:61]
	v_mfma_f32_16x16x32_bf16 v[50:53], v[178:181], v[202:205], v[50:53]
	s_waitcnt lgkmcnt(0)
	v_mfma_f32_16x16x32_bf16 v[42:45], v[170:173], v[210:213], v[42:45]
	v_mfma_f32_16x16x32_bf16 v[34:37], v[178:181], v[210:213], v[34:37]
	s_setprio 0
	s_setprio 1
	v_mfma_f32_16x16x32_bf16 v[70:73], v[150:153], v[182:185], v[70:73]
	v_mfma_f32_16x16x32_bf16 v[62:65], v[158:161], v[182:185], v[62:65]
	v_mfma_f32_16x16x32_bf16 v[54:57], v[150:153], v[190:193], v[54:57]
	v_mfma_f32_16x16x32_bf16 v[46:49], v[158:161], v[190:193], v[46:49]
	v_mfma_f32_16x16x32_bf16 v[38:41], v[150:153], v[198:201], v[38:41]
	v_mfma_f32_16x16x32_bf16 v[30:33], v[158:161], v[198:201], v[30:33]
	v_mfma_f32_16x16x32_bf16 v[26:29], v[150:153], v[206:209], v[26:29]
	v_mfma_f32_16x16x32_bf16 v[22:25], v[158:161], v[206:209], v[22:25]
	v_mfma_f32_16x16x32_bf16 v[70:73], v[154:157], v[186:189], v[70:73]
	v_mfma_f32_16x16x32_bf16 v[62:65], v[162:165], v[186:189], v[62:65]
	v_mfma_f32_16x16x32_bf16 v[54:57], v[154:157], v[194:197], v[54:57]
	v_mfma_f32_16x16x32_bf16 v[46:49], v[162:165], v[194:197], v[46:49]
	v_mfma_f32_16x16x32_bf16 v[38:41], v[154:157], v[202:205], v[38:41]
	v_mfma_f32_16x16x32_bf16 v[30:33], v[162:165], v[202:205], v[30:33]
	v_mfma_f32_16x16x32_bf16 v[26:29], v[154:157], v[210:213], v[26:29]
	v_mfma_f32_16x16x32_bf16 v[22:25], v[162:165], v[210:213], v[22:25]
	s_setprio 0
	s_barrier
	s_add_i32 s23, s23, 2
	s_addk_i32 s22, 0x1000
	s_add_u32 s38, s38, 0x100
	s_addc_u32 s39, s39, 0
	s_add_u32 s27, s27, 0x100
	s_addc_u32 s82, s82, 0
	s_cmp_gt_u32 s23, 29
	s_cbranch_scc1 .LBB0_549

; #define PG8_STAGE(bufoff, gbase, voff) do { _Pragma("unroll") for (int _i = 0; _i < 2; ++_i) glds16_s((voff)[_i], (const void*)(gbase), ldsbase + (unsigned)((bufoff) + _i * 8192) + ldsw); } while (0)
; #define PG8_STAGEX(pb, gbase) glds16_s(voffX, (const void*)(gbase), ldsbase + (unsigned)(XOFF + (pb) * 4096) + ldsx)
; #define PG8_LDA(dst, b, h) do { _Pragma("unroll") for (int m = 0; m < 4; ++m) _Pragma("unroll") for (int k = 0; k < 2; ++k) dst[m][k] = *(const PG8_LAS bf16x8*)(lds + PG8_SA(b, h) + aoff + m * 2048 + k * 1024); } while (0)
; #define PG8_LDB(dst, b, h) do { _Pragma("unroll") for (int n = 0; n < 2; ++n) _Pragma("unroll") for (int k = 0; k < 2; ++k) dst[n][k] = *(const PG8_LAS bf16x8*)(lds + PG8_SB(b, h) + boff + n * 2048 + k * 1024); } while (0)
; #define PG8_LDX(pb, tp) do { _Pragma("unroll") for (int k = 0; k < 2; ++k) Ax[k] = *(const PG8_LAS bf16x8*)(lds + xoff + (pb) * 4096 + (tp) * 128 + k * 64); } while (0)
; #define PG8_MMA(ai, bj, At, Bt) do { __builtin_amdgcn_s_setprio(1); _Pragma("unroll") for (int m = 0; m < 4; ++m) _Pragma("unroll") for (int n = 0; n < 2; ++n) _Pragma("unroll") for (int k = 0; k < 2; ++k) \
;         acc[ai][bj][m][n] = __builtin_amdgcn_mfma_f32_16x16x32_bf16(Bt[n][k], At[m][k], acc[ai][bj][m][n], 0, 0, 0); __builtin_amdgcn_s_setprio(0); } while (0)
; #define PG8_WAIT_V(n) asm volatile("s_waitcnt vmcnt(" #n ")" ::: "memory")
; #define PG8_WAIT_L(n) asm volatile("s_waitcnt lgkmcnt(" #n ")" ::: "memory")
; #define PG8_BAR __builtin_amdgcn_s_barrier()
; #define PG8_SCHED __builtin_amdgcn_sched_barrier(0)
; template <class Epi, class Sched, bool HM = false>
; __device__ __forceinline__ void gemm_phase(PG8_LAS unsigned char* lds, const Gemm g, const Sched& S, const Epi& E) {
;     ...
;             PG8_LDB(B0, 0, 0); PG8_LDB(B1, 0, 1); PG8_SCHED; PG8_LDA(At, 0, 0); if (hasx) PG8_LDX(pb, 0); PG8_STAGE(PG8_SA(1, 1), a1 + hstepA, voffA); PG8_STAGEX(pb ^ 1, a2 + xstep);
;             PG8_WAIT_V(9); PG8_WAIT_L(0); PG8_BAR; PG8_MMA(0, 0, At, B0); PG8_MMA(0, 1, At, B1); if (hasx) PG8_MMAX(); PG8_BAR; PG8_SCHED;
.LBB0_536:
	s_add_u32 s34, s34, 0x80000
	s_addc_u32 s35, s35, 0
	s_mov_b32 m0, s83
	s_nop 0
	global_load_lds_dwordx4 v225, s[34:35]
	s_nop 0
	s_mov_b32 m0, s88
	s_nop 0
	global_load_lds_dwordx4 v227, s[34:35]
	s_add_u32 s34, s94, 0x100000
	s_addc_u32 s35, s95, 0
	s_xor_b32 s20, s20, 0x21400
	s_add_i32 s20, s30, s20
	s_mov_b32 m0, s20
	s_nop 0
	global_load_lds_dwordx4 v229, s[34:35]
	s_waitcnt vmcnt(9)
	s_waitcnt lgkmcnt(0)
	s_barrier
	s_setprio 1
	s_waitcnt lgkmcnt(7)
	v_mfma_f32_16x16x32_bf16 v[146:149], v[166:169], v[206:209], v[146:149]
	v_mfma_f32_16x16x32_bf16 v[142:145], v[174:177], v[206:209], v[142:145]
	s_waitcnt lgkmcnt(5)
	v_mfma_f32_16x16x32_bf16 v[138:141], v[166:169], v[198:201], v[138:141]
	v_mfma_f32_16x16x32_bf16 v[130:133], v[174:177], v[198:201], v[130:133]
	s_waitcnt lgkmcnt(3)
	v_mfma_f32_16x16x32_bf16 v[122:125], v[166:169], v[190:193], v[122:125]
	v_mfma_f32_16x16x32_bf16 v[114:117], v[174:177], v[190:193], v[114:117]
	s_waitcnt lgkmcnt(1)
	v_mfma_f32_16x16x32_bf16 v[106:109], v[166:169], v[182:185], v[106:109]
	v_mfma_f32_16x16x32_bf16 v[98:101], v[174:177], v[182:185], v[98:101]
	v_mfma_f32_16x16x32_bf16 v[146:149], v[170:173], v[210:213], v[146:149]
	v_mfma_f32_16x16x32_bf16 v[142:145], v[178:181], v[210:213], v[142:145]
	v_mfma_f32_16x16x32_bf16 v[138:141], v[170:173], v[202:205], v[138:141]
	v_mfma_f32_16x16x32_bf16 v[130:133], v[178:181], v[202:205], v[130:133]
	v_mfma_f32_16x16x32_bf16 v[122:125], v[170:173], v[194:197], v[122:125]
	v_mfma_f32_16x16x32_bf16 v[114:117], v[178:181], v[194:197], v[114:117]
	s_waitcnt lgkmcnt(0)
	v_mfma_f32_16x16x32_bf16 v[106:109], v[170:173], v[186:189], v[106:109]
	v_mfma_f32_16x16x32_bf16 v[98:101], v[178:181], v[186:189], v[98:101]
	s_setprio 0
	s_setprio 1
	v_mfma_f32_16x16x32_bf16 v[134:137], v[150:153], v[206:209], v[134:137]
	v_mfma_f32_16x16x32_bf16 v[126:129], v[158:161], v[206:209], v[126:129]
	v_mfma_f32_16x16x32_bf16 v[118:121], v[150:153], v[198:201], v[118:121]
	v_mfma_f32_16x16x32_bf16 v[110:113], v[158:161], v[198:201], v[110:113]
	v_mfma_f32_16x16x32_bf16 v[102:105], v[150:153], v[190:193], v[102:105]
	v_mfma_f32_16x16x32_bf16 v[94:97], v[158:161], v[190:193], v[94:97]
	v_mfma_f32_16x16x32_bf16 v[90:93], v[150:153], v[182:185], v[90:93]
	v_mfma_f32_16x16x32_bf16 v[86:89], v[158:161], v[182:185], v[86:89]
	v_mfma_f32_16x16x32_bf16 v[134:137], v[154:157], v[210:213], v[134:137]
	v_mfma_f32_16x16x32_bf16 v[126:129], v[162:165], v[210:213], v[126:129]
	v_mfma_f32_16x16x32_bf16 v[118:121], v[154:157], v[202:205], v[118:121]
	v_mfma_f32_16x16x32_bf16 v[110:113], v[162:165], v[202:205], v[110:113]
	v_mfma_f32_16x16x32_bf16 v[102:105], v[154:157], v[194:197], v[102:105]
	v_mfma_f32_16x16x32_bf16 v[94:97], v[162:165], v[194:197], v[94:97]
	v_mfma_f32_16x16x32_bf16 v[90:93], v[154:157], v[186:189], v[90:93]
	v_mfma_f32_16x16x32_bf16 v[86:89], v[162:165], v[186:189], v[86:89]
	s_setprio 0
	v_cndmask_b32_e64 v4, 0, 1, s[78:79]
	s_and_b64 vcc, exec, s[42:43]
	v_cmp_ne_u32_e64 s[44:45], 1, v4
	s_cbranch_vccnz .LBB0_542
	s_and_b64 vcc, exec, s[44:45]
	s_mov_b64 s[20:21], -1
	s_cbranch_vccnz .LBB0_539
	v_mfma_f32_16x16x32_bf16 v[18:21], v[174:177], v[6:9], v[18:21]
	s_mov_b64 s[20:21], 0
	v_mfma_f32_16x16x32_bf16 v[14:17], v[158:161], v[6:9], v[14:17]
	v_mfma_f32_16x16x32_bf16 v[18:21], v[178:181], v[10:13], v[18:21]
	v_mfma_f32_16x16x32_bf16 v[14:17], v[162:165], v[10:13], v[14:17]

; #define PG8_STAGE(bufoff, gbase, voff) do { _Pragma("unroll") for (int _i = 0; _i < 2; ++_i) glds16_s((voff)[_i], (const void*)(gbase), ldsbase + (unsigned)((bufoff) + _i * 8192) + ldsw); } while (0)
; #define PG8_LDA(dst, b, h) do { _Pragma("unroll") for (int m = 0; m < 4; ++m) _Pragma("unroll") for (int k = 0; k < 2; ++k) dst[m][k] = *(const PG8_LAS bf16x8*)(lds + PG8_SA(b, h) + aoff + m * 2048 + k * 1024); } while (0)
; #define PG8_LDB(dst, b, h) do { _Pragma("unroll") for (int n = 0; n < 2; ++n) _Pragma("unroll") for (int k = 0; k < 2; ++k) dst[n][k] = *(const PG8_LAS bf16x8*)(lds + PG8_SB(b, h) + boff + n * 2048 + k * 1024); } while (0)
; #define PG8_LDX(pb, tp) do { _Pragma("unroll") for (int k = 0; k < 2; ++k) Ax[k] = *(const PG8_LAS bf16x8*)(lds + xoff + (pb) * 4096 + (tp) * 128 + k * 64); } while (0)
; #define PG8_MMA(ai, bj, At, Bt) do { __builtin_amdgcn_s_setprio(1); _Pragma("unroll") for (int m = 0; m < 4; ++m) _Pragma("unroll") for (int n = 0; n < 2; ++n) _Pragma("unroll") for (int k = 0; k < 2; ++k) \
;         acc[ai][bj][m][n] = __builtin_amdgcn_mfma_f32_16x16x32_bf16(Bt[n][k], At[m][k], acc[ai][bj][m][n], 0, 0, 0); __builtin_amdgcn_s_setprio(0); } while (0)
; #define PG8_WAIT_V(n) asm volatile("s_waitcnt vmcnt(" #n ")" ::: "memory")
; #define PG8_WAIT_L(n) asm volatile("s_waitcnt lgkmcnt(" #n ")" ::: "memory")
; #define PG8_BAR __builtin_amdgcn_s_barrier()
; #define PG8_SCHED __builtin_amdgcn_sched_barrier(0)
; template <class Epi, class Sched, bool HM = false>
; __device__ __forceinline__ void gemm_phase(PG8_LAS unsigned char* lds, const Gemm g, const Sched& S, const Epi& E) {
;     ...
;             if (!HM) PG8_LDA(At, 0, 1); PG8_STAGE(PG8_SB(0, 0), b2, voffB); PG8_STAGE(PG8_SB(0, 1), b2 + hstepB, voffB); PG8_STAGE(PG8_SA(0, 0), a2, voffA);
;             PG8_WAIT_V(9); PG8_WAIT_L(0); PG8_BAR; if (!HM) { PG8_MMA(1, 0, At, B0); PG8_MMA(1, 1, At, B1); } PG8_BAR; PG8_SCHED;
;             PG8_LDB(B0, 1, 0); PG8_LDB(B1, 1, 1); PG8_SCHED; PG8_LDA(At, 1, 0); if (hasx) PG8_LDX(pb, 1); PG8_STAGE(PG8_SA(0, 1), a2 + hstepA, voffA);
.LBB0_541:
.LBB0_542:
	s_barrier
	ds_read_b128 v[182:185], v235 offset:16384
	ds_read_b128 v[186:189], v235 offset:17408
	ds_read_b128 v[190:193], v235 offset:18432
	ds_read_b128 v[194:197], v235 offset:19456
	ds_read_b128 v[198:201], v235 offset:20480
	ds_read_b128 v[202:205], v235 offset:21504
	ds_read_b128 v[206:209], v235 offset:22528
	ds_read_b128 v[210:213], v235 offset:23552
	s_mov_b32 m0, s19
	s_nop 0
	global_load_lds_dwordx4 v226, s[8:9]
	s_nop 0
	s_mov_b32 m0, s24
	s_nop 0
	global_load_lds_dwordx4 v228, s[8:9]
	s_add_u32 s8, s8, 0x80000
	s_addc_u32 s9, s9, 0
	s_mov_b32 m0, s25
	s_nop 0
	global_load_lds_dwordx4 v226, s[8:9]
	s_nop 0
	s_mov_b32 m0, s28
	s_nop 0
	global_load_lds_dwordx4 v228, s[8:9]
	s_mov_b32 m0, s18
	s_nop 0
	global_load_lds_dwordx4 v225, s[94:95]
	s_nop 0
	s_mov_b32 m0, s29
	s_nop 0
	global_load_lds_dwordx4 v227, s[94:95]
	s_waitcnt vmcnt(9)
	s_waitcnt lgkmcnt(0)
	s_barrier
	s_setprio 1
	s_waitcnt lgkmcnt(7)
	v_mfma_f32_16x16x32_bf16 v[82:85], v[166:169], v[182:185], v[82:85]
	v_mfma_f32_16x16x32_bf16 v[78:81], v[174:177], v[182:185], v[78:81]
	s_waitcnt lgkmcnt(5)
	v_mfma_f32_16x16x32_bf16 v[74:77], v[166:169], v[190:193], v[74:77]
	v_mfma_f32_16x16x32_bf16 v[66:69], v[174:177], v[190:193], v[66:69]
	s_waitcnt lgkmcnt(3)
	v_mfma_f32_16x16x32_bf16 v[58:61], v[166:169], v[198:201], v[58:61]
	v_mfma_f32_16x16x32_bf16 v[50:53], v[174:177], v[198:201], v[50:53]
	s_waitcnt lgkmcnt(1)
	v_mfma_f32_16x16x32_bf16 v[42:45], v[166:169], v[206:209], v[42:45]
	v_mfma_f32_16x16x32_bf16 v[34:37], v[174:177], v[206:209], v[34:37]
	v_mfma_f32_16x16x32_bf16 v[82:85], v[170:173], v[186:189], v[82:85]
	v_mfma_f32_16x16x32_bf16 v[78:81], v[178:181], v[186:189], v[78:81]
	v_mfma_f32_16x16x32_bf16 v[74:77], v[170:173], v[194:197], v[74:77]
	v_mfma_f32_16x16x32_bf16 v[66:69], v[178:181], v[194:197], v[66:69]
	v_mfma_f32_16x16x32_bf16 v[58:61], v[170:173], v[202:205], v[58:61]
	v_mfma_f32_16x16x32_bf16 v[50:53], v[178:181], v[202:205], v[50:53]
	s_waitcnt lgkmcnt(0)
	v_mfma_f32_16x16x32_bf16 v[42:45], v[170:173], v[210:213], v[42:45]
	v_mfma_f32_16x16x32_bf16 v[34:37], v[178:181], v[210:213], v[34:37]
	s_setprio 0
	s_setprio 1
	v_mfma_f32_16x16x32_bf16 v[70:73], v[150:153], v[182:185], v[70:73]
	v_mfma_f32_16x16x32_bf16 v[62:65], v[158:161], v[182:185], v[62:65]
	v_mfma_f32_16x16x32_bf16 v[54:57], v[150:153], v[190:193], v[54:57]
	v_mfma_f32_16x16x32_bf16 v[46:49], v[158:161], v[190:193], v[46:49]
	v_mfma_f32_16x16x32_bf16 v[38:41], v[150:153], v[198:201], v[38:41]
	v_mfma_f32_16x16x32_bf16 v[30:33], v[158:161], v[198:201], v[30:33]
	v_mfma_f32_16x16x32_bf16 v[26:29], v[150:153], v[206:209], v[26:29]
	v_mfma_f32_16x16x32_bf16 v[22:25], v[158:161], v[206:209], v[22:25]
	v_mfma_f32_16x16x32_bf16 v[70:73], v[154:157], v[186:189], v[70:73]
	v_mfma_f32_16x16x32_bf16 v[62:65], v[162:165], v[186:189], v[62:65]
	v_mfma_f32_16x16x32_bf16 v[54:57], v[154:157], v[194:197], v[54:57]
	v_mfma_f32_16x16x32_bf16 v[46:49], v[162:165], v[194:197], v[46:49]
	v_mfma_f32_16x16x32_bf16 v[38:41], v[154:157], v[202:205], v[38:41]
	v_mfma_f32_16x16x32_bf16 v[30:33], v[162:165], v[202:205], v[30:33]
	v_mfma_f32_16x16x32_bf16 v[26:29], v[154:157], v[210:213], v[26:29]
	v_mfma_f32_16x16x32_bf16 v[22:25], v[162:165], v[210:213], v[22:25]
	s_setprio 0
	s_barrier
	v_add_u32_e32 v4, 0x18000, v234
	ds_read_b128 v[166:169], v4
	ds_read_b128 v[170:173], v4 offset:1024
	ds_read_b128 v[174:177], v4 offset:2048
	ds_read_b128 v[178:181], v4 offset:3072
	v_add_u32_e32 v4, 0x1c000, v234
	ds_read_b128 v[150:153], v4
	ds_read_b128 v[154:157], v4 offset:1024
	ds_read_b128 v[158:161], v4 offset:2048
	ds_read_b128 v[162:165], v4 offset:3072
	ds_read_b128 v[206:209], v235 offset:32768
	ds_read_b128 v[210:213], v235 offset:33792
	ds_read_b128 v[198:201], v235 offset:34816
	ds_read_b128 v[202:205], v235 offset:35840
	ds_read_b128 v[190:193], v235 offset:36864
	ds_read_b128 v[194:197], v235 offset:37888
	ds_read_b128 v[182:185], v235 offset:38912
	ds_read_b128 v[186:189], v235 offset:39936
	s_and_b64 vcc, exec, s[42:43]
	s_cbranch_vccnz .LBB0_544
	v_xor_b32_e32 v6, 0x80, v2
	ds_read_b128 v[6:9], v6
	v_xor_b32_e32 v10, 0xc0, v2
	ds_read_b128 v[10:13], v10
; #define PG8_STAGE(bufoff, gbase, voff) do { _Pragma("unroll") for (int _i = 0; _i < 2; ++_i) glds16_s((voff)[_i], (const void*)(gbase), ldsbase + (unsigned)((bufoff) + _i * 8192) + ldsw); } while (0)
; #define PG8_LDA(dst, b, h) do { _Pragma("unroll") for (int m = 0; m < 4; ++m) _Pragma("unroll") for (int k = 0; k < 2; ++k) dst[m][k] = *(const PG8_LAS bf16x8*)(lds + PG8_SA(b, h) + aoff + m * 2048 + k * 1024); } while (0)
; #define PG8_LDB(dst, b, h) do { _Pragma("unroll") for (int n = 0; n < 2; ++n) _Pragma("unroll") for (int k = 0; k < 2; ++k) dst[n][k] = *(const PG8_LAS bf16x8*)(lds + PG8_SB(b, h) + boff + n * 2048 + k * 1024); } while (0)
; #define PG8_LDX(pb, tp) do { _Pragma("unroll") for (int k = 0; k < 2; ++k) Ax[k] = *(const PG8_LAS bf16x8*)(lds + xoff + (pb) * 4096 + (tp) * 128 + k * 64); } while (0)
; #define PG8_MMA(ai, bj, At, Bt) do { __builtin_amdgcn_s_setprio(1); _Pragma("unroll") for (int m = 0; m < 4; ++m) _Pragma("unroll") for (int n = 0; n < 2; ++n) _Pragma("unroll") for (int k = 0; k < 2; ++k) \
;         acc[ai][bj][m][n] = __builtin_amdgcn_mfma_f32_16x16x32_bf16(Bt[n][k], At[m][k], acc[ai][bj][m][n], 0, 0, 0); __builtin_amdgcn_s_setprio(0); } while (0)
; #define PG8_WAIT_V(n) asm volatile("s_waitcnt vmcnt(" #n ")" ::: "memory")
; #define PG8_WAIT_L(n) asm volatile("s_waitcnt lgkmcnt(" #n ")" ::: "memory")
; #define PG8_BAR __builtin_amdgcn_s_barrier()
; #define PG8_SCHED __builtin_amdgcn_sched_barrier(0)
; template <class Epi, class Sched, bool HM = false>
; __device__ __forceinline__ void gemm_phase(PG8_LAS unsigned char* lds, const Gemm g, const Sched& S, const Epi& E) {
;     ...
;             PG8_LDB(B0, 1, 0); PG8_LDB(B1, 1, 1); PG8_SCHED; PG8_LDA(At, 1, 0); if (hasx) PG8_LDX(pb, 1); PG8_STAGE(PG8_SA(0, 1), a2 + hstepA, voffA);
;             PG8_WAIT_V(9); PG8_WAIT_L(0); PG8_BAR; PG8_MMA(0, 0, At, B0); PG8_MMA(0, 1, At, B1); if (hasx) PG8_MMAX(); PG8_BAR; PG8_SCHED;
.LBB0_544:
	s_add_u32 s8, s94, 0x80000
	s_addc_u32 s9, s95, 0
	s_mov_b32 m0, s31
	s_nop 0
	global_load_lds_dwordx4 v225, s[8:9]
	s_nop 0
	s_mov_b32 m0, s36
	s_nop 0
	global_load_lds_dwordx4 v227, s[8:9]
	s_waitcnt vmcnt(9)
	s_waitcnt lgkmcnt(0)
	s_barrier
	s_setprio 1
	s_waitcnt lgkmcnt(7)
	v_mfma_f32_16x16x32_bf16 v[146:149], v[166:169], v[206:209], v[146:149]
	v_mfma_f32_16x16x32_bf16 v[142:145], v[174:177], v[206:209], v[142:145]
	s_waitcnt lgkmcnt(5)
	v_mfma_f32_16x16x32_bf16 v[138:141], v[166:169], v[198:201], v[138:141]
	v_mfma_f32_16x16x32_bf16 v[130:133], v[174:177], v[198:201], v[130:133]
	s_waitcnt lgkmcnt(3)
	v_mfma_f32_16x16x32_bf16 v[122:125], v[166:169], v[190:193], v[122:125]
	v_mfma_f32_16x16x32_bf16 v[114:117], v[174:177], v[190:193], v[114:117]
	s_waitcnt lgkmcnt(1)
	v_mfma_f32_16x16x32_bf16 v[106:109], v[166:169], v[182:185], v[106:109]
	v_mfma_f32_16x16x32_bf16 v[98:101], v[174:177], v[182:185], v[98:101]
	v_mfma_f32_16x16x32_bf16 v[146:149], v[170:173], v[210:213], v[146:149]
	v_mfma_f32_16x16x32_bf16 v[142:145], v[178:181], v[210:213], v[142:145]
	v_mfma_f32_16x16x32_bf16 v[138:141], v[170:173], v[202:205], v[138:141]
	v_mfma_f32_16x16x32_bf16 v[130:133], v[178:181], v[202:205], v[130:133]
	v_mfma_f32_16x16x32_bf16 v[122:125], v[170:173], v[194:197], v[122:125]
	v_mfma_f32_16x16x32_bf16 v[114:117], v[178:181], v[194:197], v[114:117]
	s_waitcnt lgkmcnt(0)
	v_mfma_f32_16x16x32_bf16 v[106:109], v[170:173], v[186:189], v[106:109]
	v_mfma_f32_16x16x32_bf16 v[98:101], v[178:181], v[186:189], v[98:101]
	s_setprio 0
	s_setprio 1
	v_mfma_f32_16x16x32_bf16 v[134:137], v[150:153], v[206:209], v[134:137]
	v_mfma_f32_16x16x32_bf16 v[126:129], v[158:161], v[206:209], v[126:129]
	v_mfma_f32_16x16x32_bf16 v[118:121], v[150:153], v[198:201], v[118:121]
	v_mfma_f32_16x16x32_bf16 v[110:113], v[158:161], v[198:201], v[110:113]
	v_mfma_f32_16x16x32_bf16 v[102:105], v[150:153], v[190:193], v[102:105]
	v_mfma_f32_16x16x32_bf16 v[94:97], v[158:161], v[190:193], v[94:97]
	v_mfma_f32_16x16x32_bf16 v[90:93], v[150:153], v[182:185], v[90:93]
	v_mfma_f32_16x16x32_bf16 v[86:89], v[158:161], v[182:185], v[86:89]
	v_mfma_f32_16x16x32_bf16 v[134:137], v[154:157], v[210:213], v[134:137]
	v_mfma_f32_16x16x32_bf16 v[126:129], v[162:165], v[210:213], v[126:129]
	v_mfma_f32_16x16x32_bf16 v[118:121], v[154:157], v[202:205], v[118:121]
	v_mfma_f32_16x16x32_bf16 v[110:113], v[162:165], v[202:205], v[110:113]
	v_mfma_f32_16x16x32_bf16 v[102:105], v[154:157], v[194:197], v[102:105]
	v_mfma_f32_16x16x32_bf16 v[94:97], v[162:165], v[194:197], v[94:97]
	v_mfma_f32_16x16x32_bf16 v[90:93], v[154:157], v[186:189], v[90:93]
	v_mfma_f32_16x16x32_bf16 v[86:89], v[162:165], v[186:189], v[86:89]
	s_setprio 0
	s_and_b64 vcc, exec, s[42:43]
	s_cbranch_vccnz .LBB0_533
	s_and_b64 vcc, exec, s[44:45]
	s_mov_b64 s[8:9], -1
	s_cbranch_vccnz .LBB0_547
	v_mfma_f32_16x16x32_bf16 v[18:21], v[174:177], v[6:9], v[18:21]
	s_mov_b64 s[8:9], 0
	v_mfma_f32_16x16x32_bf16 v[14:17], v[158:161], v[6:9], v[14:17]
	v_mfma_f32_16x16x32_bf16 v[18:21], v[178:181], v[10:13], v[18:21]
	v_mfma_f32_16x16x32_bf16 v[14:17], v[162:165], v[10:13], v[14:17]

; #define PG8_STAGE(bufoff, gbase, voff) do { _Pragma("unroll") for (int _i = 0; _i < 2; ++_i) glds16_s((voff)[_i], (const void*)(gbase), ldsbase + (unsigned)((bufoff) + _i * 8192) + ldsw); } while (0)
; template <class Epi, class Sched, bool HM = false>
; __device__ __forceinline__ void gemm_phase(PG8_LAS unsigned char* lds, const Gemm g, const Sched& S, const Epi& E) {
;     ...
;     for (int i = 0; i < 2; ++i) { int R, C; stage_rc(tid * 16 + i * 8192, R, C); const int Rb = Epi::PERM ? ((R & ~31) + perm32(R & 31)) : R;
;         voffA[i] = (unsigned)(R * g.lda + C) * 2u; voffB[i] = (unsigned)(Rb * g.ldb + C) * 2u; }
;     const unsigned voffX = (unsigned)((4 * (wid & 3) + (lane >> 4)) * g.lda + 8 * (lane & 15)) * 2u;
;     const size_t kstep = (size_t)(BK * 2);
;     const size_t hstepA = (size_t)HALF * g.lda * 2, hstepB = (size_t)HALF * g.ldb * 2;
;     const size_t tstepA = (size_t)(HM ? HALF : g.pms) * g.lda * 2, tstepB = 2 * hstepB, xstep = 2 * hstepA; const bool hasx = g.pms != BM;
;     const unsigned ldsw = (unsigned)wid * 1024u, ldsx = (unsigned)(wid & 3) * 1024u;
;     const unsigned ldsbase = (unsigned)__builtin_amdgcn_readfirstlane((int)(unsigned)(__UINTPTR_TYPE__)lds);
;     const int aoff = lds_byte(wr * 64 + fr, fq * 8), boff = lds_byte(wc * 32 + fr, fq * 8);
;     const int xoff = XOFF + fr * 256 + fq * 16;
;     ...
;     Unit cur, nxt; int ui = 0;
;     if (!S.next(0, cur)) return;
;     f32x4 acc[2][2][4][2]; f32x4 accx[2];
; #pragma unroll
;     for (int a = 0; a < 2; ++a)
; #pragma unroll
;         for (int b = 0; b < 2; ++b)
; #pragma unroll
;             for (int m = 0; m < 4; ++m)
; #pragma unroll
;                 for (int n = 0; n < 2; ++n) acc[a][b][m][n] = (f32x4){0.f, 0.f, 0.f, 0.f};
;     accx[0] = (f32x4){0.f, 0.f, 0.f, 0.f}; accx[1] = accx[0];
;     bf16x8 At[4][2], B0[2][2], B1[2][2], Ax[2];
;     const char* cA = PG8_APTR(cur); const char* cB = PG8_BPTR(cur);
;     S.a_ready(cur);
;     PG8_STAGE(PG8_SB(0, 0), cB, voffB); PG8_STAGE(PG8_SB(0, 1), cB + hstepB, voffB); PG8_STAGE(PG8_SA(0, 0), cA, voffA); PG8_STAGEX(0, cA + xstep); PG8_STAGE(PG8_SA(0, 1), cA + hstepA, voffA);
;     if (wr == 1) PG8_BAR;
;     PG8_WAIT_V(2); PG8_BAR;
;     PG8_STAGE(PG8_SB(1, 0), cB + kstep, voffB); PG8_STAGE(PG8_SA(1, 0), cA + kstep, voffA); PG8_STAGE(PG8_SB(1, 1), cB + hstepB + kstep, voffB);
;     PG8_WAIT_V(6); PG8_BAR;
.LBB0_566:
	v_readlane_b32 s12, v254, 5
	s_mov_b64 s[4:5], s[30:31]
	s_mov_b64 s[6:7], s[30:31]
	s_mov_b64 s[38:39], s[30:31]
	s_mov_b64 s[34:35], s[30:31]
	s_mov_b64 s[8:9], s[30:31]
	s_mov_b64 s[0:1], s[30:31]
	s_waitcnt vmcnt(0)
	v_mov_b32_e32 v4, v0
	v_readlane_b32 s13, v254, 6
	s_andn2_b64 vcc, exec, s[12:13]
	v_readfirstlane_b32 s20, v4
	s_cbranch_vccnz .LBB0_616
	v_bfe_i32 v6, v4, 27, 1
	v_lshlrev_b32_e32 v2, 4, v4
	v_lshrrev_b32_e32 v6, 22, v6
	v_add_u32_e32 v6, v2, v6
	v_and_b32_e32 v6, 0xfffffc00, v6
	v_sub_u32_e32 v6, v2, v6
	v_ashrrev_i32_e32 v5, 31, v4
	v_lshrrev_b32_e32 v7, 4, v6
	v_lshrrev_b32_e32 v5, 26, v5
	v_bitop3_b32 v6, v7, v6, 32 bitop3:0x6c
	s_add_u32 s10, s4, 0x1a1e4000
	v_add_u32_e32 v5, v4, v5
	v_ashrrev_i32_e32 v8, 31, v6
	s_addc_u32 s14, s5, 0
	v_ashrrev_i32_e32 v5, 6, v5
	v_lshrrev_b32_e32 v8, 26, v8
	s_add_u32 s4, s6, s66
	v_lshlrev_b32_e32 v7, 3, v5
	v_add_u32_e32 v8, v6, v8
	s_addc_u32 s5, s7, s67
	v_and_b32_e32 v7, -16, v7
	v_ashrrev_i32_e32 v9, 6, v8
	v_and_b32_e32 v8, 0xc0, v8
	s_add_u32 s15, s4, 0xa0000
	v_add_u32_e32 v7, v9, v7
	v_sub_u32_e32 v6, v6, v8
	s_addc_u32 s45, s5, 0
	v_lshlrev_b32_e32 v5, 5, v5
	v_ashrrev_i16_sdwa v6, v1, sext(v6) dst_sel:DWORD dst_unused:UNUSED_PAD src0_sel:DWORD src1_sel:BYTE_0
	v_lshlrev_b32_e32 v8, 1, v7
	v_lshrrev_b32_e32 v10, 2, v7
	v_and_b32_e32 v9, 3, v9
	s_mov_b32 s5, 0xfffe0
	v_and_b32_e32 v5, 32, v5
	v_bfe_i32 v6, v6, 0, 16
	v_and_b32_e32 v8, 24, v8
	v_and_b32_e32 v10, 4, v10
	v_and_or_b32 v9, v7, s5, v9
	v_or3_b32 v8, v9, v10, v8
	v_add_lshl_u32 v5, v5, v6, 1
	v_add_u32_e32 v2, 0x2000, v2
	v_lshl_add_u32 v225, v7, 12, v5
	v_lshl_add_u32 v226, v8, 12, v5
	v_ashrrev_i32_e32 v5, 31, v2
	v_lshrrev_b32_e32 v5, 22, v5
	v_add_u32_e32 v5, v2, v5
	v_ashrrev_i32_e32 v5, 10, v5
	v_mul_i32_i24_e32 v6, 0x400, v5
	v_sub_u32_e32 v2, v2, v6
	v_lshrrev_b32_e32 v6, 4, v2
	v_bitop3_b32 v2, v6, v2, 32 bitop3:0x6c
	v_ashrrev_i32_e32 v7, 31, v2
	v_lshrrev_b32_e32 v7, 26, v7
	v_lshlrev_b32_e32 v6, 3, v5
	v_add_u32_e32 v7, v2, v7
	v_and_b32_e32 v6, -16, v6
	v_ashrrev_i32_e32 v8, 6, v7
	v_and_b32_e32 v7, 0xc0, v7
	v_add_u32_e32 v6, v8, v6
	v_sub_u32_e32 v2, v2, v7
	v_lshlrev_b32_e32 v5, 5, v5
	v_ashrrev_i16_sdwa v2, v1, sext(v2) dst_sel:DWORD dst_unused:UNUSED_PAD src0_sel:DWORD src1_sel:BYTE_0
	v_lshlrev_b32_e32 v7, 1, v6
	v_lshrrev_b32_e32 v9, 2, v6
	v_and_b32_e32 v8, 3, v8
	v_and_b32_e32 v5, 32, v5
	v_bfe_i32 v2, v2, 0, 16
	v_and_b32_e32 v7, 24, v7
	v_and_b32_e32 v9, 4, v9
	v_and_or_b32 v8, v6, s5, v8
	s_ashr_i32 s4, s20, 6
	v_or3_b32 v7, v8, v9, v7
	v_add_lshl_u32 v2, v5, v2, 1
	s_and_b32 s21, s4, 3
	v_lshl_add_u32 v227, v6, 12, v2
	v_lshl_add_u32 v228, v7, 12, v2
	v_and_b32_e32 v2, 15, v4
	v_bfe_u32 v4, v4, 4, 2
	s_lshl_b32 s5, s21, 14
	v_lshlrev_b32_e32 v5, 12, v4
	v_lshlrev_b32_e32 v6, 4, v2
	s_ashr_i32 s22, s20, 8
	v_or3_b32 v229, s5, v5, v6
	v_lshrrev_b32_e32 v232, 8, v229
	v_and_b32_e32 v232, 0xf0, v232
	v_xor_b32_e32 v229, v229, v232
	s_lshl_b32 s6, s4, 10
	s_lshl_b32 s18, s21, 10
	v_readlane_b32 s4, v254, 46
	v_readlane_b32 s5, v254, 47
	s_add_u32 s4, s15, s4
	s_addc_u32 s5, s45, s5
	s_add_i32 s51, s6, 0
	s_add_i32 s83, s51, 0x10000
	s_mov_b32 m0, s83
	s_nop 0
	global_load_lds_dwordx4 v226, s[4:5]
	s_add_i32 s36, s51, 0x12000
	s_mov_b32 m0, s36
	s_nop 0
	global_load_lds_dwordx4 v228, s[4:5]
	v_readlane_b32 s7, v254, 26
	s_mul_i32 s6, s7, s57
	s_add_u32 s12, s10, s6
	s_mul_hi_i32 s6, s7, s57
	s_addc_u32 s13, s14, s6
	s_add_u32 s6, s4, 0x80000
	s_addc_u32 s7, s5, 0
	s_add_i32 s37, s51, 0x14000
	s_mov_b32 m0, s37
	s_nop 0
	global_load_lds_dwordx4 v226, s[6:7]
	s_add_i32 s16, s51, 0x16000
	s_mov_b32 m0, s16
	s_nop 0
	global_load_lds_dwordx4 v228, s[6:7]
	v_readlane_b32 s6, v254, 43
	v_readlane_b32 s7, v254, 44
	s_add_u32 s6, s12, s6
	s_addc_u32 s7, s13, s7
	s_mov_b32 m0, s51
	s_nop 0
	global_load_lds_dwordx4 v225, s[6:7]
	s_add_i32 s17, s51, 0x2000
	s_mov_b32 m0, s17
	s_nop 0
	global_load_lds_dwordx4 v227, s[6:7]
	s_add_u32 s12, s6, 0x100000
	s_addc_u32 s13, s7, 0
	s_add_i32 s18, s18, 0
	s_add_i32 s19, s18, 0x20400
	s_mov_b32 m0, s19
	s_nop 0
	global_load_lds_dwordx4 v229, s[12:13]
	s_add_u32 s12, s6, 0x80000
	s_addc_u32 s13, s7, 0
	s_add_i32 s19, s51, 0x4000
	s_mov_b32 m0, s19
	s_nop 0
	global_load_lds_dwordx4 v225, s[12:13]
	s_add_i32 s28, s51, 0x6000
	s_mov_b32 m0, s28
	s_nop 0
	global_load_lds_dwordx4 v227, s[12:13]
	s_cmp_eq_u32 s22, 1
	s_cselect_b64 s[74:75], -1, 0
	s_cmp_lg_u32 s22, 1
	s_cbranch_scc1 .LBB0_569
	s_barrier
.LBB0_569:
	s_add_u32 s76, s38, 0x1c3e4000
	s_addc_u32 s77, s39, 0
	s_add_u32 s78, s34, 0x1d4e4000
	s_addc_u32 s79, s35, 0
	s_add_u32 s84, s8, 0x1e5e4000
	s_addc_u32 s85, s9, 0
	s_add_u32 s92, s0, 0x207e4000
	v_lshlrev_b32_e32 v5, 3, v4
	v_lshlrev_b32_e32 v4, 4, v4
	v_lshlrev_b32_e32 v7, 2, v2
	s_addc_u32 s93, s1, 0
	v_lshl_or_b32 v6, v2, 6, v4
	s_lshl_b32 s0, s22, 13
	v_and_b32_e32 v7, 32, v7
	v_bitop3_b32 v8, v6, s0, v7 bitop3:0xde
	s_lshl_b32 s0, s21, 12
	v_bitop3_b32 v6, v6, s0, v7 bitop3:0xde
	s_add_u32 s0, s4, 0x80
	s_waitcnt vmcnt(2)
	s_barrier
	s_addc_u32 s1, s5, 0
	s_add_i32 s29, s51, 0x18000
	s_mov_b32 m0, s29
	s_nop 0
	global_load_lds_dwordx4 v226, s[0:1]
	s_add_i32 s30, s51, 0x1a000
	s_mov_b32 m0, s30
	s_nop 0
	global_load_lds_dwordx4 v228, s[0:1]
	s_add_u32 s0, s6, 0x80
	s_addc_u32 s1, s7, 0
	s_add_i32 s31, s51, 0x8000
	s_mov_b32 m0, s31
	s_nop 0
	global_load_lds_dwordx4 v225, s[0:1]
	s_add_i32 s24, s51, 0xa000
	s_mov_b32 m0, s24
	s_nop 0
	global_load_lds_dwordx4 v227, s[0:1]
	s_add_u32 s0, s4, 0x80080
	s_addc_u32 s1, s5, 0
	s_add_i32 s25, s51, 0x1c000
	s_mov_b32 m0, s25
	s_nop 0
	global_load_lds_dwordx4 v226, s[0:1]
	s_add_i32 s12, s51, 0x1e000
	s_add_i32 s13, s51, 0xc000
	s_mov_b32 m0, s12
	s_nop 0
	global_load_lds_dwordx4 v228, s[0:1]
	s_cmpk_lt_u32 s20, 0x100
	s_waitcnt vmcnt(6)
	s_cselect_b64 s[94:95], -1, 0
	s_cmpk_gt_u32 s20, 0xff
	v_lshl_add_u32 v7, v2, 8, 0
	s_mov_b32 s0, 0x20400
	s_cselect_b64 s[96:97], -1, 0
	s_lshl_b32 s90, s22, 2
	v_lshl_or_b32 v230, s22, 6, v2
	v_lshlrev_b32_e32 v231, 4, v2
	v_xor_b32_e32 v231, v231, v4
	v_add3_u32 v231, v7, v231, s0
	v_lshl_or_b32 v232, s21, 5, v5
	v_or_b32_e32 v233, 0x100, v2
	s_ashr_i32 s91, s90, 31
	s_add_i32 s52, s51, 0xe000
	s_mov_b32 s88, 0
	v_add_u32_e32 v234, 0, v6
	v_add_u32_e32 v235, 0, v8
	v_readlane_b32 s89, v254, 45
	v_readlane_b32 s59, v254, 26
	s_barrier
	s_branch .LBB0_572

; #define PG8_STAGE(bufoff, gbase, voff) do { _Pragma("unroll") for (int _i = 0; _i < 2; ++_i) glds16_s((voff)[_i], (const void*)(gbase), ldsbase + (unsigned)((bufoff) + _i * 8192) + ldsw); } while (0)
; #define PG8_LDA(dst, b, h) do { _Pragma("unroll") for (int m = 0; m < 4; ++m) _Pragma("unroll") for (int k = 0; k < 2; ++k) dst[m][k] = *(const PG8_LAS bf16x8*)(lds + PG8_SA(b, h) + aoff + m * 2048 + k * 1024); } while (0)
; #define PG8_MMA(ai, bj, At, Bt) do { __builtin_amdgcn_s_setprio(1); _Pragma("unroll") for (int m = 0; m < 4; ++m) _Pragma("unroll") for (int n = 0; n < 2; ++n) _Pragma("unroll") for (int k = 0; k < 2; ++k) \
;         acc[ai][bj][m][n] = __builtin_amdgcn_mfma_f32_16x16x32_bf16(Bt[n][k], At[m][k], acc[ai][bj][m][n], 0, 0, 0); __builtin_amdgcn_s_setprio(0); } while (0)
; #define PG8_WAIT_V(n) asm volatile("s_waitcnt vmcnt(" #n ")" ::: "memory")
; #define PG8_WAIT_L(n) asm volatile("s_waitcnt lgkmcnt(" #n ")" ::: "memory")
; #define PG8_BAR __builtin_amdgcn_s_barrier()
; #define PG8_SCHED __builtin_amdgcn_sched_barrier(0)
; template <class Epi, class Sched, bool HM = false>
; __device__ __forceinline__ void gemm_phase(PG8_LAS unsigned char* lds, const Gemm g, const Sched& S, const Epi& E) {
;     ...
;             if (!HM) PG8_LDA(At, 1, 1); PG8_STAGE(PG8_SB(1, 0), b3, voffB); PG8_STAGE(PG8_SB(1, 1), b3 + hstepB, voffB); PG8_STAGE(PG8_SA(1, 0), a3, voffA);
;             PG8_WAIT_V(8); PG8_WAIT_L(0); PG8_BAR; if (!HM) { PG8_MMA(1, 0, At, B0); PG8_MMA(1, 1, At, B1); } PG8_BAR; PG8_SCHED;
;         }
.LBB0_579:
.LBB0_580:
	s_barrier
	ds_read_b128 v[182:185], v235 offset:49152
	ds_read_b128 v[186:189], v235 offset:50176
	ds_read_b128 v[190:193], v235 offset:51200
	ds_read_b128 v[194:197], v235 offset:52224
	ds_read_b128 v[198:201], v235 offset:53248
	ds_read_b128 v[202:205], v235 offset:54272
	ds_read_b128 v[206:209], v235 offset:55296
	ds_read_b128 v[210:213], v235 offset:56320
	s_mov_b32 m0, s29
	s_nop 0
	global_load_lds_dwordx4 v226, s[6:7]
	s_nop 0
	s_mov_b32 m0, s30
	s_nop 0
	global_load_lds_dwordx4 v228, s[6:7]
	s_add_u32 s6, s6, 0x80000
	s_addc_u32 s7, s7, 0
	s_mov_b32 m0, s25
	s_nop 0
	global_load_lds_dwordx4 v226, s[6:7]
	s_nop 0
	s_mov_b32 m0, s12
	s_nop 0
	global_load_lds_dwordx4 v228, s[6:7]
	s_mov_b32 m0, s31
	s_nop 0
	global_load_lds_dwordx4 v225, s[4:5]
	s_nop 0
	s_mov_b32 m0, s24
	s_nop 0
	global_load_lds_dwordx4 v227, s[4:5]
	s_waitcnt vmcnt(8)
	s_waitcnt lgkmcnt(0)
	s_barrier
	s_setprio 1
	s_waitcnt lgkmcnt(7)
	v_mfma_f32_16x16x32_bf16 v[82:85], v[166:169], v[182:185], v[82:85]
	v_mfma_f32_16x16x32_bf16 v[78:81], v[174:177], v[182:185], v[78:81]
	s_waitcnt lgkmcnt(5)
	v_mfma_f32_16x16x32_bf16 v[66:69], v[166:169], v[190:193], v[66:69]
	v_mfma_f32_16x16x32_bf16 v[62:65], v[174:177], v[190:193], v[62:65]
	s_waitcnt lgkmcnt(3)
	v_mfma_f32_16x16x32_bf16 v[50:53], v[166:169], v[198:201], v[50:53]
	v_mfma_f32_16x16x32_bf16 v[46:49], v[174:177], v[198:201], v[46:49]
	s_waitcnt lgkmcnt(1)
	v_mfma_f32_16x16x32_bf16 v[34:37], v[166:169], v[206:209], v[34:37]
	v_mfma_f32_16x16x32_bf16 v[30:33], v[174:177], v[206:209], v[30:33]
	v_mfma_f32_16x16x32_bf16 v[82:85], v[170:173], v[186:189], v[82:85]
	v_mfma_f32_16x16x32_bf16 v[78:81], v[178:181], v[186:189], v[78:81]
	v_mfma_f32_16x16x32_bf16 v[66:69], v[170:173], v[194:197], v[66:69]
	v_mfma_f32_16x16x32_bf16 v[62:65], v[178:181], v[194:197], v[62:65]
	v_mfma_f32_16x16x32_bf16 v[50:53], v[170:173], v[202:205], v[50:53]
	v_mfma_f32_16x16x32_bf16 v[46:49], v[178:181], v[202:205], v[46:49]
	s_waitcnt lgkmcnt(0)
	v_mfma_f32_16x16x32_bf16 v[34:37], v[170:173], v[210:213], v[34:37]
	v_mfma_f32_16x16x32_bf16 v[30:33], v[178:181], v[210:213], v[30:33]
	s_setprio 0
	s_setprio 1
	v_mfma_f32_16x16x32_bf16 v[74:77], v[150:153], v[182:185], v[74:77]
	v_mfma_f32_16x16x32_bf16 v[70:73], v[158:161], v[182:185], v[70:73]
	v_mfma_f32_16x16x32_bf16 v[58:61], v[150:153], v[190:193], v[58:61]
	v_mfma_f32_16x16x32_bf16 v[54:57], v[158:161], v[190:193], v[54:57]
	v_mfma_f32_16x16x32_bf16 v[42:45], v[150:153], v[198:201], v[42:45]
	v_mfma_f32_16x16x32_bf16 v[38:41], v[158:161], v[198:201], v[38:41]
	v_mfma_f32_16x16x32_bf16 v[26:29], v[150:153], v[206:209], v[26:29]
	v_mfma_f32_16x16x32_bf16 v[22:25], v[158:161], v[206:209], v[22:25]
	v_mfma_f32_16x16x32_bf16 v[74:77], v[154:157], v[186:189], v[74:77]
	v_mfma_f32_16x16x32_bf16 v[70:73], v[162:165], v[186:189], v[70:73]
	v_mfma_f32_16x16x32_bf16 v[58:61], v[154:157], v[194:197], v[58:61]
	v_mfma_f32_16x16x32_bf16 v[54:57], v[162:165], v[194:197], v[54:57]
	v_mfma_f32_16x16x32_bf16 v[42:45], v[154:157], v[202:205], v[42:45]
	v_mfma_f32_16x16x32_bf16 v[38:41], v[162:165], v[202:205], v[38:41]
	v_mfma_f32_16x16x32_bf16 v[26:29], v[154:157], v[210:213], v[26:29]
	v_mfma_f32_16x16x32_bf16 v[22:25], v[162:165], v[210:213], v[22:25]
	s_setprio 0
	s_barrier
	s_add_i32 s23, s23, 2
	s_addk_i32 s22, 0x1000
	s_add_u32 s61, s61, 0x100
	s_addc_u32 s44, s44, 0
	s_add_u32 s82, s82, 0x100
	s_addc_u32 s27, s27, 0
	s_cmp_gt_u32 s23, 29
	s_cbranch_scc1 .LBB0_596

; #define PG8_STAGE(bufoff, gbase, voff) do { _Pragma("unroll") for (int _i = 0; _i < 2; ++_i) glds16_s((voff)[_i], (const void*)(gbase), ldsbase + (unsigned)((bufoff) + _i * 8192) + ldsw); } while (0)
; #define PG8_STAGEX(pb, gbase) glds16_s(voffX, (const void*)(gbase), ldsbase + (unsigned)(XOFF + (pb) * 4096) + ldsx)
; #define PG8_LDA(dst, b, h) do { _Pragma("unroll") for (int m = 0; m < 4; ++m) _Pragma("unroll") for (int k = 0; k < 2; ++k) dst[m][k] = *(const PG8_LAS bf16x8*)(lds + PG8_SA(b, h) + aoff + m * 2048 + k * 1024); } while (0)
; #define PG8_LDB(dst, b, h) do { _Pragma("unroll") for (int n = 0; n < 2; ++n) _Pragma("unroll") for (int k = 0; k < 2; ++k) dst[n][k] = *(const PG8_LAS bf16x8*)(lds + PG8_SB(b, h) + boff + n * 2048 + k * 1024); } while (0)
; #define PG8_LDX(pb, tp) do { _Pragma("unroll") for (int k = 0; k < 2; ++k) Ax[k] = *(const PG8_LAS bf16x8*)(lds + xoff + (pb) * 4096 + (tp) * 128 + k * 64); } while (0)
; #define PG8_MMA(ai, bj, At, Bt) do { __builtin_amdgcn_s_setprio(1); _Pragma("unroll") for (int m = 0; m < 4; ++m) _Pragma("unroll") for (int n = 0; n < 2; ++n) _Pragma("unroll") for (int k = 0; k < 2; ++k) \
;         acc[ai][bj][m][n] = __builtin_amdgcn_mfma_f32_16x16x32_bf16(Bt[n][k], At[m][k], acc[ai][bj][m][n], 0, 0, 0); __builtin_amdgcn_s_setprio(0); } while (0)
; #define PG8_WAIT_V(n) asm volatile("s_waitcnt vmcnt(" #n ")" ::: "memory")
; #define PG8_WAIT_L(n) asm volatile("s_waitcnt lgkmcnt(" #n ")" ::: "memory")
; #define PG8_BAR __builtin_amdgcn_s_barrier()
; #define PG8_SCHED __builtin_amdgcn_sched_barrier(0)
; template <class Epi, class Sched, bool HM = false>
; __device__ __forceinline__ void gemm_phase(PG8_LAS unsigned char* lds, const Gemm g, const Sched& S, const Epi& E) {
;     ...
;             PG8_LDB(B0, 0, 0); PG8_LDB(B1, 0, 1); PG8_SCHED; PG8_LDA(At, 0, 0); if (hasx) PG8_LDX(pb, 0); PG8_STAGE(PG8_SA(1, 1), a1 + hstepA, voffA); PG8_STAGEX(pb ^ 1, a2 + xstep);
;             PG8_WAIT_V(9); PG8_WAIT_L(0); PG8_BAR; PG8_MMA(0, 0, At, B0); PG8_MMA(0, 1, At, B1); if (hasx) PG8_MMAX(); PG8_BAR; PG8_SCHED;
.LBB0_583:
	s_add_u32 s42, s42, 0x80000
	s_addc_u32 s43, s43, 0
	s_mov_b32 m0, s13
	s_nop 0
	global_load_lds_dwordx4 v225, s[42:43]
	s_nop 0
	s_mov_b32 m0, s52
	s_nop 0
	global_load_lds_dwordx4 v227, s[42:43]
	s_add_u32 s42, s8, 0x100000
	s_addc_u32 s43, s9, 0
	s_xor_b32 s20, s20, 0x21400
	s_add_i32 s20, s18, s20
	s_mov_b32 m0, s20
	s_nop 0
	global_load_lds_dwordx4 v229, s[42:43]
	s_waitcnt vmcnt(9)
	s_waitcnt lgkmcnt(0)
	s_barrier
	s_setprio 1
	s_waitcnt lgkmcnt(7)
	v_mfma_f32_16x16x32_bf16 v[146:149], v[166:169], v[206:209], v[146:149]
	v_mfma_f32_16x16x32_bf16 v[142:145], v[174:177], v[206:209], v[142:145]
	s_waitcnt lgkmcnt(5)
	v_mfma_f32_16x16x32_bf16 v[130:133], v[166:169], v[198:201], v[130:133]
	v_mfma_f32_16x16x32_bf16 v[126:129], v[174:177], v[198:201], v[126:129]
	s_waitcnt lgkmcnt(3)
	v_mfma_f32_16x16x32_bf16 v[114:117], v[166:169], v[190:193], v[114:117]
	v_mfma_f32_16x16x32_bf16 v[110:113], v[174:177], v[190:193], v[110:113]
	s_waitcnt lgkmcnt(1)
	v_mfma_f32_16x16x32_bf16 v[98:101], v[166:169], v[182:185], v[98:101]
	v_mfma_f32_16x16x32_bf16 v[94:97], v[174:177], v[182:185], v[94:97]
	v_mfma_f32_16x16x32_bf16 v[146:149], v[170:173], v[210:213], v[146:149]
	v_mfma_f32_16x16x32_bf16 v[142:145], v[178:181], v[210:213], v[142:145]
	v_mfma_f32_16x16x32_bf16 v[130:133], v[170:173], v[202:205], v[130:133]
	v_mfma_f32_16x16x32_bf16 v[126:129], v[178:181], v[202:205], v[126:129]
	v_mfma_f32_16x16x32_bf16 v[114:117], v[170:173], v[194:197], v[114:117]
	v_mfma_f32_16x16x32_bf16 v[110:113], v[178:181], v[194:197], v[110:113]
	s_waitcnt lgkmcnt(0)
	v_mfma_f32_16x16x32_bf16 v[98:101], v[170:173], v[186:189], v[98:101]
	v_mfma_f32_16x16x32_bf16 v[94:97], v[178:181], v[186:189], v[94:97]
	s_setprio 0
	s_setprio 1
	v_mfma_f32_16x16x32_bf16 v[138:141], v[150:153], v[206:209], v[138:141]
	v_mfma_f32_16x16x32_bf16 v[134:137], v[158:161], v[206:209], v[134:137]
	v_mfma_f32_16x16x32_bf16 v[122:125], v[150:153], v[198:201], v[122:125]
	v_mfma_f32_16x16x32_bf16 v[118:121], v[158:161], v[198:201], v[118:121]
	v_mfma_f32_16x16x32_bf16 v[106:109], v[150:153], v[190:193], v[106:109]
	v_mfma_f32_16x16x32_bf16 v[102:105], v[158:161], v[190:193], v[102:105]
	v_mfma_f32_16x16x32_bf16 v[90:93], v[150:153], v[182:185], v[90:93]
	v_mfma_f32_16x16x32_bf16 v[86:89], v[158:161], v[182:185], v[86:89]
	v_mfma_f32_16x16x32_bf16 v[138:141], v[154:157], v[210:213], v[138:141]
	v_mfma_f32_16x16x32_bf16 v[134:137], v[162:165], v[210:213], v[134:137]
	v_mfma_f32_16x16x32_bf16 v[122:125], v[154:157], v[202:205], v[122:125]
	v_mfma_f32_16x16x32_bf16 v[118:121], v[162:165], v[202:205], v[118:121]
	v_mfma_f32_16x16x32_bf16 v[106:109], v[154:157], v[194:197], v[106:109]
	v_mfma_f32_16x16x32_bf16 v[102:105], v[162:165], v[194:197], v[102:105]
	v_mfma_f32_16x16x32_bf16 v[90:93], v[154:157], v[186:189], v[90:93]
	v_mfma_f32_16x16x32_bf16 v[86:89], v[162:165], v[186:189], v[86:89]
	s_setprio 0
	v_cndmask_b32_e64 v4, 0, 1, s[96:97]
	s_and_b64 vcc, exec, s[40:41]
	v_cmp_ne_u32_e64 s[42:43], 1, v4
	s_cbranch_vccnz .LBB0_589
	s_and_b64 vcc, exec, s[42:43]
	s_mov_b64 s[20:21], -1
	s_cbranch_vccnz .LBB0_586
	v_mfma_f32_16x16x32_bf16 v[18:21], v[174:177], v[6:9], v[18:21]
	s_mov_b64 s[20:21], 0
	v_mfma_f32_16x16x32_bf16 v[14:17], v[158:161], v[6:9], v[14:17]
	v_mfma_f32_16x16x32_bf16 v[18:21], v[178:181], v[10:13], v[18:21]
	v_mfma_f32_16x16x32_bf16 v[14:17], v[162:165], v[10:13], v[14:17]

; #define PG8_STAGE(bufoff, gbase, voff) do { _Pragma("unroll") for (int _i = 0; _i < 2; ++_i) glds16_s((voff)[_i], (const void*)(gbase), ldsbase + (unsigned)((bufoff) + _i * 8192) + ldsw); } while (0)
; #define PG8_LDA(dst, b, h) do { _Pragma("unroll") for (int m = 0; m < 4; ++m) _Pragma("unroll") for (int k = 0; k < 2; ++k) dst[m][k] = *(const PG8_LAS bf16x8*)(lds + PG8_SA(b, h) + aoff + m * 2048 + k * 1024); } while (0)
; #define PG8_LDB(dst, b, h) do { _Pragma("unroll") for (int n = 0; n < 2; ++n) _Pragma("unroll") for (int k = 0; k < 2; ++k) dst[n][k] = *(const PG8_LAS bf16x8*)(lds + PG8_SB(b, h) + boff + n * 2048 + k * 1024); } while (0)
; #define PG8_LDX(pb, tp) do { _Pragma("unroll") for (int k = 0; k < 2; ++k) Ax[k] = *(const PG8_LAS bf16x8*)(lds + xoff + (pb) * 4096 + (tp) * 128 + k * 64); } while (0)
; #define PG8_MMA(ai, bj, At, Bt) do { __builtin_amdgcn_s_setprio(1); _Pragma("unroll") for (int m = 0; m < 4; ++m) _Pragma("unroll") for (int n = 0; n < 2; ++n) _Pragma("unroll") for (int k = 0; k < 2; ++k) \
;         acc[ai][bj][m][n] = __builtin_amdgcn_mfma_f32_16x16x32_bf16(Bt[n][k], At[m][k], acc[ai][bj][m][n], 0, 0, 0); __builtin_amdgcn_s_setprio(0); } while (0)
; #define PG8_WAIT_V(n) asm volatile("s_waitcnt vmcnt(" #n ")" ::: "memory")
; #define PG8_WAIT_L(n) asm volatile("s_waitcnt lgkmcnt(" #n ")" ::: "memory")
; #define PG8_BAR __builtin_amdgcn_s_barrier()
; #define PG8_SCHED __builtin_amdgcn_sched_barrier(0)
; template <class Epi, class Sched, bool HM = false>
; __device__ __forceinline__ void gemm_phase(PG8_LAS unsigned char* lds, const Gemm g, const Sched& S, const Epi& E) {
;     ...
;             if (!HM) PG8_LDA(At, 0, 1); PG8_STAGE(PG8_SB(0, 0), b2, voffB); PG8_STAGE(PG8_SB(0, 1), b2 + hstepB, voffB); PG8_STAGE(PG8_SA(0, 0), a2, voffA);
;             PG8_WAIT_V(9); PG8_WAIT_L(0); PG8_BAR; if (!HM) { PG8_MMA(1, 0, At, B0); PG8_MMA(1, 1, At, B1); } PG8_BAR; PG8_SCHED;
;             PG8_LDB(B0, 1, 0); PG8_LDB(B1, 1, 1); PG8_SCHED; PG8_LDA(At, 1, 0); if (hasx) PG8_LDX(pb, 1); PG8_STAGE(PG8_SA(0, 1), a2 + hstepA, voffA);
.LBB0_588:
.LBB0_589:
	s_barrier
	ds_read_b128 v[182:185], v235 offset:16384
	ds_read_b128 v[186:189], v235 offset:17408
	ds_read_b128 v[190:193], v235 offset:18432
	ds_read_b128 v[194:197], v235 offset:19456
	ds_read_b128 v[198:201], v235 offset:20480
	ds_read_b128 v[202:205], v235 offset:21504
	ds_read_b128 v[206:209], v235 offset:22528
	ds_read_b128 v[210:213], v235 offset:23552
	s_mov_b32 m0, s83
	s_nop 0
	global_load_lds_dwordx4 v226, s[34:35]
	s_nop 0
	s_mov_b32 m0, s36
	s_nop 0
	global_load_lds_dwordx4 v228, s[34:35]
	s_add_u32 s20, s34, 0x80000
	s_addc_u32 s21, s35, 0
	s_mov_b32 m0, s37
	s_nop 0
	global_load_lds_dwordx4 v226, s[20:21]
	s_nop 0
	s_mov_b32 m0, s16
	s_nop 0
	global_load_lds_dwordx4 v228, s[20:21]
	s_mov_b32 m0, s51
	s_nop 0
	global_load_lds_dwordx4 v225, s[8:9]
	s_nop 0
	s_mov_b32 m0, s17
	s_nop 0
	global_load_lds_dwordx4 v227, s[8:9]
	s_waitcnt vmcnt(9)
	s_waitcnt lgkmcnt(0)
	s_barrier
	s_setprio 1
	s_waitcnt lgkmcnt(7)
	v_mfma_f32_16x16x32_bf16 v[82:85], v[166:169], v[182:185], v[82:85]
	v_mfma_f32_16x16x32_bf16 v[78:81], v[174:177], v[182:185], v[78:81]
	s_waitcnt lgkmcnt(5)
	v_mfma_f32_16x16x32_bf16 v[66:69], v[166:169], v[190:193], v[66:69]
	v_mfma_f32_16x16x32_bf16 v[62:65], v[174:177], v[190:193], v[62:65]
	s_waitcnt lgkmcnt(3)
	v_mfma_f32_16x16x32_bf16 v[50:53], v[166:169], v[198:201], v[50:53]
	v_mfma_f32_16x16x32_bf16 v[46:49], v[174:177], v[198:201], v[46:49]
	s_waitcnt lgkmcnt(1)
	v_mfma_f32_16x16x32_bf16 v[34:37], v[166:169], v[206:209], v[34:37]
	v_mfma_f32_16x16x32_bf16 v[30:33], v[174:177], v[206:209], v[30:33]
	v_mfma_f32_16x16x32_bf16 v[82:85], v[170:173], v[186:189], v[82:85]
	v_mfma_f32_16x16x32_bf16 v[78:81], v[178:181], v[186:189], v[78:81]
	v_mfma_f32_16x16x32_bf16 v[66:69], v[170:173], v[194:197], v[66:69]
	v_mfma_f32_16x16x32_bf16 v[62:65], v[178:181], v[194:197], v[62:65]
	v_mfma_f32_16x16x32_bf16 v[50:53], v[170:173], v[202:205], v[50:53]
	v_mfma_f32_16x16x32_bf16 v[46:49], v[178:181], v[202:205], v[46:49]
	s_waitcnt lgkmcnt(0)
	v_mfma_f32_16x16x32_bf16 v[34:37], v[170:173], v[210:213], v[34:37]
	v_mfma_f32_16x16x32_bf16 v[30:33], v[178:181], v[210:213], v[30:33]
	s_setprio 0
	s_setprio 1
	v_mfma_f32_16x16x32_bf16 v[74:77], v[150:153], v[182:185], v[74:77]
	v_mfma_f32_16x16x32_bf16 v[70:73], v[158:161], v[182:185], v[70:73]
	v_mfma_f32_16x16x32_bf16 v[58:61], v[150:153], v[190:193], v[58:61]
	v_mfma_f32_16x16x32_bf16 v[54:57], v[158:161], v[190:193], v[54:57]
	v_mfma_f32_16x16x32_bf16 v[42:45], v[150:153], v[198:201], v[42:45]
	v_mfma_f32_16x16x32_bf16 v[38:41], v[158:161], v[198:201], v[38:41]
	v_mfma_f32_16x16x32_bf16 v[26:29], v[150:153], v[206:209], v[26:29]
	v_mfma_f32_16x16x32_bf16 v[22:25], v[158:161], v[206:209], v[22:25]
	v_mfma_f32_16x16x32_bf16 v[74:77], v[154:157], v[186:189], v[74:77]
	v_mfma_f32_16x16x32_bf16 v[70:73], v[162:165], v[186:189], v[70:73]
	v_mfma_f32_16x16x32_bf16 v[58:61], v[154:157], v[194:197], v[58:61]
	v_mfma_f32_16x16x32_bf16 v[54:57], v[162:165], v[194:197], v[54:57]
	v_mfma_f32_16x16x32_bf16 v[42:45], v[154:157], v[202:205], v[42:45]
	v_mfma_f32_16x16x32_bf16 v[38:41], v[162:165], v[202:205], v[38:41]
	v_mfma_f32_16x16x32_bf16 v[26:29], v[154:157], v[210:213], v[26:29]
	v_mfma_f32_16x16x32_bf16 v[22:25], v[162:165], v[210:213], v[22:25]
	s_setprio 0
	s_barrier
	v_add_u32_e32 v4, 0x18000, v234
	ds_read_b128 v[166:169], v4
	ds_read_b128 v[170:173], v4 offset:1024
	ds_read_b128 v[174:177], v4 offset:2048
	ds_read_b128 v[178:181], v4 offset:3072
	v_add_u32_e32 v4, 0x1c000, v234
	ds_read_b128 v[150:153], v4
	ds_read_b128 v[154:157], v4 offset:1024
	ds_read_b128 v[158:161], v4 offset:2048
	ds_read_b128 v[162:165], v4 offset:3072
	ds_read_b128 v[206:209], v235 offset:32768
	ds_read_b128 v[210:213], v235 offset:33792
	ds_read_b128 v[198:201], v235 offset:34816
	ds_read_b128 v[202:205], v235 offset:35840
	ds_read_b128 v[190:193], v235 offset:36864
	ds_read_b128 v[194:197], v235 offset:37888
	ds_read_b128 v[182:185], v235 offset:38912
	ds_read_b128 v[186:189], v235 offset:39936
	s_and_b64 vcc, exec, s[40:41]
	s_cbranch_vccnz .LBB0_591
	v_xor_b32_e32 v6, 0x80, v2
	ds_read_b128 v[6:9], v6
	v_xor_b32_e32 v10, 0xc0, v2
	ds_read_b128 v[10:13], v10
; #define PG8_STAGE(bufoff, gbase, voff) do { _Pragma("unroll") for (int _i = 0; _i < 2; ++_i) glds16_s((voff)[_i], (const void*)(gbase), ldsbase + (unsigned)((bufoff) + _i * 8192) + ldsw); } while (0)
; #define PG8_LDA(dst, b, h) do { _Pragma("unroll") for (int m = 0; m < 4; ++m) _Pragma("unroll") for (int k = 0; k < 2; ++k) dst[m][k] = *(const PG8_LAS bf16x8*)(lds + PG8_SA(b, h) + aoff + m * 2048 + k * 1024); } while (0)
; #define PG8_LDB(dst, b, h) do { _Pragma("unroll") for (int n = 0; n < 2; ++n) _Pragma("unroll") for (int k = 0; k < 2; ++k) dst[n][k] = *(const PG8_LAS bf16x8*)(lds + PG8_SB(b, h) + boff + n * 2048 + k * 1024); } while (0)
; #define PG8_LDX(pb, tp) do { _Pragma("unroll") for (int k = 0; k < 2; ++k) Ax[k] = *(const PG8_LAS bf16x8*)(lds + xoff + (pb) * 4096 + (tp) * 128 + k * 64); } while (0)
; #define PG8_MMA(ai, bj, At, Bt) do { __builtin_amdgcn_s_setprio(1); _Pragma("unroll") for (int m = 0; m < 4; ++m) _Pragma("unroll") for (int n = 0; n < 2; ++n) _Pragma("unroll") for (int k = 0; k < 2; ++k) \
;         acc[ai][bj][m][n] = __builtin_amdgcn_mfma_f32_16x16x32_bf16(Bt[n][k], At[m][k], acc[ai][bj][m][n], 0, 0, 0); __builtin_amdgcn_s_setprio(0); } while (0)
; #define PG8_WAIT_V(n) asm volatile("s_waitcnt vmcnt(" #n ")" ::: "memory")
; #define PG8_WAIT_L(n) asm volatile("s_waitcnt lgkmcnt(" #n ")" ::: "memory")
; #define PG8_BAR __builtin_amdgcn_s_barrier()
; #define PG8_SCHED __builtin_amdgcn_sched_barrier(0)
; template <class Epi, class Sched, bool HM = false>
; __device__ __forceinline__ void gemm_phase(PG8_LAS unsigned char* lds, const Gemm g, const Sched& S, const Epi& E) {
;     ...
;             PG8_LDB(B0, 1, 0); PG8_LDB(B1, 1, 1); PG8_SCHED; PG8_LDA(At, 1, 0); if (hasx) PG8_LDX(pb, 1); PG8_STAGE(PG8_SA(0, 1), a2 + hstepA, voffA);
;             PG8_WAIT_V(9); PG8_WAIT_L(0); PG8_BAR; PG8_MMA(0, 0, At, B0); PG8_MMA(0, 1, At, B1); if (hasx) PG8_MMAX(); PG8_BAR; PG8_SCHED;
.LBB0_591:
	s_add_u32 s8, s8, 0x80000
	s_addc_u32 s9, s9, 0
	s_mov_b32 m0, s19
	s_nop 0
	global_load_lds_dwordx4 v225, s[8:9]
	s_nop 0
	s_mov_b32 m0, s28
	s_nop 0
	global_load_lds_dwordx4 v227, s[8:9]
	s_waitcnt vmcnt(9)
	s_waitcnt lgkmcnt(0)
	s_barrier
	s_setprio 1
	s_waitcnt lgkmcnt(7)
	v_mfma_f32_16x16x32_bf16 v[146:149], v[166:169], v[206:209], v[146:149]
	v_mfma_f32_16x16x32_bf16 v[142:145], v[174:177], v[206:209], v[142:145]
	s_waitcnt lgkmcnt(5)
	v_mfma_f32_16x16x32_bf16 v[130:133], v[166:169], v[198:201], v[130:133]
	v_mfma_f32_16x16x32_bf16 v[126:129], v[174:177], v[198:201], v[126:129]
	s_waitcnt lgkmcnt(3)
	v_mfma_f32_16x16x32_bf16 v[114:117], v[166:169], v[190:193], v[114:117]
	v_mfma_f32_16x16x32_bf16 v[110:113], v[174:177], v[190:193], v[110:113]
	s_waitcnt lgkmcnt(1)
	v_mfma_f32_16x16x32_bf16 v[98:101], v[166:169], v[182:185], v[98:101]
	v_mfma_f32_16x16x32_bf16 v[94:97], v[174:177], v[182:185], v[94:97]
	v_mfma_f32_16x16x32_bf16 v[146:149], v[170:173], v[210:213], v[146:149]
	v_mfma_f32_16x16x32_bf16 v[142:145], v[178:181], v[210:213], v[142:145]
	v_mfma_f32_16x16x32_bf16 v[130:133], v[170:173], v[202:205], v[130:133]
	v_mfma_f32_16x16x32_bf16 v[126:129], v[178:181], v[202:205], v[126:129]
	v_mfma_f32_16x16x32_bf16 v[114:117], v[170:173], v[194:197], v[114:117]
	v_mfma_f32_16x16x32_bf16 v[110:113], v[178:181], v[194:197], v[110:113]
	s_waitcnt lgkmcnt(0)
	v_mfma_f32_16x16x32_bf16 v[98:101], v[170:173], v[186:189], v[98:101]
	v_mfma_f32_16x16x32_bf16 v[94:97], v[178:181], v[186:189], v[94:97]
	s_setprio 0
	s_setprio 1
	v_mfma_f32_16x16x32_bf16 v[138:141], v[150:153], v[206:209], v[138:141]
	v_mfma_f32_16x16x32_bf16 v[134:137], v[158:161], v[206:209], v[134:137]
	v_mfma_f32_16x16x32_bf16 v[122:125], v[150:153], v[198:201], v[122:125]
	v_mfma_f32_16x16x32_bf16 v[118:121], v[158:161], v[198:201], v[118:121]
	v_mfma_f32_16x16x32_bf16 v[106:109], v[150:153], v[190:193], v[106:109]
	v_mfma_f32_16x16x32_bf16 v[102:105], v[158:161], v[190:193], v[102:105]
	v_mfma_f32_16x16x32_bf16 v[90:93], v[150:153], v[182:185], v[90:93]
	v_mfma_f32_16x16x32_bf16 v[86:89], v[158:161], v[182:185], v[86:89]
	v_mfma_f32_16x16x32_bf16 v[138:141], v[154:157], v[210:213], v[138:141]
	v_mfma_f32_16x16x32_bf16 v[134:137], v[162:165], v[210:213], v[134:137]
	v_mfma_f32_16x16x32_bf16 v[122:125], v[154:157], v[202:205], v[122:125]
	v_mfma_f32_16x16x32_bf16 v[118:121], v[162:165], v[202:205], v[118:121]
	v_mfma_f32_16x16x32_bf16 v[106:109], v[154:157], v[194:197], v[106:109]
	v_mfma_f32_16x16x32_bf16 v[102:105], v[162:165], v[194:197], v[102:105]
	v_mfma_f32_16x16x32_bf16 v[90:93], v[154:157], v[186:189], v[90:93]
	v_mfma_f32_16x16x32_bf16 v[86:89], v[162:165], v[186:189], v[86:89]
	s_setprio 0
	s_and_b64 vcc, exec, s[40:41]
	s_cbranch_vccnz .LBB0_580
	s_and_b64 vcc, exec, s[42:43]
	s_mov_b64 s[8:9], -1
	s_cbranch_vccnz .LBB0_594
	v_mfma_f32_16x16x32_bf16 v[18:21], v[174:177], v[6:9], v[18:21]
	s_mov_b64 s[8:9], 0
	v_mfma_f32_16x16x32_bf16 v[14:17], v[158:161], v[6:9], v[14:17]
	v_mfma_f32_16x16x32_bf16 v[18:21], v[178:181], v[10:13], v[18:21]
	v_mfma_f32_16x16x32_bf16 v[14:17], v[162:165], v[10:13], v[14:17]

; #define PG8_STAGE(bufoff, gbase, voff) do { _Pragma("unroll") for (int _i = 0; _i < 2; ++_i) glds16_s((voff)[_i], (const void*)(gbase), ldsbase + (unsigned)((bufoff) + _i * 8192) + ldsw); } while (0)
; template <class Epi, class Sched, bool HM = false>
; __device__ __forceinline__ void gemm_phase(PG8_LAS unsigned char* lds, const Gemm g, const Sched& S, const Epi& E) {
;     ...
;     for (int i = 0; i < 2; ++i) { int R, C; stage_rc(tid * 16 + i * 8192, R, C); const int Rb = Epi::PERM ? ((R & ~31) + perm32(R & 31)) : R;
;         voffA[i] = (unsigned)(R * g.lda + C) * 2u; voffB[i] = (unsigned)(Rb * g.ldb + C) * 2u; }
;     const unsigned voffX = (unsigned)((4 * (wid & 3) + (lane >> 4)) * g.lda + 8 * (lane & 15)) * 2u;
;     const size_t kstep = (size_t)(BK * 2);
;     const size_t hstepA = (size_t)HALF * g.lda * 2, hstepB = (size_t)HALF * g.ldb * 2;
;     const size_t tstepA = (size_t)(HM ? HALF : g.pms) * g.lda * 2, tstepB = 2 * hstepB, xstep = 2 * hstepA; const bool hasx = g.pms != BM;
;     const unsigned ldsw = (unsigned)wid * 1024u, ldsx = (unsigned)(wid & 3) * 1024u;
;     const unsigned ldsbase = (unsigned)__builtin_amdgcn_readfirstlane((int)(unsigned)(__UINTPTR_TYPE__)lds);
;     const int aoff = lds_byte(wr * 64 + fr, fq * 8), boff = lds_byte(wc * 32 + fr, fq * 8);
;     const int xoff = XOFF + fr * 256 + fq * 16;
;     ...
;     Unit cur, nxt; int ui = 0;
;     if (!S.next(0, cur)) return;
;     f32x4 acc[2][2][4][2]; f32x4 accx[2];
; #pragma unroll
;     for (int a = 0; a < 2; ++a)
; #pragma unroll
;         for (int b = 0; b < 2; ++b)
; #pragma unroll
;             for (int m = 0; m < 4; ++m)
; #pragma unroll
;                 for (int n = 0; n < 2; ++n) acc[a][b][m][n] = (f32x4){0.f, 0.f, 0.f, 0.f};
;     accx[0] = (f32x4){0.f, 0.f, 0.f, 0.f}; accx[1] = accx[0];
;     bf16x8 At[4][2], B0[2][2], B1[2][2], Ax[2];
;     const char* cA = PG8_APTR(cur); const char* cB = PG8_BPTR(cur);
;     S.a_ready(cur);
;     PG8_STAGE(PG8_SB(0, 0), cB, voffB); PG8_STAGE(PG8_SB(0, 1), cB + hstepB, voffB); PG8_STAGE(PG8_SA(0, 0), cA, voffA); PG8_STAGEX(0, cA + xstep); PG8_STAGE(PG8_SA(0, 1), cA + hstepA, voffA);
;     if (wr == 1) PG8_BAR;
;     PG8_WAIT_V(2); PG8_BAR;
;     PG8_STAGE(PG8_SB(1, 0), cB + kstep, voffB); PG8_STAGE(PG8_SA(1, 0), cA + kstep, voffA); PG8_STAGE(PG8_SB(1, 1), cB + hstepB + kstep, voffB);
;     PG8_WAIT_V(6); PG8_BAR;
.LBB0_968:
	s_mov_b64 s[0:1], s[30:31]
	s_mov_b64 s[4:5], s[30:31]
	s_mov_b64 s[8:9], s[30:31]
	v_mov_b32_e32 v4, v0
	s_andn2_b64 vcc, exec, s[96:97]
	v_readfirstlane_b32 s20, v4
	s_cbranch_vccnz .LBB0_967
	v_bfe_i32 v7, v4, 27, 1
	v_lshlrev_b32_e32 v5, 4, v4
	v_lshrrev_b32_e32 v7, 22, v7
	v_add_u32_e32 v7, v5, v7
	v_and_b32_e32 v7, 0xfffffc00, v7
	v_sub_u32_e32 v7, v5, v7
	v_ashrrev_i32_e32 v6, 31, v4
	v_lshrrev_b32_e32 v8, 4, v7
	v_lshrrev_b32_e32 v6, 26, v6
	v_bitop3_b32 v7, v8, v7, 32 bitop3:0x6c
	s_add_u32 s14, s0, 0x1a1e4000
	v_add_u32_e32 v6, v4, v6
	v_ashrrev_i32_e32 v9, 31, v7
	s_addc_u32 s15, s1, 0
	v_ashrrev_i32_e32 v6, 6, v6
	v_lshrrev_b32_e32 v9, 26, v9
	s_add_u32 s0, s4, s12
	v_lshlrev_b32_e32 v8, 3, v6
	v_add_u32_e32 v9, v7, v9
	s_addc_u32 s1, s5, 0
	v_and_b32_e32 v8, -16, v8
	v_ashrrev_i32_e32 v10, 6, v9
	v_and_b32_e32 v9, 0xc0, v9
	s_add_u32 s16, s0, 0x32a0000
	v_add_u32_e32 v8, v10, v8
	v_sub_u32_e32 v7, v7, v9
	s_addc_u32 s17, s1, 0
	v_lshlrev_b32_e32 v6, 5, v6
	v_ashrrev_i16_sdwa v7, v1, sext(v7) dst_sel:DWORD dst_unused:UNUSED_PAD src0_sel:DWORD src1_sel:BYTE_0
	v_lshlrev_b32_e32 v9, 1, v8
	v_lshrrev_b32_e32 v11, 2, v8
	v_and_b32_e32 v10, 3, v10
	s_mov_b32 s1, 0xfffe0
	v_and_b32_e32 v6, 32, v6
	v_bfe_i32 v7, v7, 0, 16
	v_and_b32_e32 v9, 24, v9
	v_and_b32_e32 v11, 4, v11
	v_and_or_b32 v10, v8, s1, v10
	v_or3_b32 v9, v10, v11, v9
	v_add_lshl_u32 v6, v6, v7, 1
	v_add_u32_e32 v5, 0x2000, v5
	v_lshl_add_u32 v225, v8, 12, v6
	v_lshl_add_u32 v226, v9, 12, v6
	v_ashrrev_i32_e32 v6, 31, v5
	v_lshrrev_b32_e32 v6, 22, v6
	v_add_u32_e32 v6, v5, v6
	v_ashrrev_i32_e32 v6, 10, v6
	v_mul_i32_i24_e32 v7, 0x400, v6
	v_sub_u32_e32 v5, v5, v7
	v_lshrrev_b32_e32 v7, 4, v5
	v_bitop3_b32 v5, v7, v5, 32 bitop3:0x6c
	v_ashrrev_i32_e32 v8, 31, v5
	v_lshrrev_b32_e32 v8, 26, v8
	v_lshlrev_b32_e32 v7, 3, v6
	v_add_u32_e32 v8, v5, v8
	s_ashr_i32 s0, s20, 6
	v_and_b32_e32 v7, -16, v7
	v_ashrrev_i32_e32 v9, 6, v8
	v_and_b32_e32 v8, 0xc0, v8
	s_and_b32 s21, s0, 3
	v_add_u32_e32 v7, v9, v7
	v_sub_u32_e32 v5, v5, v8
	v_and_b32_e32 v9, 3, v9
	v_lshlrev_b32_e32 v6, 5, v6
	v_ashrrev_i16_sdwa v5, v1, sext(v5) dst_sel:DWORD dst_unused:UNUSED_PAD src0_sel:DWORD src1_sel:BYTE_0
	v_lshlrev_b32_e32 v8, 1, v7
	v_lshrrev_b32_e32 v10, 2, v7
	v_and_or_b32 v9, v7, s1, v9
	s_ashr_i32 s22, s20, 8
	s_lshl_b32 s1, s21, 14
	s_lshl_b32 s0, s0, 10
	s_lshl_b32 s23, s21, 10
	v_readlane_b32 s4, v254, 41
	v_and_b32_e32 v6, 32, v6
	v_bfe_i32 v5, v5, 0, 16
	v_and_b32_e32 v8, 24, v8
	v_and_b32_e32 v10, 4, v10
	v_readlane_b32 s5, v254, 42
	s_add_u32 s4, s16, s4
	v_bfe_u32 v2, v4, 4, 2
	v_or3_b32 v8, v9, v10, v8
	v_add_lshl_u32 v5, v6, v5, 1
	v_and_b32_e32 v4, 15, v4
	s_addc_u32 s5, s17, s5
	s_add_i32 s18, s0, 0
	v_lshl_add_u32 v227, v7, 12, v5
	v_lshl_add_u32 v228, v8, 12, v5
	v_lshlrev_b32_e32 v5, 4, v4
	v_lshlrev_b32_e32 v6, 12, v2
	s_add_i32 s19, s18, 0x10000
	s_mov_b32 m0, s19
	s_nop 0
	global_load_lds_dwordx4 v226, s[4:5]
	v_or3_b32 v229, s1, v6, v5
	v_lshrrev_b32_e32 v232, 8, v229
	v_and_b32_e32 v232, 0xf0, v232
	v_xor_b32_e32 v229, v229, v232
	s_add_i32 s24, s18, 0x12000
	s_mov_b32 m0, s24
	s_nop 0
	global_load_lds_dwordx4 v228, s[4:5]
	v_readlane_b32 s1, v254, 23
	s_mul_i32 s0, s1, s10
	s_add_u32 s6, s14, s0
	s_mul_hi_i32 s0, s1, s10
	s_addc_u32 s7, s15, s0
	s_add_u32 s0, s4, 0x80000
	s_addc_u32 s1, s5, 0
	s_add_i32 s25, s18, 0x14000
	s_mov_b32 m0, s25
	s_nop 0
	global_load_lds_dwordx4 v226, s[0:1]
	s_add_i32 s28, s18, 0x16000
	s_mov_b32 m0, s28
	s_nop 0
	global_load_lds_dwordx4 v228, s[0:1]
	v_readlane_b32 s0, v254, 38
	v_readlane_b32 s1, v254, 39
	s_add_u32 s6, s6, s0
	s_addc_u32 s7, s7, s1
	s_mov_b32 m0, s18
	s_nop 0
	global_load_lds_dwordx4 v225, s[6:7]
	s_add_i32 s29, s18, 0x2000
	s_mov_b32 m0, s29
	s_nop 0
	global_load_lds_dwordx4 v227, s[6:7]
	s_add_u32 s0, s6, 0x100000
	s_addc_u32 s1, s7, 0
	s_add_i32 s30, s23, 0
	s_add_i32 s23, s30, 0x20400
	s_mov_b32 m0, s23
	s_nop 0
	global_load_lds_dwordx4 v229, s[0:1]
	s_add_u32 s0, s6, 0x80000
	s_addc_u32 s1, s7, 0
	s_add_i32 s31, s18, 0x4000
	s_mov_b32 m0, s31
	s_nop 0
	global_load_lds_dwordx4 v225, s[0:1]
	s_add_i32 s36, s18, 0x6000
	s_mov_b32 m0, s36
	s_nop 0
	global_load_lds_dwordx4 v227, s[0:1]
	s_cmp_eq_u32 s22, 1
	s_cselect_b64 s[0:1], -1, 0
	s_cmp_lg_u32 s22, 1
	s_cbranch_scc1 .LBB0_971
	s_barrier
.LBB0_971:
	s_add_u32 s44, s8, 0x2de84000
	v_lshlrev_b32_e32 v5, 3, v2
	v_lshlrev_b32_e32 v2, 4, v2
	v_lshlrev_b32_e32 v7, 2, v4
	s_addc_u32 s45, s9, 0
	v_lshl_or_b32 v6, v4, 6, v2
	s_lshl_b32 s8, s22, 13
	v_and_b32_e32 v7, 32, v7
	v_bitop3_b32 v8, v6, s8, v7 bitop3:0xde
	s_lshl_b32 s8, s21, 12
	v_bitop3_b32 v6, v6, s8, v7 bitop3:0xde
	s_add_u32 s8, s4, 0x80
	s_waitcnt vmcnt(2)
	s_barrier
	s_addc_u32 s9, s5, 0
	s_add_i32 s37, s18, 0x18000
	s_mov_b32 m0, s37
	s_nop 0
	global_load_lds_dwordx4 v226, s[8:9]
	s_add_i32 s51, s18, 0x1a000
	s_mov_b32 m0, s51
	s_nop 0
	global_load_lds_dwordx4 v228, s[8:9]
	s_add_u32 s8, s6, 0x80
	s_addc_u32 s9, s7, 0
	s_add_i32 s52, s18, 0x8000
	s_mov_b32 m0, s52
	s_nop 0
	global_load_lds_dwordx4 v225, s[8:9]
	s_add_i32 s56, s18, 0xa000
	s_mov_b32 m0, s56
	s_nop 0
	global_load_lds_dwordx4 v227, s[8:9]
	s_add_u32 s8, s4, 0x80080
	s_addc_u32 s9, s5, 0
	s_add_i32 s57, s18, 0x1c000
	s_mov_b32 m0, s57
	s_nop 0
	global_load_lds_dwordx4 v226, s[8:9]
	s_add_i32 s58, s18, 0x1e000
	s_add_i32 s59, s18, 0xc000
	s_mov_b32 m0, s58
	s_nop 0
	global_load_lds_dwordx4 v228, s[8:9]
	s_cmpk_lt_u32 s20, 0x100
	s_waitcnt vmcnt(6)
	s_cselect_b64 s[46:47], -1, 0
	s_cmpk_gt_u32 s20, 0xff
	v_lshl_or_b32 v231, s21, 5, v5
	v_lshl_add_u32 v5, v4, 8, 0
	s_mov_b32 s8, 0x20400
	s_cselect_b64 s[62:63], -1, 0
	s_lshl_b32 s74, s22, 2
	v_lshl_or_b32 v230, s22, 6, v4
	v_lshlrev_b32_e32 v232, 4, v4
	v_xor_b32_e32 v232, v232, v2
	v_add3_u32 v232, v5, v232, s8
	v_or_b32_e32 v233, 0x100, v4
	s_ashr_i32 s75, s74, 31
	s_add_i32 s83, s18, 0xe000
	s_mov_b32 s84, 0
	v_add_u32_e32 v234, 0, v6
	v_add_u32_e32 v235, 0, v8
	v_readlane_b32 s60, v254, 40
	v_readlane_b32 s61, v254, 23
	s_barrier
	s_branch .LBB0_974

; #define PG8_STAGE(bufoff, gbase, voff) do { _Pragma("unroll") for (int _i = 0; _i < 2; ++_i) glds16_s((voff)[_i], (const void*)(gbase), ldsbase + (unsigned)((bufoff) + _i * 8192) + ldsw); } while (0)
; #define PG8_LDA(dst, b, h) do { _Pragma("unroll") for (int m = 0; m < 4; ++m) _Pragma("unroll") for (int k = 0; k < 2; ++k) dst[m][k] = *(const PG8_LAS bf16x8*)(lds + PG8_SA(b, h) + aoff + m * 2048 + k * 1024); } while (0)
; #define PG8_MMA(ai, bj, At, Bt) do { __builtin_amdgcn_s_setprio(1); _Pragma("unroll") for (int m = 0; m < 4; ++m) _Pragma("unroll") for (int n = 0; n < 2; ++n) _Pragma("unroll") for (int k = 0; k < 2; ++k) \
;         acc[ai][bj][m][n] = __builtin_amdgcn_mfma_f32_16x16x32_bf16(Bt[n][k], At[m][k], acc[ai][bj][m][n], 0, 0, 0); __builtin_amdgcn_s_setprio(0); } while (0)
; #define PG8_WAIT_V(n) asm volatile("s_waitcnt vmcnt(" #n ")" ::: "memory")
; #define PG8_WAIT_L(n) asm volatile("s_waitcnt lgkmcnt(" #n ")" ::: "memory")
; #define PG8_BAR __builtin_amdgcn_s_barrier()
; #define PG8_SCHED __builtin_amdgcn_sched_barrier(0)
; template <class Epi, class Sched, bool HM = false>
; __device__ __forceinline__ void gemm_phase(PG8_LAS unsigned char* lds, const Gemm g, const Sched& S, const Epi& E) {
;     ...
;             if (!HM) PG8_LDA(At, 1, 1); PG8_STAGE(PG8_SB(1, 0), b3, voffB); PG8_STAGE(PG8_SB(1, 1), b3 + hstepB, voffB); PG8_STAGE(PG8_SA(1, 0), a3, voffA);
;             PG8_WAIT_V(8); PG8_WAIT_L(0); PG8_BAR; if (!HM) { PG8_MMA(1, 0, At, B0); PG8_MMA(1, 1, At, B1); } PG8_BAR; PG8_SCHED;
;         }
.LBB0_985:
.LBB0_986:
	s_barrier
	ds_read_b128 v[182:185], v235 offset:49152
	ds_read_b128 v[186:189], v235 offset:50176
	ds_read_b128 v[190:193], v235 offset:51200
	ds_read_b128 v[194:197], v235 offset:52224
	ds_read_b128 v[198:201], v235 offset:53248
	ds_read_b128 v[202:205], v235 offset:54272
	ds_read_b128 v[206:209], v235 offset:55296
	ds_read_b128 v[210:213], v235 offset:56320
	s_mov_b32 m0, s37
	s_nop 0
	global_load_lds_dwordx4 v226, s[6:7]
	s_nop 0
	s_mov_b32 m0, s51
	s_nop 0
	global_load_lds_dwordx4 v228, s[6:7]
	s_add_u32 s6, s6, 0x80000
	s_addc_u32 s7, s7, 0
	s_mov_b32 m0, s57
	s_nop 0
	global_load_lds_dwordx4 v226, s[6:7]
	s_nop 0
	s_mov_b32 m0, s58
	s_nop 0
	global_load_lds_dwordx4 v228, s[6:7]
	s_mov_b32 m0, s52
	s_nop 0
	global_load_lds_dwordx4 v225, s[4:5]
	s_nop 0
	s_mov_b32 m0, s56
	s_nop 0
	global_load_lds_dwordx4 v227, s[4:5]
	s_waitcnt vmcnt(8)
	s_waitcnt lgkmcnt(0)
	s_barrier
	s_setprio 1
	s_waitcnt lgkmcnt(7)
	v_mfma_f32_16x16x32_bf16 v[82:85], v[166:169], v[182:185], v[82:85]
	v_mfma_f32_16x16x32_bf16 v[78:81], v[174:177], v[182:185], v[78:81]
	s_waitcnt lgkmcnt(5)
	v_mfma_f32_16x16x32_bf16 v[74:77], v[166:169], v[190:193], v[74:77]
	v_mfma_f32_16x16x32_bf16 v[66:69], v[174:177], v[190:193], v[66:69]
	s_waitcnt lgkmcnt(3)
	v_mfma_f32_16x16x32_bf16 v[58:61], v[166:169], v[198:201], v[58:61]
	v_mfma_f32_16x16x32_bf16 v[50:53], v[174:177], v[198:201], v[50:53]
	s_waitcnt lgkmcnt(1)
	v_mfma_f32_16x16x32_bf16 v[42:45], v[166:169], v[206:209], v[42:45]
	v_mfma_f32_16x16x32_bf16 v[34:37], v[174:177], v[206:209], v[34:37]
	v_mfma_f32_16x16x32_bf16 v[82:85], v[170:173], v[186:189], v[82:85]
	v_mfma_f32_16x16x32_bf16 v[78:81], v[178:181], v[186:189], v[78:81]
	v_mfma_f32_16x16x32_bf16 v[74:77], v[170:173], v[194:197], v[74:77]
	v_mfma_f32_16x16x32_bf16 v[66:69], v[178:181], v[194:197], v[66:69]
	v_mfma_f32_16x16x32_bf16 v[58:61], v[170:173], v[202:205], v[58:61]
	v_mfma_f32_16x16x32_bf16 v[50:53], v[178:181], v[202:205], v[50:53]
	s_waitcnt lgkmcnt(0)
	v_mfma_f32_16x16x32_bf16 v[42:45], v[170:173], v[210:213], v[42:45]
	v_mfma_f32_16x16x32_bf16 v[34:37], v[178:181], v[210:213], v[34:37]
	s_setprio 0
	s_setprio 1
	v_mfma_f32_16x16x32_bf16 v[70:73], v[150:153], v[182:185], v[70:73]
	v_mfma_f32_16x16x32_bf16 v[62:65], v[158:161], v[182:185], v[62:65]
	v_mfma_f32_16x16x32_bf16 v[54:57], v[150:153], v[190:193], v[54:57]
	v_mfma_f32_16x16x32_bf16 v[46:49], v[158:161], v[190:193], v[46:49]
	v_mfma_f32_16x16x32_bf16 v[38:41], v[150:153], v[198:201], v[38:41]
	v_mfma_f32_16x16x32_bf16 v[30:33], v[158:161], v[198:201], v[30:33]
	v_mfma_f32_16x16x32_bf16 v[26:29], v[150:153], v[206:209], v[26:29]
	v_mfma_f32_16x16x32_bf16 v[22:25], v[158:161], v[206:209], v[22:25]
	v_mfma_f32_16x16x32_bf16 v[70:73], v[154:157], v[186:189], v[70:73]
	v_mfma_f32_16x16x32_bf16 v[62:65], v[162:165], v[186:189], v[62:65]
	v_mfma_f32_16x16x32_bf16 v[54:57], v[154:157], v[194:197], v[54:57]
	v_mfma_f32_16x16x32_bf16 v[46:49], v[162:165], v[194:197], v[46:49]
	v_mfma_f32_16x16x32_bf16 v[38:41], v[154:157], v[202:205], v[38:41]
	v_mfma_f32_16x16x32_bf16 v[30:33], v[162:165], v[202:205], v[30:33]
	v_mfma_f32_16x16x32_bf16 v[26:29], v[154:157], v[210:213], v[26:29]
	v_mfma_f32_16x16x32_bf16 v[22:25], v[162:165], v[210:213], v[22:25]
	s_setprio 0
	s_barrier
	s_add_i32 s23, s23, 2
	s_addk_i32 s22, 0x1000
	s_add_u32 s89, s89, 0x100
	s_addc_u32 s90, s90, 0
	s_add_u32 s27, s27, 0x100
	s_addc_u32 s82, s82, 0
	s_cmp_gt_u32 s23, 29
	s_cbranch_scc1 .LBB0_1002

; #define PG8_STAGE(bufoff, gbase, voff) do { _Pragma("unroll") for (int _i = 0; _i < 2; ++_i) glds16_s((voff)[_i], (const void*)(gbase), ldsbase + (unsigned)((bufoff) + _i * 8192) + ldsw); } while (0)
; #define PG8_STAGEX(pb, gbase) glds16_s(voffX, (const void*)(gbase), ldsbase + (unsigned)(XOFF + (pb) * 4096) + ldsx)
; #define PG8_LDA(dst, b, h) do { _Pragma("unroll") for (int m = 0; m < 4; ++m) _Pragma("unroll") for (int k = 0; k < 2; ++k) dst[m][k] = *(const PG8_LAS bf16x8*)(lds + PG8_SA(b, h) + aoff + m * 2048 + k * 1024); } while (0)
; #define PG8_LDB(dst, b, h) do { _Pragma("unroll") for (int n = 0; n < 2; ++n) _Pragma("unroll") for (int k = 0; k < 2; ++k) dst[n][k] = *(const PG8_LAS bf16x8*)(lds + PG8_SB(b, h) + boff + n * 2048 + k * 1024); } while (0)
; #define PG8_LDX(pb, tp) do { _Pragma("unroll") for (int k = 0; k < 2; ++k) Ax[k] = *(const PG8_LAS bf16x8*)(lds + xoff + (pb) * 4096 + (tp) * 128 + k * 64); } while (0)
; #define PG8_MMA(ai, bj, At, Bt) do { __builtin_amdgcn_s_setprio(1); _Pragma("unroll") for (int m = 0; m < 4; ++m) _Pragma("unroll") for (int n = 0; n < 2; ++n) _Pragma("unroll") for (int k = 0; k < 2; ++k) \
;         acc[ai][bj][m][n] = __builtin_amdgcn_mfma_f32_16x16x32_bf16(Bt[n][k], At[m][k], acc[ai][bj][m][n], 0, 0, 0); __builtin_amdgcn_s_setprio(0); } while (0)
; #define PG8_WAIT_V(n) asm volatile("s_waitcnt vmcnt(" #n ")" ::: "memory")
; #define PG8_WAIT_L(n) asm volatile("s_waitcnt lgkmcnt(" #n ")" ::: "memory")
; #define PG8_BAR __builtin_amdgcn_s_barrier()
; #define PG8_SCHED __builtin_amdgcn_sched_barrier(0)
; template <class Epi, class Sched, bool HM = false>
; __device__ __forceinline__ void gemm_phase(PG8_LAS unsigned char* lds, const Gemm g, const Sched& S, const Epi& E) {
;     ...
;             PG8_LDB(B0, 0, 0); PG8_LDB(B1, 0, 1); PG8_SCHED; PG8_LDA(At, 0, 0); if (hasx) PG8_LDX(pb, 0); PG8_STAGE(PG8_SA(1, 1), a1 + hstepA, voffA); PG8_STAGEX(pb ^ 1, a2 + xstep);
;             PG8_WAIT_V(9); PG8_WAIT_L(0); PG8_BAR; PG8_MMA(0, 0, At, B0); PG8_MMA(0, 1, At, B1); if (hasx) PG8_MMAX(); PG8_BAR; PG8_SCHED;
.LBB0_989:
	s_add_u32 s42, s42, 0x80000
	s_addc_u32 s43, s43, 0
	s_mov_b32 m0, s59
	s_nop 0
	global_load_lds_dwordx4 v225, s[42:43]
	s_nop 0
	s_mov_b32 m0, s83
	s_nop 0
	global_load_lds_dwordx4 v227, s[42:43]
	s_add_u32 s42, s8, 0x100000
	s_addc_u32 s43, s9, 0
	s_xor_b32 s20, s20, 0x21400
	s_add_i32 s20, s30, s20
	s_mov_b32 m0, s20
	s_nop 0
	global_load_lds_dwordx4 v229, s[42:43]
	s_waitcnt vmcnt(9)
	s_waitcnt lgkmcnt(0)
	s_barrier
	s_setprio 1
	s_waitcnt lgkmcnt(7)
	v_mfma_f32_16x16x32_bf16 v[146:149], v[166:169], v[206:209], v[146:149]
	v_mfma_f32_16x16x32_bf16 v[142:145], v[174:177], v[206:209], v[142:145]
	s_waitcnt lgkmcnt(5)
	v_mfma_f32_16x16x32_bf16 v[138:141], v[166:169], v[198:201], v[138:141]
	v_mfma_f32_16x16x32_bf16 v[130:133], v[174:177], v[198:201], v[130:133]
	s_waitcnt lgkmcnt(3)
	v_mfma_f32_16x16x32_bf16 v[122:125], v[166:169], v[190:193], v[122:125]
	v_mfma_f32_16x16x32_bf16 v[114:117], v[174:177], v[190:193], v[114:117]
	s_waitcnt lgkmcnt(1)
	v_mfma_f32_16x16x32_bf16 v[106:109], v[166:169], v[182:185], v[106:109]
	v_mfma_f32_16x16x32_bf16 v[98:101], v[174:177], v[182:185], v[98:101]
	v_mfma_f32_16x16x32_bf16 v[146:149], v[170:173], v[210:213], v[146:149]
	v_mfma_f32_16x16x32_bf16 v[142:145], v[178:181], v[210:213], v[142:145]
	v_mfma_f32_16x16x32_bf16 v[138:141], v[170:173], v[202:205], v[138:141]
	v_mfma_f32_16x16x32_bf16 v[130:133], v[178:181], v[202:205], v[130:133]
	v_mfma_f32_16x16x32_bf16 v[122:125], v[170:173], v[194:197], v[122:125]
	v_mfma_f32_16x16x32_bf16 v[114:117], v[178:181], v[194:197], v[114:117]
	s_waitcnt lgkmcnt(0)
	v_mfma_f32_16x16x32_bf16 v[106:109], v[170:173], v[186:189], v[106:109]
	v_mfma_f32_16x16x32_bf16 v[98:101], v[178:181], v[186:189], v[98:101]
	s_setprio 0
	s_setprio 1
	v_mfma_f32_16x16x32_bf16 v[134:137], v[150:153], v[206:209], v[134:137]
	v_mfma_f32_16x16x32_bf16 v[126:129], v[158:161], v[206:209], v[126:129]
	v_mfma_f32_16x16x32_bf16 v[118:121], v[150:153], v[198:201], v[118:121]
	v_mfma_f32_16x16x32_bf16 v[110:113], v[158:161], v[198:201], v[110:113]
	v_mfma_f32_16x16x32_bf16 v[102:105], v[150:153], v[190:193], v[102:105]
	v_mfma_f32_16x16x32_bf16 v[94:97], v[158:161], v[190:193], v[94:97]
	v_mfma_f32_16x16x32_bf16 v[90:93], v[150:153], v[182:185], v[90:93]
	v_mfma_f32_16x16x32_bf16 v[86:89], v[158:161], v[182:185], v[86:89]
	v_mfma_f32_16x16x32_bf16 v[134:137], v[154:157], v[210:213], v[134:137]
	v_mfma_f32_16x16x32_bf16 v[126:129], v[162:165], v[210:213], v[126:129]
	v_mfma_f32_16x16x32_bf16 v[118:121], v[154:157], v[202:205], v[118:121]
	v_mfma_f32_16x16x32_bf16 v[110:113], v[162:165], v[202:205], v[110:113]
	v_mfma_f32_16x16x32_bf16 v[102:105], v[154:157], v[194:197], v[102:105]
	v_mfma_f32_16x16x32_bf16 v[94:97], v[162:165], v[194:197], v[94:97]
	v_mfma_f32_16x16x32_bf16 v[90:93], v[154:157], v[186:189], v[90:93]
	v_mfma_f32_16x16x32_bf16 v[86:89], v[162:165], v[186:189], v[86:89]
	s_setprio 0
	v_cndmask_b32_e64 v4, 0, 1, s[62:63]
	s_and_b64 vcc, exec, s[40:41]
	v_cmp_ne_u32_e64 s[42:43], 1, v4
	s_cbranch_vccnz .LBB0_995
	s_and_b64 vcc, exec, s[42:43]
	s_mov_b64 s[20:21], -1
	s_cbranch_vccnz .LBB0_992
	v_mfma_f32_16x16x32_bf16 v[18:21], v[174:177], v[6:9], v[18:21]
	s_mov_b64 s[20:21], 0
	v_mfma_f32_16x16x32_bf16 v[14:17], v[158:161], v[6:9], v[14:17]
	v_mfma_f32_16x16x32_bf16 v[18:21], v[178:181], v[10:13], v[18:21]
	v_mfma_f32_16x16x32_bf16 v[14:17], v[162:165], v[10:13], v[14:17]

; #define PG8_STAGE(bufoff, gbase, voff) do { _Pragma("unroll") for (int _i = 0; _i < 2; ++_i) glds16_s((voff)[_i], (const void*)(gbase), ldsbase + (unsigned)((bufoff) + _i * 8192) + ldsw); } while (0)
; #define PG8_LDA(dst, b, h) do { _Pragma("unroll") for (int m = 0; m < 4; ++m) _Pragma("unroll") for (int k = 0; k < 2; ++k) dst[m][k] = *(const PG8_LAS bf16x8*)(lds + PG8_SA(b, h) + aoff + m * 2048 + k * 1024); } while (0)
; #define PG8_LDB(dst, b, h) do { _Pragma("unroll") for (int n = 0; n < 2; ++n) _Pragma("unroll") for (int k = 0; k < 2; ++k) dst[n][k] = *(const PG8_LAS bf16x8*)(lds + PG8_SB(b, h) + boff + n * 2048 + k * 1024); } while (0)
; #define PG8_LDX(pb, tp) do { _Pragma("unroll") for (int k = 0; k < 2; ++k) Ax[k] = *(const PG8_LAS bf16x8*)(lds + xoff + (pb) * 4096 + (tp) * 128 + k * 64); } while (0)
; #define PG8_MMA(ai, bj, At, Bt) do { __builtin_amdgcn_s_setprio(1); _Pragma("unroll") for (int m = 0; m < 4; ++m) _Pragma("unroll") for (int n = 0; n < 2; ++n) _Pragma("unroll") for (int k = 0; k < 2; ++k) \
;         acc[ai][bj][m][n] = __builtin_amdgcn_mfma_f32_16x16x32_bf16(Bt[n][k], At[m][k], acc[ai][bj][m][n], 0, 0, 0); __builtin_amdgcn_s_setprio(0); } while (0)
; #define PG8_WAIT_V(n) asm volatile("s_waitcnt vmcnt(" #n ")" ::: "memory")
; #define PG8_WAIT_L(n) asm volatile("s_waitcnt lgkmcnt(" #n ")" ::: "memory")
; #define PG8_BAR __builtin_amdgcn_s_barrier()
; #define PG8_SCHED __builtin_amdgcn_sched_barrier(0)
; template <class Epi, class Sched, bool HM = false>
; __device__ __forceinline__ void gemm_phase(PG8_LAS unsigned char* lds, const Gemm g, const Sched& S, const Epi& E) {
;     ...
;             if (!HM) PG8_LDA(At, 0, 1); PG8_STAGE(PG8_SB(0, 0), b2, voffB); PG8_STAGE(PG8_SB(0, 1), b2 + hstepB, voffB); PG8_STAGE(PG8_SA(0, 0), a2, voffA);
;             PG8_WAIT_V(9); PG8_WAIT_L(0); PG8_BAR; if (!HM) { PG8_MMA(1, 0, At, B0); PG8_MMA(1, 1, At, B1); } PG8_BAR; PG8_SCHED;
;             PG8_LDB(B0, 1, 0); PG8_LDB(B1, 1, 1); PG8_SCHED; PG8_LDA(At, 1, 0); if (hasx) PG8_LDX(pb, 1); PG8_STAGE(PG8_SA(0, 1), a2 + hstepA, voffA);
.LBB0_994:
.LBB0_995:
	s_barrier
	ds_read_b128 v[182:185], v235 offset:16384
	ds_read_b128 v[186:189], v235 offset:17408
	ds_read_b128 v[190:193], v235 offset:18432
	ds_read_b128 v[194:197], v235 offset:19456
	ds_read_b128 v[198:201], v235 offset:20480
	ds_read_b128 v[202:205], v235 offset:21504
	ds_read_b128 v[206:209], v235 offset:22528
	ds_read_b128 v[210:213], v235 offset:23552
	s_mov_b32 m0, s19
	s_nop 0
	global_load_lds_dwordx4 v226, s[34:35]
	s_nop 0
	s_mov_b32 m0, s24
	s_nop 0
	global_load_lds_dwordx4 v228, s[34:35]
	s_add_u32 s20, s34, 0x80000
	s_addc_u32 s21, s35, 0
	s_mov_b32 m0, s25
	s_nop 0
	global_load_lds_dwordx4 v226, s[20:21]
	s_nop 0
	s_mov_b32 m0, s28
	s_nop 0
	global_load_lds_dwordx4 v228, s[20:21]
	s_mov_b32 m0, s18
	s_nop 0
	global_load_lds_dwordx4 v225, s[8:9]
	s_nop 0
	s_mov_b32 m0, s29
	s_nop 0
	global_load_lds_dwordx4 v227, s[8:9]
	s_waitcnt vmcnt(9)
	s_waitcnt lgkmcnt(0)
	s_barrier
	s_setprio 1
	s_waitcnt lgkmcnt(7)
	v_mfma_f32_16x16x32_bf16 v[82:85], v[166:169], v[182:185], v[82:85]
	v_mfma_f32_16x16x32_bf16 v[78:81], v[174:177], v[182:185], v[78:81]
	s_waitcnt lgkmcnt(5)
	v_mfma_f32_16x16x32_bf16 v[74:77], v[166:169], v[190:193], v[74:77]
	v_mfma_f32_16x16x32_bf16 v[66:69], v[174:177], v[190:193], v[66:69]
	s_waitcnt lgkmcnt(3)
	v_mfma_f32_16x16x32_bf16 v[58:61], v[166:169], v[198:201], v[58:61]
	v_mfma_f32_16x16x32_bf16 v[50:53], v[174:177], v[198:201], v[50:53]
	s_waitcnt lgkmcnt(1)
	v_mfma_f32_16x16x32_bf16 v[42:45], v[166:169], v[206:209], v[42:45]
	v_mfma_f32_16x16x32_bf16 v[34:37], v[174:177], v[206:209], v[34:37]
	v_mfma_f32_16x16x32_bf16 v[82:85], v[170:173], v[186:189], v[82:85]
	v_mfma_f32_16x16x32_bf16 v[78:81], v[178:181], v[186:189], v[78:81]
	v_mfma_f32_16x16x32_bf16 v[74:77], v[170:173], v[194:197], v[74:77]
	v_mfma_f32_16x16x32_bf16 v[66:69], v[178:181], v[194:197], v[66:69]
	v_mfma_f32_16x16x32_bf16 v[58:61], v[170:173], v[202:205], v[58:61]
	v_mfma_f32_16x16x32_bf16 v[50:53], v[178:181], v[202:205], v[50:53]
	s_waitcnt lgkmcnt(0)
	v_mfma_f32_16x16x32_bf16 v[42:45], v[170:173], v[210:213], v[42:45]
	v_mfma_f32_16x16x32_bf16 v[34:37], v[178:181], v[210:213], v[34:37]
	s_setprio 0
	s_setprio 1
	v_mfma_f32_16x16x32_bf16 v[70:73], v[150:153], v[182:185], v[70:73]
	v_mfma_f32_16x16x32_bf16 v[62:65], v[158:161], v[182:185], v[62:65]
	v_mfma_f32_16x16x32_bf16 v[54:57], v[150:153], v[190:193], v[54:57]
	v_mfma_f32_16x16x32_bf16 v[46:49], v[158:161], v[190:193], v[46:49]
	v_mfma_f32_16x16x32_bf16 v[38:41], v[150:153], v[198:201], v[38:41]
	v_mfma_f32_16x16x32_bf16 v[30:33], v[158:161], v[198:201], v[30:33]
	v_mfma_f32_16x16x32_bf16 v[26:29], v[150:153], v[206:209], v[26:29]
	v_mfma_f32_16x16x32_bf16 v[22:25], v[158:161], v[206:209], v[22:25]
	v_mfma_f32_16x16x32_bf16 v[70:73], v[154:157], v[186:189], v[70:73]
	v_mfma_f32_16x16x32_bf16 v[62:65], v[162:165], v[186:189], v[62:65]
	v_mfma_f32_16x16x32_bf16 v[54:57], v[154:157], v[194:197], v[54:57]
	v_mfma_f32_16x16x32_bf16 v[46:49], v[162:165], v[194:197], v[46:49]
	v_mfma_f32_16x16x32_bf16 v[38:41], v[154:157], v[202:205], v[38:41]
	v_mfma_f32_16x16x32_bf16 v[30:33], v[162:165], v[202:205], v[30:33]
	v_mfma_f32_16x16x32_bf16 v[26:29], v[154:157], v[210:213], v[26:29]
	v_mfma_f32_16x16x32_bf16 v[22:25], v[162:165], v[210:213], v[22:25]
	s_setprio 0
	s_barrier
	v_add_u32_e32 v4, 0x18000, v234
	ds_read_b128 v[166:169], v4
	ds_read_b128 v[170:173], v4 offset:1024
	ds_read_b128 v[174:177], v4 offset:2048
	ds_read_b128 v[178:181], v4 offset:3072
	v_add_u32_e32 v4, 0x1c000, v234
	ds_read_b128 v[150:153], v4
	ds_read_b128 v[154:157], v4 offset:1024
	ds_read_b128 v[158:161], v4 offset:2048
	ds_read_b128 v[162:165], v4 offset:3072
	ds_read_b128 v[206:209], v235 offset:32768
	ds_read_b128 v[210:213], v235 offset:33792
	ds_read_b128 v[198:201], v235 offset:34816
	ds_read_b128 v[202:205], v235 offset:35840
	ds_read_b128 v[190:193], v235 offset:36864
	ds_read_b128 v[194:197], v235 offset:37888
	ds_read_b128 v[182:185], v235 offset:38912
	ds_read_b128 v[186:189], v235 offset:39936
	s_and_b64 vcc, exec, s[40:41]
	s_cbranch_vccnz .LBB0_997
	v_xor_b32_e32 v6, 0x80, v2
	ds_read_b128 v[6:9], v6
	v_xor_b32_e32 v10, 0xc0, v2
	ds_read_b128 v[10:13], v10
; #define PG8_STAGE(bufoff, gbase, voff) do { _Pragma("unroll") for (int _i = 0; _i < 2; ++_i) glds16_s((voff)[_i], (const void*)(gbase), ldsbase + (unsigned)((bufoff) + _i * 8192) + ldsw); } while (0)
; #define PG8_LDA(dst, b, h) do { _Pragma("unroll") for (int m = 0; m < 4; ++m) _Pragma("unroll") for (int k = 0; k < 2; ++k) dst[m][k] = *(const PG8_LAS bf16x8*)(lds + PG8_SA(b, h) + aoff + m * 2048 + k * 1024); } while (0)
; #define PG8_LDB(dst, b, h) do { _Pragma("unroll") for (int n = 0; n < 2; ++n) _Pragma("unroll") for (int k = 0; k < 2; ++k) dst[n][k] = *(const PG8_LAS bf16x8*)(lds + PG8_SB(b, h) + boff + n * 2048 + k * 1024); } while (0)
; #define PG8_LDX(pb, tp) do { _Pragma("unroll") for (int k = 0; k < 2; ++k) Ax[k] = *(const PG8_LAS bf16x8*)(lds + xoff + (pb) * 4096 + (tp) * 128 + k * 64); } while (0)
; #define PG8_MMA(ai, bj, At, Bt) do { __builtin_amdgcn_s_setprio(1); _Pragma("unroll") for (int m = 0; m < 4; ++m) _Pragma("unroll") for (int n = 0; n < 2; ++n) _Pragma("unroll") for (int k = 0; k < 2; ++k) \
;         acc[ai][bj][m][n] = __builtin_amdgcn_mfma_f32_16x16x32_bf16(Bt[n][k], At[m][k], acc[ai][bj][m][n], 0, 0, 0); __builtin_amdgcn_s_setprio(0); } while (0)
; #define PG8_WAIT_V(n) asm volatile("s_waitcnt vmcnt(" #n ")" ::: "memory")
; #define PG8_WAIT_L(n) asm volatile("s_waitcnt lgkmcnt(" #n ")" ::: "memory")
; #define PG8_BAR __builtin_amdgcn_s_barrier()
; #define PG8_SCHED __builtin_amdgcn_sched_barrier(0)
; template <class Epi, class Sched, bool HM = false>
; __device__ __forceinline__ void gemm_phase(PG8_LAS unsigned char* lds, const Gemm g, const Sched& S, const Epi& E) {
;     ...
;             PG8_LDB(B0, 1, 0); PG8_LDB(B1, 1, 1); PG8_SCHED; PG8_LDA(At, 1, 0); if (hasx) PG8_LDX(pb, 1); PG8_STAGE(PG8_SA(0, 1), a2 + hstepA, voffA);
;             PG8_WAIT_V(9); PG8_WAIT_L(0); PG8_BAR; PG8_MMA(0, 0, At, B0); PG8_MMA(0, 1, At, B1); if (hasx) PG8_MMAX(); PG8_BAR; PG8_SCHED;
.LBB0_997:
	s_add_u32 s8, s8, 0x80000
	s_addc_u32 s9, s9, 0
	s_mov_b32 m0, s31
	s_nop 0
	global_load_lds_dwordx4 v225, s[8:9]
	s_nop 0
	s_mov_b32 m0, s36
	s_nop 0
	global_load_lds_dwordx4 v227, s[8:9]
	s_waitcnt vmcnt(9)
	s_waitcnt lgkmcnt(0)
	s_barrier
	s_setprio 1
	s_waitcnt lgkmcnt(7)
	v_mfma_f32_16x16x32_bf16 v[146:149], v[166:169], v[206:209], v[146:149]
	v_mfma_f32_16x16x32_bf16 v[142:145], v[174:177], v[206:209], v[142:145]
	s_waitcnt lgkmcnt(5)
	v_mfma_f32_16x16x32_bf16 v[138:141], v[166:169], v[198:201], v[138:141]
	v_mfma_f32_16x16x32_bf16 v[130:133], v[174:177], v[198:201], v[130:133]
	s_waitcnt lgkmcnt(3)
	v_mfma_f32_16x16x32_bf16 v[122:125], v[166:169], v[190:193], v[122:125]
	v_mfma_f32_16x16x32_bf16 v[114:117], v[174:177], v[190:193], v[114:117]
	s_waitcnt lgkmcnt(1)
	v_mfma_f32_16x16x32_bf16 v[106:109], v[166:169], v[182:185], v[106:109]
	v_mfma_f32_16x16x32_bf16 v[98:101], v[174:177], v[182:185], v[98:101]
	v_mfma_f32_16x16x32_bf16 v[146:149], v[170:173], v[210:213], v[146:149]
	v_mfma_f32_16x16x32_bf16 v[142:145], v[178:181], v[210:213], v[142:145]
	v_mfma_f32_16x16x32_bf16 v[138:141], v[170:173], v[202:205], v[138:141]
	v_mfma_f32_16x16x32_bf16 v[130:133], v[178:181], v[202:205], v[130:133]
	v_mfma_f32_16x16x32_bf16 v[122:125], v[170:173], v[194:197], v[122:125]
	v_mfma_f32_16x16x32_bf16 v[114:117], v[178:181], v[194:197], v[114:117]
	s_waitcnt lgkmcnt(0)
	v_mfma_f32_16x16x32_bf16 v[106:109], v[170:173], v[186:189], v[106:109]
	v_mfma_f32_16x16x32_bf16 v[98:101], v[178:181], v[186:189], v[98:101]
	s_setprio 0
	s_setprio 1
	v_mfma_f32_16x16x32_bf16 v[134:137], v[150:153], v[206:209], v[134:137]
	v_mfma_f32_16x16x32_bf16 v[126:129], v[158:161], v[206:209], v[126:129]
	v_mfma_f32_16x16x32_bf16 v[118:121], v[150:153], v[198:201], v[118:121]
	v_mfma_f32_16x16x32_bf16 v[110:113], v[158:161], v[198:201], v[110:113]
	v_mfma_f32_16x16x32_bf16 v[102:105], v[150:153], v[190:193], v[102:105]
	v_mfma_f32_16x16x32_bf16 v[94:97], v[158:161], v[190:193], v[94:97]
	v_mfma_f32_16x16x32_bf16 v[90:93], v[150:153], v[182:185], v[90:93]
	v_mfma_f32_16x16x32_bf16 v[86:89], v[158:161], v[182:185], v[86:89]
	v_mfma_f32_16x16x32_bf16 v[134:137], v[154:157], v[210:213], v[134:137]
	v_mfma_f32_16x16x32_bf16 v[126:129], v[162:165], v[210:213], v[126:129]
	v_mfma_f32_16x16x32_bf16 v[118:121], v[154:157], v[202:205], v[118:121]
	v_mfma_f32_16x16x32_bf16 v[110:113], v[162:165], v[202:205], v[110:113]
	v_mfma_f32_16x16x32_bf16 v[102:105], v[154:157], v[194:197], v[102:105]
	v_mfma_f32_16x16x32_bf16 v[94:97], v[162:165], v[194:197], v[94:97]
	v_mfma_f32_16x16x32_bf16 v[90:93], v[154:157], v[186:189], v[90:93]
	v_mfma_f32_16x16x32_bf16 v[86:89], v[162:165], v[186:189], v[86:89]
	s_setprio 0
	s_and_b64 vcc, exec, s[40:41]
	s_cbranch_vccnz .LBB0_986
	s_and_b64 vcc, exec, s[42:43]
	s_mov_b64 s[8:9], -1
	s_cbranch_vccnz .LBB0_1000
	v_mfma_f32_16x16x32_bf16 v[18:21], v[174:177], v[6:9], v[18:21]
	s_mov_b64 s[8:9], 0
	v_mfma_f32_16x16x32_bf16 v[14:17], v[158:161], v[6:9], v[14:17]
	v_mfma_f32_16x16x32_bf16 v[18:21], v[178:181], v[10:13], v[18:21]
	v_mfma_f32_16x16x32_bf16 v[14:17], v[162:165], v[10:13], v[14:17]

; #define PG8_STAGE(bufoff, gbase, voff) do { _Pragma("unroll") for (int _i = 0; _i < 2; ++_i) glds16_s((voff)[_i], (const void*)(gbase), ldsbase + (unsigned)((bufoff) + _i * 8192) + ldsw); } while (0)
; template <class Epi, class Sched, bool HM = false>
; __device__ __forceinline__ void gemm_phase(PG8_LAS unsigned char* lds, const Gemm g, const Sched& S, const Epi& E) {
;     ...
;     for (int i = 0; i < 2; ++i) { int R, C; stage_rc(tid * 16 + i * 8192, R, C); const int Rb = Epi::PERM ? ((R & ~31) + perm32(R & 31)) : R;
;         voffA[i] = (unsigned)(R * g.lda + C) * 2u; voffB[i] = (unsigned)(Rb * g.ldb + C) * 2u; }
;     const unsigned voffX = (unsigned)((4 * (wid & 3) + (lane >> 4)) * g.lda + 8 * (lane & 15)) * 2u;
;     const size_t kstep = (size_t)(BK * 2);
;     const size_t hstepA = (size_t)HALF * g.lda * 2, hstepB = (size_t)HALF * g.ldb * 2;
;     const size_t tstepA = (size_t)(HM ? HALF : g.pms) * g.lda * 2, tstepB = 2 * hstepB, xstep = 2 * hstepA; const bool hasx = g.pms != BM;
;     const unsigned ldsw = (unsigned)wid * 1024u, ldsx = (unsigned)(wid & 3) * 1024u;
;     const unsigned ldsbase = (unsigned)__builtin_amdgcn_readfirstlane((int)(unsigned)(__UINTPTR_TYPE__)lds);
;     const int aoff = lds_byte(wr * 64 + fr, fq * 8), boff = lds_byte(wc * 32 + fr, fq * 8);
;     const int xoff = XOFF + fr * 256 + fq * 16;
;     ...
;     Unit cur, nxt; int ui = 0;
;     if (!S.next(0, cur)) return;
;     f32x4 acc[2][2][4][2]; f32x4 accx[2];
; #pragma unroll
;     for (int a = 0; a < 2; ++a)
; #pragma unroll
;         for (int b = 0; b < 2; ++b)
; #pragma unroll
;             for (int m = 0; m < 4; ++m)
; #pragma unroll
;                 for (int n = 0; n < 2; ++n) acc[a][b][m][n] = (f32x4){0.f, 0.f, 0.f, 0.f};
;     accx[0] = (f32x4){0.f, 0.f, 0.f, 0.f}; accx[1] = accx[0];
;     bf16x8 At[4][2], B0[2][2], B1[2][2], Ax[2];
;     const char* cA = PG8_APTR(cur); const char* cB = PG8_BPTR(cur);
;     S.a_ready(cur);
;     PG8_STAGE(PG8_SB(0, 0), cB, voffB); PG8_STAGE(PG8_SB(0, 1), cB + hstepB, voffB); PG8_STAGE(PG8_SA(0, 0), cA, voffA); PG8_STAGEX(0, cA + xstep); PG8_STAGE(PG8_SA(0, 1), cA + hstepA, voffA);
;     if (wr == 1) PG8_BAR;
;     PG8_WAIT_V(2); PG8_BAR;
;     PG8_STAGE(PG8_SB(1, 0), cB + kstep, voffB); PG8_STAGE(PG8_SA(1, 0), cA + kstep, voffA); PG8_STAGE(PG8_SB(1, 1), cB + hstepB + kstep, voffB);
;     PG8_WAIT_V(6); PG8_BAR;
.LBB0_1149:
	s_mov_b64 s[0:1], s[30:31]
	s_mov_b64 s[4:5], s[30:31]
	s_mov_b64 s[6:7], s[30:31]
	v_mov_b32_e32 v5, v0
	s_andn2_b64 vcc, exec, s[70:71]
	v_readfirstlane_b32 s8, v5
	s_cbranch_vccnz .LBB0_1169
	v_bfe_i32 v6, v5, 27, 1
	v_lshlrev_b32_e32 v4, 4, v5
	v_lshrrev_b32_e32 v6, 22, v6
	v_add_u32_e32 v6, v4, v6
	v_and_b32_e32 v6, 0xfffffc00, v6
	v_sub_u32_e32 v6, v4, v6
	v_ashrrev_i32_e32 v2, 31, v5
	v_lshrrev_b32_e32 v7, 4, v6
	v_lshrrev_b32_e32 v2, 26, v2
	v_bitop3_b32 v6, v7, v6, 32 bitop3:0x6c
	s_add_u32 s34, s0, 0x1a1e4000
	v_add_u32_e32 v2, v5, v2
	v_ashrrev_i32_e32 v8, 31, v6
	s_addc_u32 s35, s1, 0
	v_readlane_b32 s0, v255, 25
	v_ashrrev_i32_e32 v2, 6, v2
	v_lshrrev_b32_e32 v8, 26, v8
	s_add_u32 s0, s4, s0
	v_lshlrev_b32_e32 v7, 3, v2
	v_add_u32_e32 v8, v6, v8
	s_addc_u32 s1, s5, s89
	v_and_b32_e32 v7, -16, v7
	v_ashrrev_i32_e32 v9, 6, v8
	v_and_b32_e32 v8, 0xc0, v8
	s_add_u32 s43, s0, 0x52a0000
	v_add_u32_e32 v7, v9, v7
	v_sub_u32_e32 v6, v6, v8
	s_addc_u32 s46, s1, 0
	v_lshlrev_b32_e32 v2, 5, v2
	v_ashrrev_i16_sdwa v6, v1, sext(v6) dst_sel:DWORD dst_unused:UNUSED_PAD src0_sel:DWORD src1_sel:BYTE_0
	v_lshlrev_b32_e32 v8, 1, v7
	v_lshrrev_b32_e32 v10, 2, v7
	v_and_b32_e32 v9, 3, v9
	s_mov_b32 s1, 0xfffe0
	v_and_b32_e32 v2, 32, v2
	v_bfe_i32 v6, v6, 0, 16
	v_and_b32_e32 v8, 24, v8
	v_and_b32_e32 v10, 4, v10
	v_and_or_b32 v9, v7, s1, v9
	v_or3_b32 v8, v9, v10, v8
	v_add_lshl_u32 v6, v2, v6, 1
	v_add_u32_e32 v4, 0x2000, v4
	v_lshl_add_u32 v2, v7, 12, v6
	v_lshl_add_u32 v134, v8, 12, v6
	v_ashrrev_i32_e32 v6, 31, v4
	v_lshrrev_b32_e32 v6, 22, v6
	v_add_u32_e32 v6, v4, v6
	v_ashrrev_i32_e32 v6, 10, v6
	v_mul_i32_i24_e32 v7, 0x400, v6
	v_sub_u32_e32 v4, v4, v7
	v_lshrrev_b32_e32 v7, 4, v4
	v_bitop3_b32 v4, v7, v4, 32 bitop3:0x6c
	v_ashrrev_i32_e32 v8, 31, v4
	v_lshrrev_b32_e32 v8, 26, v8
	v_lshlrev_b32_e32 v7, 3, v6
	v_add_u32_e32 v8, v4, v8
	v_and_b32_e32 v7, -16, v7
	v_ashrrev_i32_e32 v9, 6, v8
	v_and_b32_e32 v8, 0xc0, v8
	v_add_u32_e32 v7, v9, v7
	v_sub_u32_e32 v4, v4, v8
	v_lshlrev_b32_e32 v6, 5, v6
	v_ashrrev_i16_sdwa v4, v1, sext(v4) dst_sel:DWORD dst_unused:UNUSED_PAD src0_sel:DWORD src1_sel:BYTE_0
	v_lshlrev_b32_e32 v8, 1, v7
	v_lshrrev_b32_e32 v10, 2, v7
	v_and_b32_e32 v9, 3, v9
	v_and_b32_e32 v6, 32, v6
	v_bfe_i32 v4, v4, 0, 16
	v_and_b32_e32 v8, 24, v8
	v_and_b32_e32 v10, 4, v10
	v_and_or_b32 v9, v7, s1, v9
	s_ashr_i32 s0, s8, 6
	v_or3_b32 v8, v9, v10, v8
	v_add_lshl_u32 v4, v6, v4, 1
	s_and_b32 s9, s0, 3
	v_lshl_add_u32 v135, v7, 12, v4
	v_lshl_add_u32 v136, v8, 12, v4
	v_and_b32_e32 v4, 15, v5
	v_bfe_u32 v5, v5, 4, 2
	s_lshl_b32 s1, s9, 14
	v_lshlrev_b32_e32 v6, 12, v5
	v_lshlrev_b32_e32 v7, 4, v4
	s_ashr_i32 s12, s8, 8
	v_or3_b32 v137, s1, v6, v7
	s_lshl_b32 s4, s0, 10
	s_lshl_b32 s13, s9, 10
	s_mov_b64 s[0:1], s[68:69]
	s_add_u32 s0, s43, s0
	s_addc_u32 s1, s46, s1
	s_add_i32 s47, s4, 0
	s_add_i32 s90, s47, 0x10000
	s_mov_b32 m0, s90
	s_nop 0
	global_load_lds_dwordx4 v134, s[0:1]
	s_add_i32 s91, s47, 0x12000
	s_mov_b32 m0, s91
	s_nop 0
	global_load_lds_dwordx4 v136, s[0:1]
	s_nop 0
	v_readlane_b32 s4, v255, 23
	v_readlane_b32 s5, v255, 24
	s_add_u32 s14, s34, s4
	s_addc_u32 s15, s35, s5
	s_add_u32 s4, s0, 0x80000
	s_addc_u32 s5, s1, 0
	s_add_i32 s92, s47, 0x14000
	s_mov_b32 m0, s92
	s_nop 0
	global_load_lds_dwordx4 v134, s[4:5]
	s_add_i32 s20, s47, 0x16000
	s_mov_b32 m0, s20
	s_nop 0
	global_load_lds_dwordx4 v136, s[4:5]
	s_mov_b64 s[4:5], s[66:67]
	s_add_u32 s4, s14, s4
	s_addc_u32 s5, s15, s5
	s_mov_b32 m0, s47
	s_nop 0
	global_load_lds_dwordx4 v2, s[4:5]
	s_add_i32 s21, s47, 0x2000
	s_mov_b32 m0, s21
	s_nop 0
	global_load_lds_dwordx4 v135, s[4:5]
	s_add_u32 s14, s4, 0x100000
	s_addc_u32 s15, s5, 0
	s_add_i32 s97, s13, 0
	s_add_i32 s13, s97, 0x20400
	s_mov_b32 m0, s13
	s_nop 0
	global_load_lds_dwordx4 v137, s[14:15]
	s_add_u32 s14, s4, 0x80000
	s_addc_u32 s15, s5, 0
	s_add_i32 s42, s47, 0x4000
	s_mov_b32 m0, s42
	s_nop 0
	global_load_lds_dwordx4 v2, s[14:15]
	s_add_i32 s40, s47, 0x6000
	s_mov_b32 m0, s40
	s_nop 0
	global_load_lds_dwordx4 v135, s[14:15]
	s_cmp_eq_u32 s12, 1
	s_cselect_b64 s[62:63], -1, 0
	s_cmp_lg_u32 s12, 1
	s_cbranch_scc1 .LBB0_1152
	s_barrier
.LBB0_1152:
	v_lshlrev_b32_e32 v6, 3, v5
	v_lshlrev_b32_e32 v5, 4, v5
	s_add_u32 s74, s6, 0x30084000
	v_lshl_or_b32 v138, s12, 6, v4
	v_lshl_or_b32 v5, v4, 6, v5
	v_lshlrev_b32_e32 v4, 2, v4
	s_addc_u32 s75, s7, 0
	s_lshl_b32 s6, s12, 13
	v_and_b32_e32 v4, 32, v4
	v_bitop3_b32 v7, v5, s6, v4 bitop3:0xde
	s_lshl_b32 s6, s9, 12
	v_bitop3_b32 v4, v5, s6, v4 bitop3:0xde
	s_add_u32 s6, s0, 0x80
	s_waitcnt vmcnt(2)
	s_barrier
	s_addc_u32 s7, s1, 0
	s_add_i32 s41, s47, 0x18000
	s_mov_b32 m0, s41
	s_nop 0
	global_load_lds_dwordx4 v134, s[6:7]
	s_add_i32 s44, s47, 0x1a000
	s_mov_b32 m0, s44
	s_nop 0
	global_load_lds_dwordx4 v136, s[6:7]
	s_add_u32 s6, s4, 0x80
	s_addc_u32 s7, s5, 0
	s_add_i32 s45, s47, 0x8000
	s_mov_b32 m0, s45
	s_nop 0
	global_load_lds_dwordx4 v2, s[6:7]
	s_add_i32 s58, s47, 0xa000
	s_mov_b32 m0, s58
	s_nop 0
	global_load_lds_dwordx4 v135, s[6:7]
	s_add_u32 s6, s0, 0x80080
	s_addc_u32 s7, s1, 0
	s_add_i32 s59, s47, 0x1c000
	s_mov_b32 m0, s59
	s_nop 0
	global_load_lds_dwordx4 v134, s[6:7]
	s_add_i32 s60, s47, 0x1e000
	s_mov_b32 m0, s60
	s_nop 0
	global_load_lds_dwordx4 v136, s[6:7]
	s_waitcnt vmcnt(6)
	s_add_i32 s61, s47, 0xc000
	s_cmpk_lt_u32 s8, 0x100
	v_readlane_b32 s6, v255, 21
	v_lshl_or_b32 v139, s9, 5, v6
	s_cselect_b64 s[76:77], -1, 0
	s_add_i32 s83, s47, 0xe000
	s_mov_b32 s51, 0
	v_add_u32_e32 v140, 0, v4
	v_add_u32_e32 v141, 0, v7
	s_mov_b32 s12, s88
	s_mov_b32 s13, s6
	s_barrier
	v_readlane_b32 s7, v255, 22
	s_branch .LBB0_1155

; #define PG8_STAGE(bufoff, gbase, voff) do { _Pragma("unroll") for (int _i = 0; _i < 2; ++_i) glds16_s((voff)[_i], (const void*)(gbase), ldsbase + (unsigned)((bufoff) + _i * 8192) + ldsw); } while (0)
; #define PG8_STAGEX(pb, gbase) glds16_s(voffX, (const void*)(gbase), ldsbase + (unsigned)(XOFF + (pb) * 4096) + ldsx)
; #define PG8_LDA(dst, b, h) do { _Pragma("unroll") for (int m = 0; m < 4; ++m) _Pragma("unroll") for (int k = 0; k < 2; ++k) dst[m][k] = *(const PG8_LAS bf16x8*)(lds + PG8_SA(b, h) + aoff + m * 2048 + k * 1024); } while (0)
; #define PG8_LDB(dst, b, h) do { _Pragma("unroll") for (int n = 0; n < 2; ++n) _Pragma("unroll") for (int k = 0; k < 2; ++k) dst[n][k] = *(const PG8_LAS bf16x8*)(lds + PG8_SB(b, h) + boff + n * 2048 + k * 1024); } while (0)
; #define PG8_LDX(pb, tp) do { _Pragma("unroll") for (int k = 0; k < 2; ++k) Ax[k] = *(const PG8_LAS bf16x8*)(lds + xoff + (pb) * 4096 + (tp) * 128 + k * 64); } while (0)
; #define PG8_WAIT_V(n) asm volatile("s_waitcnt vmcnt(" #n ")" ::: "memory")
; #define PG8_WAIT_L(n) asm volatile("s_waitcnt lgkmcnt(" #n ")" ::: "memory")
; #define PG8_BAR __builtin_amdgcn_s_barrier()
; template <class Epi, class Sched, bool HM = false>
; __device__ __forceinline__ void gemm_phase(PG8_LAS unsigned char* lds, const Gemm g, const Sched& S, const Epi& E) {
;     ...
;         for (int t = 0; t < nt; t += 2) {
;             const bool last = (t == nt - 2);
;             const char* a1 = cA + (size_t)(t + 1) * kstep;
;             const char* a2 = last ? nA : cA + (size_t)(t + 2) * kstep; const char* b2 = last ? nB : cB + (size_t)(t + 2) * kstep;
;             const char* a3 = a2 + kstep; const char* b3 = b2 + kstep;
;             asm volatile("; uniform bases" : "+s"(a1), "+s"(a2), "+s"(a3), "+s"(b2), "+s"(b3));
;             if (last && has_next) S.a_ready(nxt);
;             const int pb = (t >> 1) & 1;
;             PG8_LDB(B0, 0, 0); PG8_LDB(B1, 0, 1); PG8_SCHED; PG8_LDA(At, 0, 0); if (hasx) PG8_LDX(pb, 0); PG8_STAGE(PG8_SA(1, 1), a1 + hstepA, voffA); PG8_STAGEX(pb ^ 1, a2 + xstep);
;             PG8_WAIT_V(9); PG8_WAIT_L(0); PG8_BAR; PG8_MMA(0, 0, At, B0); PG8_MMA(0, 1, At, B1); if (hasx) PG8_MMAX(); PG8_BAR; PG8_SCHED;
;             if (!HM) PG8_LDA(At, 0, 1); PG8_STAGE(PG8_SB(0, 0), b2, voffB); PG8_STAGE(PG8_SB(0, 1), b2 + hstepB, voffB); PG8_STAGE(PG8_SA(0, 0), a2, voffA);
.LBB0_1162:
	s_add_u32 s24, s17, 0xffffff80
	s_addc_u32 s25, s18, -1
	s_cmp_eq_u32 s19, 28
	s_cselect_b32 s6, s38, s17
	s_cselect_b32 s7, s39, s18
	s_cselect_b32 s9, s85, s16
	s_cselect_b32 s8, s84, s15
	s_add_u32 s0, s6, 0x80
	s_addc_u32 s1, s7, 0
	s_add_u32 s4, s8, 0x80
	s_addc_u32 s5, s9, 0
	v_add_u32_e32 v132, 0x10000, v140
	ds_read_b128 v[142:145], v132
	ds_read_b128 v[146:149], v132 offset:1024
	ds_read_b128 v[150:153], v132 offset:2048
	ds_read_b128 v[154:157], v132 offset:3072
	v_add_u32_e32 v132, 0x14000, v140
	ds_read_b128 v[158:161], v132
	s_waitcnt lgkmcnt(5)
	ds_read_b128 v[162:165], v132 offset:1024
	ds_read_b128 v[166:169], v132 offset:2048
	ds_read_b128 v[170:173], v132 offset:3072
	ds_read_b128 v[174:177], v141
	ds_read_b128 v[178:181], v141 offset:1024
	ds_read_b128 v[182:185], v141 offset:2048
	ds_read_b128 v[186:189], v141 offset:3072
	ds_read_b128 v[190:193], v141 offset:4096
	ds_read_b128 v[194:197], v141 offset:5120
	ds_read_b128 v[198:201], v141 offset:6144
	ds_read_b128 v[202:205], v141 offset:7168
	s_add_u32 s24, s24, 0x80000
	s_addc_u32 s25, s25, 0
	s_mov_b32 m0, s61
	s_nop 0
	global_load_lds_dwordx4 v2, s[24:25]
	s_nop 0
	s_mov_b32 m0, s83
	s_nop 0
	global_load_lds_dwordx4 v135, s[24:25]
	s_add_u32 s24, s6, 0x100000
	s_addc_u32 s25, s7, 0
	s_and_b32 s23, s22, 0x1000
	s_xor_b32 s23, s23, 0x21400
	s_add_i32 s23, s97, s23
	s_mov_b32 m0, s23
	s_nop 0
	global_load_lds_dwordx4 v137, s[24:25]
	s_waitcnt vmcnt(9)
	s_waitcnt lgkmcnt(0)
	s_barrier
	s_setprio 1
	s_waitcnt lgkmcnt(7)
	v_mfma_f32_16x16x32_bf16 v[128:131], v[142:145], v[174:177], v[128:131]
	v_mfma_f32_16x16x32_bf16 v[120:123], v[150:153], v[174:177], v[120:123]
	s_waitcnt lgkmcnt(5)
	v_mfma_f32_16x16x32_bf16 v[112:115], v[142:145], v[182:185], v[112:115]
	v_mfma_f32_16x16x32_bf16 v[104:107], v[150:153], v[182:185], v[104:107]
	s_waitcnt lgkmcnt(3)
	v_mfma_f32_16x16x32_bf16 v[96:99], v[142:145], v[190:193], v[96:99]
	v_mfma_f32_16x16x32_bf16 v[88:91], v[150:153], v[190:193], v[88:91]
	s_waitcnt lgkmcnt(1)
	v_mfma_f32_16x16x32_bf16 v[80:83], v[142:145], v[198:201], v[80:83]
	v_mfma_f32_16x16x32_bf16 v[72:75], v[150:153], v[198:201], v[72:75]
	v_mfma_f32_16x16x32_bf16 v[128:131], v[146:149], v[178:181], v[128:131]
	v_mfma_f32_16x16x32_bf16 v[120:123], v[154:157], v[178:181], v[120:123]
	v_mfma_f32_16x16x32_bf16 v[112:115], v[146:149], v[186:189], v[112:115]
	v_mfma_f32_16x16x32_bf16 v[104:107], v[154:157], v[186:189], v[104:107]
	v_mfma_f32_16x16x32_bf16 v[96:99], v[146:149], v[194:197], v[96:99]
	v_mfma_f32_16x16x32_bf16 v[88:91], v[154:157], v[194:197], v[88:91]
	s_waitcnt lgkmcnt(0)
	v_mfma_f32_16x16x32_bf16 v[80:83], v[146:149], v[202:205], v[80:83]
	v_mfma_f32_16x16x32_bf16 v[72:75], v[154:157], v[202:205], v[72:75]
	s_setprio 0
	s_setprio 1
	v_mfma_f32_16x16x32_bf16 v[124:127], v[158:161], v[174:177], v[124:127]
	v_mfma_f32_16x16x32_bf16 v[116:119], v[166:169], v[174:177], v[116:119]
	v_mfma_f32_16x16x32_bf16 v[108:111], v[158:161], v[182:185], v[108:111]
	v_mfma_f32_16x16x32_bf16 v[100:103], v[166:169], v[182:185], v[100:103]
	v_mfma_f32_16x16x32_bf16 v[92:95], v[158:161], v[190:193], v[92:95]
	v_mfma_f32_16x16x32_bf16 v[84:87], v[166:169], v[190:193], v[84:87]
	v_mfma_f32_16x16x32_bf16 v[76:79], v[158:161], v[198:201], v[76:79]
	v_mfma_f32_16x16x32_bf16 v[68:71], v[166:169], v[198:201], v[68:71]
	v_mfma_f32_16x16x32_bf16 v[124:127], v[162:165], v[178:181], v[124:127]
	v_mfma_f32_16x16x32_bf16 v[116:119], v[170:173], v[178:181], v[116:119]
	v_mfma_f32_16x16x32_bf16 v[108:111], v[162:165], v[186:189], v[108:111]
	v_mfma_f32_16x16x32_bf16 v[100:103], v[170:173], v[186:189], v[100:103]
	v_mfma_f32_16x16x32_bf16 v[92:95], v[162:165], v[194:197], v[92:95]
	v_mfma_f32_16x16x32_bf16 v[84:87], v[170:173], v[194:197], v[84:87]
	v_mfma_f32_16x16x32_bf16 v[76:79], v[162:165], v[202:205], v[76:79]
	v_mfma_f32_16x16x32_bf16 v[68:71], v[170:173], v[202:205], v[68:71]
	s_setprio 0
	s_barrier
	ds_read_b128 v[174:177], v141 offset:16384
	ds_read_b128 v[178:181], v141 offset:17408
	ds_read_b128 v[182:185], v141 offset:18432
	ds_read_b128 v[186:189], v141 offset:19456
	ds_read_b128 v[190:193], v141 offset:20480
	ds_read_b128 v[194:197], v141 offset:21504
	ds_read_b128 v[198:201], v141 offset:22528
	ds_read_b128 v[202:205], v141 offset:23552
	s_mov_b32 m0, s90
	s_nop 0
	global_load_lds_dwordx4 v134, s[8:9]
	s_nop 0
	s_mov_b32 m0, s91
	s_nop 0
	global_load_lds_dwordx4 v136, s[8:9]
	s_add_u32 s8, s8, 0x80000
	s_addc_u32 s9, s9, 0
	s_mov_b32 m0, s92
	s_nop 0
	global_load_lds_dwordx4 v134, s[8:9]
	s_nop 0
	s_mov_b32 m0, s20
	s_nop 0
	global_load_lds_dwordx4 v136, s[8:9]
	s_mov_b32 m0, s47
	s_nop 0
	global_load_lds_dwordx4 v2, s[6:7]
	s_nop 0
	s_mov_b32 m0, s21
	s_nop 0
	global_load_lds_dwordx4 v135, s[6:7]
	s_waitcnt vmcnt(9)
	s_waitcnt lgkmcnt(0)
	s_barrier
; #define PG8_STAGE(bufoff, gbase, voff) do { _Pragma("unroll") for (int _i = 0; _i < 2; ++_i) glds16_s((voff)[_i], (const void*)(gbase), ldsbase + (unsigned)((bufoff) + _i * 8192) + ldsw); } while (0)
; #define PG8_LDA(dst, b, h) do { _Pragma("unroll") for (int m = 0; m < 4; ++m) _Pragma("unroll") for (int k = 0; k < 2; ++k) dst[m][k] = *(const PG8_LAS bf16x8*)(lds + PG8_SA(b, h) + aoff + m * 2048 + k * 1024); } while (0)
; #define PG8_LDB(dst, b, h) do { _Pragma("unroll") for (int n = 0; n < 2; ++n) _Pragma("unroll") for (int k = 0; k < 2; ++k) dst[n][k] = *(const PG8_LAS bf16x8*)(lds + PG8_SB(b, h) + boff + n * 2048 + k * 1024); } while (0)
; #define PG8_LDX(pb, tp) do { _Pragma("unroll") for (int k = 0; k < 2; ++k) Ax[k] = *(const PG8_LAS bf16x8*)(lds + xoff + (pb) * 4096 + (tp) * 128 + k * 64); } while (0)
; #define PG8_MMA(ai, bj, At, Bt) do { __builtin_amdgcn_s_setprio(1); _Pragma("unroll") for (int m = 0; m < 4; ++m) _Pragma("unroll") for (int n = 0; n < 2; ++n) _Pragma("unroll") for (int k = 0; k < 2; ++k) \
;         acc[ai][bj][m][n] = __builtin_amdgcn_mfma_f32_16x16x32_bf16(Bt[n][k], At[m][k], acc[ai][bj][m][n], 0, 0, 0); __builtin_amdgcn_s_setprio(0); } while (0)
; #define PG8_WAIT_V(n) asm volatile("s_waitcnt vmcnt(" #n ")" ::: "memory")
; #define PG8_WAIT_L(n) asm volatile("s_waitcnt lgkmcnt(" #n ")" ::: "memory")
; #define PG8_BAR __builtin_amdgcn_s_barrier()
; #define PG8_SCHED __builtin_amdgcn_sched_barrier(0)
; template <class Epi, class Sched, bool HM = false>
; __device__ __forceinline__ void gemm_phase(PG8_LAS unsigned char* lds, const Gemm g, const Sched& S, const Epi& E) {
;     ...
;             PG8_WAIT_V(9); PG8_WAIT_L(0); PG8_BAR; if (!HM) { PG8_MMA(1, 0, At, B0); PG8_MMA(1, 1, At, B1); } PG8_BAR; PG8_SCHED;
;             PG8_LDB(B0, 1, 0); PG8_LDB(B1, 1, 1); PG8_SCHED; PG8_LDA(At, 1, 0); if (hasx) PG8_LDX(pb, 1); PG8_STAGE(PG8_SA(0, 1), a2 + hstepA, voffA);
;             PG8_WAIT_V(9); PG8_WAIT_L(0); PG8_BAR; PG8_MMA(0, 0, At, B0); PG8_MMA(0, 1, At, B1); if (hasx) PG8_MMAX(); PG8_BAR; PG8_SCHED;
	s_setprio 1
	s_waitcnt lgkmcnt(7)
	v_mfma_f32_16x16x32_bf16 v[64:67], v[142:145], v[174:177], v[64:67]
	v_mfma_f32_16x16x32_bf16 v[56:59], v[150:153], v[174:177], v[56:59]
	s_waitcnt lgkmcnt(5)
	v_mfma_f32_16x16x32_bf16 v[48:51], v[142:145], v[182:185], v[48:51]
	v_mfma_f32_16x16x32_bf16 v[40:43], v[150:153], v[182:185], v[40:43]
	s_waitcnt lgkmcnt(3)
	v_mfma_f32_16x16x32_bf16 v[32:35], v[142:145], v[190:193], v[32:35]
	v_mfma_f32_16x16x32_bf16 v[24:27], v[150:153], v[190:193], v[24:27]
	s_waitcnt lgkmcnt(1)
	v_mfma_f32_16x16x32_bf16 v[16:19], v[142:145], v[198:201], v[16:19]
	v_mfma_f32_16x16x32_bf16 v[8:11], v[150:153], v[198:201], v[8:11]
	v_mfma_f32_16x16x32_bf16 v[64:67], v[146:149], v[178:181], v[64:67]
	v_mfma_f32_16x16x32_bf16 v[56:59], v[154:157], v[178:181], v[56:59]
	v_mfma_f32_16x16x32_bf16 v[48:51], v[146:149], v[186:189], v[48:51]
	v_mfma_f32_16x16x32_bf16 v[40:43], v[154:157], v[186:189], v[40:43]
	v_mfma_f32_16x16x32_bf16 v[32:35], v[146:149], v[194:197], v[32:35]
	v_mfma_f32_16x16x32_bf16 v[24:27], v[154:157], v[194:197], v[24:27]
	s_waitcnt lgkmcnt(0)
	v_mfma_f32_16x16x32_bf16 v[16:19], v[146:149], v[202:205], v[16:19]
	v_mfma_f32_16x16x32_bf16 v[8:11], v[154:157], v[202:205], v[8:11]
	s_setprio 0
	s_setprio 1
	v_mfma_f32_16x16x32_bf16 v[60:63], v[158:161], v[174:177], v[60:63]
	v_mfma_f32_16x16x32_bf16 v[52:55], v[166:169], v[174:177], v[52:55]
	v_mfma_f32_16x16x32_bf16 v[44:47], v[158:161], v[182:185], v[44:47]
	v_mfma_f32_16x16x32_bf16 v[36:39], v[166:169], v[182:185], v[36:39]
	v_mfma_f32_16x16x32_bf16 v[28:31], v[158:161], v[190:193], v[28:31]
	v_mfma_f32_16x16x32_bf16 v[20:23], v[166:169], v[190:193], v[20:23]
	v_mfma_f32_16x16x32_bf16 v[12:15], v[158:161], v[198:201], v[12:15]
	v_mfma_f32_16x16x32_bf16 v[4:7], v[166:169], v[198:201], v[4:7]
	v_mfma_f32_16x16x32_bf16 v[60:63], v[162:165], v[178:181], v[60:63]
	v_mfma_f32_16x16x32_bf16 v[52:55], v[170:173], v[178:181], v[52:55]
	v_mfma_f32_16x16x32_bf16 v[44:47], v[162:165], v[186:189], v[44:47]
	v_mfma_f32_16x16x32_bf16 v[36:39], v[170:173], v[186:189], v[36:39]
	v_mfma_f32_16x16x32_bf16 v[28:31], v[162:165], v[194:197], v[28:31]
	v_mfma_f32_16x16x32_bf16 v[20:23], v[170:173], v[194:197], v[20:23]
	v_mfma_f32_16x16x32_bf16 v[12:15], v[162:165], v[202:205], v[12:15]
	v_mfma_f32_16x16x32_bf16 v[4:7], v[170:173], v[202:205], v[4:7]
	s_setprio 0
	s_barrier
	v_add_u32_e32 v132, 0x18000, v140
	ds_read_b128 v[142:145], v132
	ds_read_b128 v[146:149], v132 offset:1024
	ds_read_b128 v[150:153], v132 offset:2048
	ds_read_b128 v[154:157], v132 offset:3072
	v_add_u32_e32 v132, 0x1c000, v140
	ds_read_b128 v[158:161], v132
	ds_read_b128 v[162:165], v132 offset:1024
	ds_read_b128 v[166:169], v132 offset:2048
	ds_read_b128 v[170:173], v132 offset:3072
	ds_read_b128 v[174:177], v141 offset:32768
	ds_read_b128 v[178:181], v141 offset:33792
	ds_read_b128 v[182:185], v141 offset:34816
	ds_read_b128 v[186:189], v141 offset:35840
	ds_read_b128 v[190:193], v141 offset:36864
	ds_read_b128 v[194:197], v141 offset:37888
	ds_read_b128 v[198:201], v141 offset:38912
	ds_read_b128 v[202:205], v141 offset:39936
	s_add_u32 s6, s6, 0x80000
	s_addc_u32 s7, s7, 0
	s_mov_b32 m0, s42
	s_nop 0
	global_load_lds_dwordx4 v2, s[6:7]
	s_nop 0
	s_mov_b32 m0, s40
	s_nop 0
	global_load_lds_dwordx4 v135, s[6:7]
	s_waitcnt vmcnt(9)
	s_waitcnt lgkmcnt(0)
	s_barrier
	s_setprio 1
	s_waitcnt lgkmcnt(7)
	v_mfma_f32_16x16x32_bf16 v[128:131], v[142:145], v[174:177], v[128:131]
	v_mfma_f32_16x16x32_bf16 v[120:123], v[150:153], v[174:177], v[120:123]
	s_waitcnt lgkmcnt(5)
	v_mfma_f32_16x16x32_bf16 v[112:115], v[142:145], v[182:185], v[112:115]
	v_mfma_f32_16x16x32_bf16 v[104:107], v[150:153], v[182:185], v[104:107]
	s_waitcnt lgkmcnt(3)
	v_mfma_f32_16x16x32_bf16 v[96:99], v[142:145], v[190:193], v[96:99]
	v_mfma_f32_16x16x32_bf16 v[88:91], v[150:153], v[190:193], v[88:91]
	s_waitcnt lgkmcnt(1)
	v_mfma_f32_16x16x32_bf16 v[80:83], v[142:145], v[198:201], v[80:83]
	v_mfma_f32_16x16x32_bf16 v[72:75], v[150:153], v[198:201], v[72:75]
	v_mfma_f32_16x16x32_bf16 v[128:131], v[146:149], v[178:181], v[128:131]
	v_mfma_f32_16x16x32_bf16 v[120:123], v[154:157], v[178:181], v[120:123]
	v_mfma_f32_16x16x32_bf16 v[112:115], v[146:149], v[186:189], v[112:115]
	v_mfma_f32_16x16x32_bf16 v[104:107], v[154:157], v[186:189], v[104:107]
	v_mfma_f32_16x16x32_bf16 v[96:99], v[146:149], v[194:197], v[96:99]
	v_mfma_f32_16x16x32_bf16 v[88:91], v[154:157], v[194:197], v[88:91]
	s_waitcnt lgkmcnt(0)
	v_mfma_f32_16x16x32_bf16 v[80:83], v[146:149], v[202:205], v[80:83]
	v_mfma_f32_16x16x32_bf16 v[72:75], v[154:157], v[202:205], v[72:75]
	s_setprio 0
	s_setprio 1
	v_mfma_f32_16x16x32_bf16 v[124:127], v[158:161], v[174:177], v[124:127]
	v_mfma_f32_16x16x32_bf16 v[116:119], v[166:169], v[174:177], v[116:119]
	v_mfma_f32_16x16x32_bf16 v[108:111], v[158:161], v[182:185], v[108:111]
	v_mfma_f32_16x16x32_bf16 v[100:103], v[166:169], v[182:185], v[100:103]
	v_mfma_f32_16x16x32_bf16 v[92:95], v[158:161], v[190:193], v[92:95]
	v_mfma_f32_16x16x32_bf16 v[84:87], v[166:169], v[190:193], v[84:87]
	v_mfma_f32_16x16x32_bf16 v[76:79], v[158:161], v[198:201], v[76:79]
	v_mfma_f32_16x16x32_bf16 v[68:71], v[166:169], v[198:201], v[68:71]
	v_mfma_f32_16x16x32_bf16 v[124:127], v[162:165], v[178:181], v[124:127]
	v_mfma_f32_16x16x32_bf16 v[116:119], v[170:173], v[178:181], v[116:119]
	v_mfma_f32_16x16x32_bf16 v[108:111], v[162:165], v[186:189], v[108:111]
	v_mfma_f32_16x16x32_bf16 v[100:103], v[170:173], v[186:189], v[100:103]
	v_mfma_f32_16x16x32_bf16 v[92:95], v[162:165], v[194:197], v[92:95]
	v_mfma_f32_16x16x32_bf16 v[84:87], v[170:173], v[194:197], v[84:87]
	v_mfma_f32_16x16x32_bf16 v[76:79], v[162:165], v[202:205], v[76:79]
	v_mfma_f32_16x16x32_bf16 v[68:71], v[170:173], v[202:205], v[68:71]
	s_setprio 0
	s_barrier
; #define PG8_STAGE(bufoff, gbase, voff) do { _Pragma("unroll") for (int _i = 0; _i < 2; ++_i) glds16_s((voff)[_i], (const void*)(gbase), ldsbase + (unsigned)((bufoff) + _i * 8192) + ldsw); } while (0)
; #define PG8_LDA(dst, b, h) do { _Pragma("unroll") for (int m = 0; m < 4; ++m) _Pragma("unroll") for (int k = 0; k < 2; ++k) dst[m][k] = *(const PG8_LAS bf16x8*)(lds + PG8_SA(b, h) + aoff + m * 2048 + k * 1024); } while (0)
; #define PG8_MMA(ai, bj, At, Bt) do { __builtin_amdgcn_s_setprio(1); _Pragma("unroll") for (int m = 0; m < 4; ++m) _Pragma("unroll") for (int n = 0; n < 2; ++n) _Pragma("unroll") for (int k = 0; k < 2; ++k) \
;         acc[ai][bj][m][n] = __builtin_amdgcn_mfma_f32_16x16x32_bf16(Bt[n][k], At[m][k], acc[ai][bj][m][n], 0, 0, 0); __builtin_amdgcn_s_setprio(0); } while (0)
; #define PG8_WAIT_V(n) asm volatile("s_waitcnt vmcnt(" #n ")" ::: "memory")
; #define PG8_WAIT_L(n) asm volatile("s_waitcnt lgkmcnt(" #n ")" ::: "memory")
; #define PG8_BAR __builtin_amdgcn_s_barrier()
; #define PG8_SCHED __builtin_amdgcn_sched_barrier(0)
; template <class Epi, class Sched, bool HM = false>
; __device__ __forceinline__ void gemm_phase(PG8_LAS unsigned char* lds, const Gemm g, const Sched& S, const Epi& E) {
;     ...
;             if (!HM) PG8_LDA(At, 1, 1); PG8_STAGE(PG8_SB(1, 0), b3, voffB); PG8_STAGE(PG8_SB(1, 1), b3 + hstepB, voffB); PG8_STAGE(PG8_SA(1, 0), a3, voffA);
;             PG8_WAIT_V(8); PG8_WAIT_L(0); PG8_BAR; if (!HM) { PG8_MMA(1, 0, At, B0); PG8_MMA(1, 1, At, B1); } PG8_BAR; PG8_SCHED;
;         }
;         if (wr == 0) PG8_BAR;
	ds_read_b128 v[174:177], v141 offset:49152
	ds_read_b128 v[178:181], v141 offset:50176
	ds_read_b128 v[182:185], v141 offset:51200
	ds_read_b128 v[186:189], v141 offset:52224
	ds_read_b128 v[190:193], v141 offset:53248
	ds_read_b128 v[194:197], v141 offset:54272
	ds_read_b128 v[198:201], v141 offset:55296
	ds_read_b128 v[202:205], v141 offset:56320
	s_mov_b32 m0, s41
	s_nop 0
	global_load_lds_dwordx4 v134, s[4:5]
	s_nop 0
	s_mov_b32 m0, s44
	s_nop 0
	global_load_lds_dwordx4 v136, s[4:5]
	s_add_u32 s4, s4, 0x80000
	s_addc_u32 s5, s5, 0
	s_mov_b32 m0, s59
	s_nop 0
	global_load_lds_dwordx4 v134, s[4:5]
	s_nop 0
	s_mov_b32 m0, s60
	s_nop 0
	global_load_lds_dwordx4 v136, s[4:5]
	s_mov_b32 m0, s45
	s_nop 0
	global_load_lds_dwordx4 v2, s[0:1]
	s_nop 0
	s_mov_b32 m0, s58
	s_nop 0
	global_load_lds_dwordx4 v135, s[0:1]
	s_waitcnt vmcnt(8)
	s_waitcnt lgkmcnt(0)
	s_barrier
	s_setprio 1
	s_waitcnt lgkmcnt(7)
	v_mfma_f32_16x16x32_bf16 v[64:67], v[142:145], v[174:177], v[64:67]
	v_mfma_f32_16x16x32_bf16 v[56:59], v[150:153], v[174:177], v[56:59]
	s_waitcnt lgkmcnt(5)
	v_mfma_f32_16x16x32_bf16 v[48:51], v[142:145], v[182:185], v[48:51]
	v_mfma_f32_16x16x32_bf16 v[40:43], v[150:153], v[182:185], v[40:43]
	s_waitcnt lgkmcnt(3)
	v_mfma_f32_16x16x32_bf16 v[32:35], v[142:145], v[190:193], v[32:35]
	v_mfma_f32_16x16x32_bf16 v[24:27], v[150:153], v[190:193], v[24:27]
	s_waitcnt lgkmcnt(1)
	v_mfma_f32_16x16x32_bf16 v[16:19], v[142:145], v[198:201], v[16:19]
	v_mfma_f32_16x16x32_bf16 v[8:11], v[150:153], v[198:201], v[8:11]
	v_mfma_f32_16x16x32_bf16 v[64:67], v[146:149], v[178:181], v[64:67]
	v_mfma_f32_16x16x32_bf16 v[56:59], v[154:157], v[178:181], v[56:59]
	v_mfma_f32_16x16x32_bf16 v[48:51], v[146:149], v[186:189], v[48:51]
	v_mfma_f32_16x16x32_bf16 v[40:43], v[154:157], v[186:189], v[40:43]
	v_mfma_f32_16x16x32_bf16 v[32:35], v[146:149], v[194:197], v[32:35]
	v_mfma_f32_16x16x32_bf16 v[24:27], v[154:157], v[194:197], v[24:27]
	s_waitcnt lgkmcnt(0)
	v_mfma_f32_16x16x32_bf16 v[16:19], v[146:149], v[202:205], v[16:19]
	v_mfma_f32_16x16x32_bf16 v[8:11], v[154:157], v[202:205], v[8:11]
	s_setprio 0
	s_setprio 1
	v_mfma_f32_16x16x32_bf16 v[60:63], v[158:161], v[174:177], v[60:63]
	v_mfma_f32_16x16x32_bf16 v[52:55], v[166:169], v[174:177], v[52:55]
	v_mfma_f32_16x16x32_bf16 v[44:47], v[158:161], v[182:185], v[44:47]
	v_mfma_f32_16x16x32_bf16 v[36:39], v[166:169], v[182:185], v[36:39]
	v_mfma_f32_16x16x32_bf16 v[28:31], v[158:161], v[190:193], v[28:31]
	v_mfma_f32_16x16x32_bf16 v[20:23], v[166:169], v[190:193], v[20:23]
	v_mfma_f32_16x16x32_bf16 v[12:15], v[158:161], v[198:201], v[12:15]
	v_mfma_f32_16x16x32_bf16 v[4:7], v[166:169], v[198:201], v[4:7]
	v_mfma_f32_16x16x32_bf16 v[60:63], v[162:165], v[178:181], v[60:63]
	v_mfma_f32_16x16x32_bf16 v[52:55], v[170:173], v[178:181], v[52:55]
	v_mfma_f32_16x16x32_bf16 v[44:47], v[162:165], v[186:189], v[44:47]
	v_mfma_f32_16x16x32_bf16 v[36:39], v[170:173], v[186:189], v[36:39]
	v_mfma_f32_16x16x32_bf16 v[28:31], v[162:165], v[194:197], v[28:31]
	v_mfma_f32_16x16x32_bf16 v[20:23], v[170:173], v[194:197], v[20:23]
	v_mfma_f32_16x16x32_bf16 v[12:15], v[162:165], v[202:205], v[12:15]
	v_mfma_f32_16x16x32_bf16 v[4:7], v[170:173], v[202:205], v[4:7]
	s_setprio 0
	s_barrier
	s_add_i32 s19, s19, 2
	s_addk_i32 s22, 0x1000
	s_add_u32 s15, s15, 0x100
	s_addc_u32 s16, s16, 0
	s_add_u32 s17, s17, 0x100
	s_addc_u32 s18, s18, 0
	s_cmp_gt_u32 s19, 29
	s_cbranch_scc0 .LBB0_1162
	s_and_b64 vcc, exec, s[76:77]
	s_cbranch_vccz .LBB0_1165
	s_barrier

; #define PG8_STAGE(bufoff, gbase, voff) do { _Pragma("unroll") for (int _i = 0; _i < 2; ++_i) glds16_s((voff)[_i], (const void*)(gbase), ldsbase + (unsigned)((bufoff) + _i * 8192) + ldsw); } while (0)
; template <class Epi, class Sched, bool HM = false>
; __device__ __forceinline__ void gemm_phase(PG8_LAS unsigned char* lds, const Gemm g, const Sched& S, const Epi& E) {
;     ...
;     for (int i = 0; i < 2; ++i) { int R, C; stage_rc(tid * 16 + i * 8192, R, C); const int Rb = Epi::PERM ? ((R & ~31) + perm32(R & 31)) : R;
;         voffA[i] = (unsigned)(R * g.lda + C) * 2u; voffB[i] = (unsigned)(Rb * g.ldb + C) * 2u; }
;     const unsigned voffX = (unsigned)((4 * (wid & 3) + (lane >> 4)) * g.lda + 8 * (lane & 15)) * 2u;
;     const size_t kstep = (size_t)(BK * 2);
;     const size_t hstepA = (size_t)HALF * g.lda * 2, hstepB = (size_t)HALF * g.ldb * 2;
;     const size_t tstepA = (size_t)(HM ? HALF : g.pms) * g.lda * 2, tstepB = 2 * hstepB, xstep = 2 * hstepA; const bool hasx = g.pms != BM;
;     const unsigned ldsw = (unsigned)wid * 1024u, ldsx = (unsigned)(wid & 3) * 1024u;
;     const unsigned ldsbase = (unsigned)__builtin_amdgcn_readfirstlane((int)(unsigned)(__UINTPTR_TYPE__)lds);
;     const int aoff = lds_byte(wr * 64 + fr, fq * 8), boff = lds_byte(wc * 32 + fr, fq * 8);
;     const int xoff = XOFF + fr * 256 + fq * 16;
;     ...
;     Unit cur, nxt; int ui = 0;
;     if (!S.next(0, cur)) return;
;     f32x4 acc[2][2][4][2]; f32x4 accx[2];
; #pragma unroll
;     for (int a = 0; a < 2; ++a)
; #pragma unroll
;         for (int b = 0; b < 2; ++b)
; #pragma unroll
;             for (int m = 0; m < 4; ++m)
; #pragma unroll
;                 for (int n = 0; n < 2; ++n) acc[a][b][m][n] = (f32x4){0.f, 0.f, 0.f, 0.f};
;     accx[0] = (f32x4){0.f, 0.f, 0.f, 0.f}; accx[1] = accx[0];
;     bf16x8 At[4][2], B0[2][2], B1[2][2], Ax[2];
;     const char* cA = PG8_APTR(cur); const char* cB = PG8_BPTR(cur);
;     S.a_ready(cur);
;     PG8_STAGE(PG8_SB(0, 0), cB, voffB); PG8_STAGE(PG8_SB(0, 1), cB + hstepB, voffB); PG8_STAGE(PG8_SA(0, 0), cA, voffA); PG8_STAGEX(0, cA + xstep); PG8_STAGE(PG8_SA(0, 1), cA + hstepA, voffA);
;     if (wr == 1) PG8_BAR;
;     PG8_WAIT_V(2); PG8_BAR;
;     PG8_STAGE(PG8_SB(1, 0), cB + kstep, voffB); PG8_STAGE(PG8_SA(1, 0), cA + kstep, voffA); PG8_STAGE(PG8_SB(1, 1), cB + hstepB + kstep, voffB);
;     PG8_WAIT_V(6); PG8_BAR;
.LBB0_1169:
	v_readlane_b32 s0, v255, 18
	v_readlane_b32 s1, v255, 19
	s_andn2_b64 vcc, exec, s[0:1]
	s_cbranch_vccnz .LBB0_1148
	v_readlane_b32 s6, v255, 5
	s_mov_b64 s[0:1], s[30:31]
	s_mov_b64 s[4:5], s[30:31]
	s_mov_b64 s[8:9], s[30:31]
	v_mov_b32_e32 v5, v0
	v_readlane_b32 s7, v255, 6
	s_andn2_b64 vcc, exec, s[6:7]
	v_readfirstlane_b32 s22, v5
	s_cbranch_vccnz .LBB0_1148
	v_bfe_i32 v6, v5, 27, 1
	v_lshlrev_b32_e32 v4, 4, v5
	v_lshrrev_b32_e32 v6, 22, v6
	v_add_u32_e32 v6, v4, v6
	v_and_b32_e32 v6, 0xfffffc00, v6
	v_sub_u32_e32 v6, v4, v6
	v_ashrrev_i32_e32 v2, 31, v5
	v_lshrrev_b32_e32 v7, 4, v6
	v_lshrrev_b32_e32 v2, 26, v2
	v_bitop3_b32 v6, v7, v6, 32 bitop3:0x6c
	s_add_u32 s12, s0, 0x1a1e4000
	v_add_u32_e32 v2, v5, v2
	v_ashrrev_i32_e32 v8, 31, v6
	s_addc_u32 s13, s1, 0
	v_readlane_b32 s0, v255, 25
	v_ashrrev_i32_e32 v2, 6, v2
	v_lshrrev_b32_e32 v8, 26, v8
	s_add_u32 s0, s4, s0
	v_lshlrev_b32_e32 v7, 3, v2
	v_add_u32_e32 v8, v6, v8
	s_addc_u32 s1, s5, s89
	v_and_b32_e32 v7, -16, v7
	v_ashrrev_i32_e32 v9, 6, v8
	v_and_b32_e32 v8, 0xc0, v8
	s_add_u32 s14, s0, 0x7aa0000
	v_add_u32_e32 v7, v9, v7
	v_sub_u32_e32 v6, v6, v8
	s_addc_u32 s15, s1, 0
	v_lshlrev_b32_e32 v2, 5, v2
	v_ashrrev_i16_sdwa v6, v1, sext(v6) dst_sel:DWORD dst_unused:UNUSED_PAD src0_sel:DWORD src1_sel:BYTE_0
	v_lshlrev_b32_e32 v8, 1, v7
	v_lshrrev_b32_e32 v10, 2, v7
	v_and_b32_e32 v9, 3, v9
	s_mov_b32 s1, 0xfffe0
	v_and_b32_e32 v2, 32, v2
	v_bfe_i32 v6, v6, 0, 16
	v_and_b32_e32 v8, 24, v8
	v_and_b32_e32 v10, 4, v10
	v_and_or_b32 v9, v7, s1, v9
	v_or3_b32 v8, v9, v10, v8
	v_add_lshl_u32 v6, v2, v6, 1
	v_add_u32_e32 v4, 0x2000, v4
	v_lshl_add_u32 v2, v7, 12, v6
	v_lshl_add_u32 v70, v8, 12, v6
	v_ashrrev_i32_e32 v6, 31, v4
	v_lshrrev_b32_e32 v6, 22, v6
	v_add_u32_e32 v6, v4, v6
	v_ashrrev_i32_e32 v6, 10, v6
	v_mul_i32_i24_e32 v7, 0x400, v6
	v_sub_u32_e32 v4, v4, v7
	v_lshrrev_b32_e32 v7, 4, v4
	v_bitop3_b32 v4, v7, v4, 32 bitop3:0x6c
	v_ashrrev_i32_e32 v8, 31, v4
	v_lshrrev_b32_e32 v8, 26, v8
	v_lshlrev_b32_e32 v7, 3, v6
	v_add_u32_e32 v8, v4, v8
	s_ashr_i32 s0, s22, 6
	v_and_b32_e32 v7, -16, v7
	v_ashrrev_i32_e32 v9, 6, v8
	v_and_b32_e32 v8, 0xc0, v8
	s_and_b32 s23, s0, 3
	v_add_u32_e32 v7, v9, v7
	v_sub_u32_e32 v4, v4, v8
	v_and_b32_e32 v9, 3, v9
	v_lshlrev_b32_e32 v6, 5, v6
	v_ashrrev_i16_sdwa v4, v1, sext(v4) dst_sel:DWORD dst_unused:UNUSED_PAD src0_sel:DWORD src1_sel:BYTE_0
	v_lshlrev_b32_e32 v8, 1, v7
	v_lshrrev_b32_e32 v10, 2, v7
	v_and_or_b32 v9, v7, s1, v9
	s_ashr_i32 s27, s22, 8
	s_lshl_b32 s1, s23, 14
	s_lshl_b32 s0, s0, 10
	s_lshl_b32 s24, s23, 10
	v_readlane_b32 s4, v254, 30
	v_and_b32_e32 v6, 32, v6
	v_bfe_i32 v4, v4, 0, 16
	v_and_b32_e32 v8, 24, v8
	v_and_b32_e32 v10, 4, v10
	v_readlane_b32 s5, v254, 31
	s_add_u32 s4, s14, s4
	v_or3_b32 v8, v9, v10, v8
	v_add_lshl_u32 v4, v6, v4, 1
	s_addc_u32 s5, s15, s5
	s_add_i32 s16, s0, 0
	v_lshl_add_u32 v71, v7, 12, v4
	v_lshl_add_u32 v72, v8, 12, v4
	v_and_b32_e32 v4, 15, v5
	v_bfe_u32 v5, v5, 4, 2
	s_add_i32 s17, s16, 0x10000
	s_mov_b32 m0, s17
	s_nop 0
	global_load_lds_dwordx4 v70, s[4:5]
	v_lshlrev_b32_e32 v6, 12, v5
	v_lshlrev_b32_e32 v7, 4, v4
	s_add_i32 s18, s16, 0x12000
	s_mov_b32 m0, s18
	s_nop 0
	global_load_lds_dwordx4 v72, s[4:5]
	v_or3_b32 v73, s1, v6, v7
	v_readlane_b32 s0, v254, 54
	v_readlane_b32 s1, v254, 55
	s_add_u32 s6, s12, s0
	s_addc_u32 s7, s13, s1
	s_add_u32 s0, s4, 0x80000
	s_addc_u32 s1, s5, 0
	s_add_i32 s19, s16, 0x14000
	s_mov_b32 m0, s19
	s_nop 0
	global_load_lds_dwordx4 v70, s[0:1]
	s_add_i32 s20, s16, 0x16000
	s_mov_b32 m0, s20
	s_nop 0
	global_load_lds_dwordx4 v72, s[0:1]
	s_mov_b32 m0, s16
	s_nop 0
	global_load_lds_dwordx4 v2, s[6:7]
	s_add_i32 s21, s16, 0x2000
	s_mov_b32 m0, s21
	s_nop 0
	global_load_lds_dwordx4 v71, s[6:7]
	s_add_u32 s0, s6, 0x100000
	s_addc_u32 s1, s7, 0
	s_add_i32 s24, s24, 0
	s_add_i32 s25, s24, 0x20400
	s_mov_b32 m0, s25
	s_nop 0
	global_load_lds_dwordx4 v73, s[0:1]
	s_add_u32 s0, s6, 0x80000
	s_addc_u32 s1, s7, 0
	s_add_i32 s25, s16, 0x4000
	s_mov_b32 m0, s25
	s_nop 0
	global_load_lds_dwordx4 v2, s[0:1]
	s_add_i32 s28, s16, 0x6000
	s_mov_b32 m0, s28
	s_nop 0
	global_load_lds_dwordx4 v71, s[0:1]
	s_cmp_eq_u32 s27, 1
	s_cselect_b64 s[0:1], -1, 0
	s_cmp_lg_u32 s27, 1
	s_cbranch_scc1 .LBB0_1173
	s_barrier
.LBB0_1173:
	v_lshlrev_b32_e32 v6, 3, v5
	v_lshlrev_b32_e32 v5, 4, v5
	s_add_u32 s46, s8, 0x30086800
	v_lshl_or_b32 v74, s27, 6, v4
	v_lshl_or_b32 v5, v4, 6, v5
	v_lshlrev_b32_e32 v4, 2, v4
	s_addc_u32 s47, s9, 0
	s_lshl_b32 s8, s27, 13
	v_and_b32_e32 v4, 32, v4
	v_bitop3_b32 v7, v5, s8, v4 bitop3:0xde
	s_lshl_b32 s8, s23, 12
	v_bitop3_b32 v4, v5, s8, v4 bitop3:0xde
	s_add_u32 s8, s4, 0x80
	s_waitcnt vmcnt(2)
	s_barrier
	s_addc_u32 s9, s5, 0
	s_add_i32 s29, s16, 0x18000
	s_mov_b32 m0, s29
	s_nop 0
	global_load_lds_dwordx4 v70, s[8:9]
	s_add_i32 s30, s16, 0x1a000
	s_mov_b32 m0, s30
	s_nop 0
	global_load_lds_dwordx4 v72, s[8:9]
	s_add_u32 s8, s6, 0x80
	s_addc_u32 s9, s7, 0
	s_add_i32 s31, s16, 0x8000
	s_mov_b32 m0, s31
	s_nop 0
	global_load_lds_dwordx4 v2, s[8:9]
	s_add_i32 s40, s16, 0xa000
	s_mov_b32 m0, s40
	s_nop 0
	global_load_lds_dwordx4 v71, s[8:9]
	s_add_u32 s8, s4, 0x80080
	s_addc_u32 s9, s5, 0
	s_add_i32 s41, s16, 0x1c000
	s_mov_b32 m0, s41
	s_nop 0
	global_load_lds_dwordx4 v70, s[8:9]
	s_add_i32 s42, s16, 0x1e000
	s_mov_b32 m0, s42
	s_nop 0
	global_load_lds_dwordx4 v72, s[8:9]
	s_waitcnt vmcnt(6)
	s_add_i32 s43, s16, 0xc000
	s_cmpk_lt_u32 s22, 0x100
	v_readlane_b32 s8, v254, 52
	v_lshl_or_b32 v75, s23, 5, v6
	s_cselect_b64 s[62:63], -1, 0
	s_add_i32 s44, s16, 0xe000
	s_mov_b32 s45, 0
	v_add_u32_e32 v76, 0, v4
	v_add_u32_e32 v77, 0, v7
	v_readlane_b32 s22, v254, 29
	s_mov_b32 s23, s8
	s_barrier
	v_readlane_b32 s9, v254, 53
	s_branch .LBB0_1176

; #define PG8_STAGE(bufoff, gbase, voff) do { _Pragma("unroll") for (int _i = 0; _i < 2; ++_i) glds16_s((voff)[_i], (const void*)(gbase), ldsbase + (unsigned)((bufoff) + _i * 8192) + ldsw); } while (0)
; #define PG8_STAGEX(pb, gbase) glds16_s(voffX, (const void*)(gbase), ldsbase + (unsigned)(XOFF + (pb) * 4096) + ldsx)
; #define PG8_LDA(dst, b, h) do { _Pragma("unroll") for (int m = 0; m < 4; ++m) _Pragma("unroll") for (int k = 0; k < 2; ++k) dst[m][k] = *(const PG8_LAS bf16x8*)(lds + PG8_SA(b, h) + aoff + m * 2048 + k * 1024); } while (0)
; #define PG8_LDB(dst, b, h) do { _Pragma("unroll") for (int n = 0; n < 2; ++n) _Pragma("unroll") for (int k = 0; k < 2; ++k) dst[n][k] = *(const PG8_LAS bf16x8*)(lds + PG8_SB(b, h) + boff + n * 2048 + k * 1024); } while (0)
; #define PG8_LDX(pb, tp) do { _Pragma("unroll") for (int k = 0; k < 2; ++k) Ax[k] = *(const PG8_LAS bf16x8*)(lds + xoff + (pb) * 4096 + (tp) * 128 + k * 64); } while (0)
; #define PG8_WAIT_V(n) asm volatile("s_waitcnt vmcnt(" #n ")" ::: "memory")
; template <class Epi, class Sched, bool HM = false>
; __device__ __forceinline__ void gemm_phase(PG8_LAS unsigned char* lds, const Gemm g, const Sched& S, const Epi& E) {
;     ...
;         for (int t = 0; t < nt; t += 2) {
;             const bool last = (t == nt - 2);
;             const char* a1 = cA + (size_t)(t + 1) * kstep;
;             const char* a2 = last ? nA : cA + (size_t)(t + 2) * kstep; const char* b2 = last ? nB : cB + (size_t)(t + 2) * kstep;
;             const char* a3 = a2 + kstep; const char* b3 = b2 + kstep;
;             asm volatile("; uniform bases" : "+s"(a1), "+s"(a2), "+s"(a3), "+s"(b2), "+s"(b3));
;             if (last && has_next) S.a_ready(nxt);
;             const int pb = (t >> 1) & 1;
;             PG8_LDB(B0, 0, 0); PG8_LDB(B1, 0, 1); PG8_SCHED; PG8_LDA(At, 0, 0); if (hasx) PG8_LDX(pb, 0); PG8_STAGE(PG8_SA(1, 1), a1 + hstepA, voffA); PG8_STAGEX(pb ^ 1, a2 + xstep);
;             PG8_WAIT_V(9); PG8_WAIT_L(0); PG8_BAR; PG8_MMA(0, 0, At, B0); PG8_MMA(0, 1, At, B1); if (hasx) PG8_MMAX(); PG8_BAR; PG8_SCHED;
;             if (!HM) PG8_LDA(At, 0, 1); PG8_STAGE(PG8_SB(0, 0), b2, voffB); PG8_STAGE(PG8_SB(0, 1), b2 + hstepB, voffB); PG8_STAGE(PG8_SA(0, 0), a2, voffA);
;             PG8_WAIT_V(9); PG8_WAIT_L(0); PG8_BAR; if (!HM) { PG8_MMA(1, 0, At, B0); PG8_MMA(1, 1, At, B1); } PG8_BAR; PG8_SCHED;
.LBB0_1187:
	s_add_u32 s78, s58, 0xffffff80
	s_addc_u32 s79, s59, -1
	s_cmp_eq_u32 s60, 28
	s_cselect_b32 s8, s38, s58
	s_cselect_b32 s9, s39, s59
	s_cselect_b32 s35, s77, s52
	s_cselect_b32 s34, s76, s27
	s_add_u32 s4, s8, 0x80
	s_addc_u32 s5, s9, 0
	s_add_u32 s6, s34, 0x80
	s_addc_u32 s7, s35, 0
	v_add_u32_e32 v68, 0x10000, v76
	ds_read_b128 v[78:81], v68
	ds_read_b128 v[82:85], v68 offset:1024
	ds_read_b128 v[86:89], v68 offset:2048
	ds_read_b128 v[90:93], v68 offset:3072
	v_add_u32_e32 v68, 0x14000, v76
	ds_read_b128 v[94:97], v68
	ds_read_b128 v[98:101], v68 offset:1024
	ds_read_b128 v[102:105], v68 offset:2048
	ds_read_b128 v[106:109], v68 offset:3072
	ds_read_b128 v[110:113], v77
	ds_read_b128 v[114:117], v77 offset:1024
	ds_read_b128 v[118:121], v77 offset:2048
	ds_read_b128 v[122:125], v77 offset:3072
	ds_read_b128 v[126:129], v77 offset:4096
	ds_read_b128 v[130:133], v77 offset:5120
	ds_read_b128 v[134:137], v77 offset:6144
	ds_read_b128 v[138:141], v77 offset:7168
	s_add_u32 s78, s78, 0x80000
	s_addc_u32 s79, s79, 0
	s_mov_b32 m0, s43
	s_nop 0
	global_load_lds_dwordx4 v2, s[78:79]
	s_nop 0
	s_mov_b32 m0, s44
	s_nop 0
	global_load_lds_dwordx4 v71, s[78:79]
	s_add_u32 s78, s8, 0x100000
	s_addc_u32 s79, s9, 0
	s_and_b32 s75, s61, 0x1000
	s_xor_b32 s75, s75, 0x21400
	s_add_i32 s75, s24, s75
	s_mov_b32 m0, s75
	s_nop 0
	global_load_lds_dwordx4 v73, s[78:79]
	s_waitcnt vmcnt(9)
	s_waitcnt lgkmcnt(0)
	s_barrier
	s_setprio 1
	s_waitcnt lgkmcnt(7)
	v_mfma_f32_16x16x32_bf16 v[64:67], v[78:81], v[110:113], v[64:67]
	v_mfma_f32_16x16x32_bf16 v[56:59], v[86:89], v[110:113], v[56:59]
	s_waitcnt lgkmcnt(5)
	v_mfma_f32_16x16x32_bf16 v[48:51], v[78:81], v[118:121], v[48:51]
	v_mfma_f32_16x16x32_bf16 v[40:43], v[86:89], v[118:121], v[40:43]
	s_waitcnt lgkmcnt(3)
	v_mfma_f32_16x16x32_bf16 v[32:35], v[78:81], v[126:129], v[32:35]
	v_mfma_f32_16x16x32_bf16 v[24:27], v[86:89], v[126:129], v[24:27]
	s_waitcnt lgkmcnt(1)
	v_mfma_f32_16x16x32_bf16 v[16:19], v[78:81], v[134:137], v[16:19]
	v_mfma_f32_16x16x32_bf16 v[8:11], v[86:89], v[134:137], v[8:11]
	v_mfma_f32_16x16x32_bf16 v[64:67], v[82:85], v[114:117], v[64:67]
	v_mfma_f32_16x16x32_bf16 v[56:59], v[90:93], v[114:117], v[56:59]
	v_mfma_f32_16x16x32_bf16 v[48:51], v[82:85], v[122:125], v[48:51]
	v_mfma_f32_16x16x32_bf16 v[40:43], v[90:93], v[122:125], v[40:43]
	v_mfma_f32_16x16x32_bf16 v[32:35], v[82:85], v[130:133], v[32:35]
	v_mfma_f32_16x16x32_bf16 v[24:27], v[90:93], v[130:133], v[24:27]
	s_waitcnt lgkmcnt(0)
	v_mfma_f32_16x16x32_bf16 v[16:19], v[82:85], v[138:141], v[16:19]
	v_mfma_f32_16x16x32_bf16 v[8:11], v[90:93], v[138:141], v[8:11]
	s_setprio 0
	s_setprio 1
	v_mfma_f32_16x16x32_bf16 v[60:63], v[94:97], v[110:113], v[60:63]
	v_mfma_f32_16x16x32_bf16 v[52:55], v[102:105], v[110:113], v[52:55]
	v_mfma_f32_16x16x32_bf16 v[44:47], v[94:97], v[118:121], v[44:47]
	v_mfma_f32_16x16x32_bf16 v[36:39], v[102:105], v[118:121], v[36:39]
	v_mfma_f32_16x16x32_bf16 v[28:31], v[94:97], v[126:129], v[28:31]
	v_mfma_f32_16x16x32_bf16 v[20:23], v[102:105], v[126:129], v[20:23]
	v_mfma_f32_16x16x32_bf16 v[12:15], v[94:97], v[134:137], v[12:15]
	v_mfma_f32_16x16x32_bf16 v[4:7], v[102:105], v[134:137], v[4:7]
	v_mfma_f32_16x16x32_bf16 v[60:63], v[98:101], v[114:117], v[60:63]
	v_mfma_f32_16x16x32_bf16 v[52:55], v[106:109], v[114:117], v[52:55]
	v_mfma_f32_16x16x32_bf16 v[44:47], v[98:101], v[122:125], v[44:47]
	v_mfma_f32_16x16x32_bf16 v[36:39], v[106:109], v[122:125], v[36:39]
	v_mfma_f32_16x16x32_bf16 v[28:31], v[98:101], v[130:133], v[28:31]
	v_mfma_f32_16x16x32_bf16 v[20:23], v[106:109], v[130:133], v[20:23]
	v_mfma_f32_16x16x32_bf16 v[12:15], v[98:101], v[138:141], v[12:15]
	v_mfma_f32_16x16x32_bf16 v[4:7], v[106:109], v[138:141], v[4:7]
	s_setprio 0
	s_barrier
	s_mov_b32 m0, s17
	s_nop 0
	global_load_lds_dwordx4 v70, s[34:35]
	s_nop 0
	s_mov_b32 m0, s18
	s_nop 0
	global_load_lds_dwordx4 v72, s[34:35]
	s_add_u32 s34, s34, 0x80000
	s_addc_u32 s35, s35, 0
	s_mov_b32 m0, s19
	s_nop 0
	global_load_lds_dwordx4 v70, s[34:35]
	s_nop 0
	s_mov_b32 m0, s20
	s_nop 0
	global_load_lds_dwordx4 v72, s[34:35]
	s_mov_b32 m0, s16
	s_nop 0
	global_load_lds_dwordx4 v2, s[8:9]
	s_nop 0
	s_mov_b32 m0, s21
	s_nop 0
	global_load_lds_dwordx4 v71, s[8:9]
	s_waitcnt vmcnt(9)
	s_waitcnt lgkmcnt(0)
	s_barrier
; #define PG8_STAGE(bufoff, gbase, voff) do { _Pragma("unroll") for (int _i = 0; _i < 2; ++_i) glds16_s((voff)[_i], (const void*)(gbase), ldsbase + (unsigned)((bufoff) + _i * 8192) + ldsw); } while (0)
; #define PG8_LDA(dst, b, h) do { _Pragma("unroll") for (int m = 0; m < 4; ++m) _Pragma("unroll") for (int k = 0; k < 2; ++k) dst[m][k] = *(const PG8_LAS bf16x8*)(lds + PG8_SA(b, h) + aoff + m * 2048 + k * 1024); } while (0)
; #define PG8_LDB(dst, b, h) do { _Pragma("unroll") for (int n = 0; n < 2; ++n) _Pragma("unroll") for (int k = 0; k < 2; ++k) dst[n][k] = *(const PG8_LAS bf16x8*)(lds + PG8_SB(b, h) + boff + n * 2048 + k * 1024); } while (0)
; #define PG8_LDX(pb, tp) do { _Pragma("unroll") for (int k = 0; k < 2; ++k) Ax[k] = *(const PG8_LAS bf16x8*)(lds + xoff + (pb) * 4096 + (tp) * 128 + k * 64); } while (0)
; #define PG8_MMA(ai, bj, At, Bt) do { __builtin_amdgcn_s_setprio(1); _Pragma("unroll") for (int m = 0; m < 4; ++m) _Pragma("unroll") for (int n = 0; n < 2; ++n) _Pragma("unroll") for (int k = 0; k < 2; ++k) \
;         acc[ai][bj][m][n] = __builtin_amdgcn_mfma_f32_16x16x32_bf16(Bt[n][k], At[m][k], acc[ai][bj][m][n], 0, 0, 0); __builtin_amdgcn_s_setprio(0); } while (0)
; #define PG8_WAIT_V(n) asm volatile("s_waitcnt vmcnt(" #n ")" ::: "memory")
; #define PG8_WAIT_L(n) asm volatile("s_waitcnt lgkmcnt(" #n ")" ::: "memory")
; #define PG8_BAR __builtin_amdgcn_s_barrier()
; #define PG8_SCHED __builtin_amdgcn_sched_barrier(0)
; template <class Epi, class Sched, bool HM = false>
; __device__ __forceinline__ void gemm_phase(PG8_LAS unsigned char* lds, const Gemm g, const Sched& S, const Epi& E) {
;     ...
;             PG8_LDB(B0, 1, 0); PG8_LDB(B1, 1, 1); PG8_SCHED; PG8_LDA(At, 1, 0); if (hasx) PG8_LDX(pb, 1); PG8_STAGE(PG8_SA(0, 1), a2 + hstepA, voffA);
;             PG8_WAIT_V(9); PG8_WAIT_L(0); PG8_BAR; PG8_MMA(0, 0, At, B0); PG8_MMA(0, 1, At, B1); if (hasx) PG8_MMAX(); PG8_BAR; PG8_SCHED;
;             if (!HM) PG8_LDA(At, 1, 1); PG8_STAGE(PG8_SB(1, 0), b3, voffB); PG8_STAGE(PG8_SB(1, 1), b3 + hstepB, voffB); PG8_STAGE(PG8_SA(1, 0), a3, voffA);
;             PG8_WAIT_V(8); PG8_WAIT_L(0); PG8_BAR; if (!HM) { PG8_MMA(1, 0, At, B0); PG8_MMA(1, 1, At, B1); } PG8_BAR; PG8_SCHED;
;         }
;         if (wr == 0) PG8_BAR;
	s_barrier
	v_add_u32_e32 v68, 0x18000, v76
	ds_read_b128 v[78:81], v68
	ds_read_b128 v[82:85], v68 offset:1024
	ds_read_b128 v[86:89], v68 offset:2048
	ds_read_b128 v[90:93], v68 offset:3072
	v_add_u32_e32 v68, 0x1c000, v76
	ds_read_b128 v[94:97], v68
	ds_read_b128 v[98:101], v68 offset:1024
	ds_read_b128 v[102:105], v68 offset:2048
	ds_read_b128 v[106:109], v68 offset:3072
	ds_read_b128 v[110:113], v77 offset:32768
	ds_read_b128 v[114:117], v77 offset:33792
	ds_read_b128 v[118:121], v77 offset:34816
	ds_read_b128 v[122:125], v77 offset:35840
	ds_read_b128 v[126:129], v77 offset:36864
	ds_read_b128 v[130:133], v77 offset:37888
	ds_read_b128 v[134:137], v77 offset:38912
	ds_read_b128 v[138:141], v77 offset:39936
	s_add_u32 s8, s8, 0x80000
	s_addc_u32 s9, s9, 0
	s_mov_b32 m0, s25
	s_nop 0
	global_load_lds_dwordx4 v2, s[8:9]
	s_nop 0
	s_mov_b32 m0, s28
	s_nop 0
	global_load_lds_dwordx4 v71, s[8:9]
	s_waitcnt vmcnt(9)
	s_waitcnt lgkmcnt(0)
	s_barrier
	s_setprio 1
	s_waitcnt lgkmcnt(7)
	v_mfma_f32_16x16x32_bf16 v[64:67], v[78:81], v[110:113], v[64:67]
	v_mfma_f32_16x16x32_bf16 v[56:59], v[86:89], v[110:113], v[56:59]
	s_waitcnt lgkmcnt(5)
	v_mfma_f32_16x16x32_bf16 v[48:51], v[78:81], v[118:121], v[48:51]
	v_mfma_f32_16x16x32_bf16 v[40:43], v[86:89], v[118:121], v[40:43]
	s_waitcnt lgkmcnt(3)
	v_mfma_f32_16x16x32_bf16 v[32:35], v[78:81], v[126:129], v[32:35]
	v_mfma_f32_16x16x32_bf16 v[24:27], v[86:89], v[126:129], v[24:27]
	s_waitcnt lgkmcnt(1)
	v_mfma_f32_16x16x32_bf16 v[16:19], v[78:81], v[134:137], v[16:19]
	v_mfma_f32_16x16x32_bf16 v[8:11], v[86:89], v[134:137], v[8:11]
	v_mfma_f32_16x16x32_bf16 v[64:67], v[82:85], v[114:117], v[64:67]
	v_mfma_f32_16x16x32_bf16 v[56:59], v[90:93], v[114:117], v[56:59]
	v_mfma_f32_16x16x32_bf16 v[48:51], v[82:85], v[122:125], v[48:51]
	v_mfma_f32_16x16x32_bf16 v[40:43], v[90:93], v[122:125], v[40:43]
	v_mfma_f32_16x16x32_bf16 v[32:35], v[82:85], v[130:133], v[32:35]
	v_mfma_f32_16x16x32_bf16 v[24:27], v[90:93], v[130:133], v[24:27]
	s_waitcnt lgkmcnt(0)
	v_mfma_f32_16x16x32_bf16 v[16:19], v[82:85], v[138:141], v[16:19]
	v_mfma_f32_16x16x32_bf16 v[8:11], v[90:93], v[138:141], v[8:11]
	s_setprio 0
	s_setprio 1
	v_mfma_f32_16x16x32_bf16 v[60:63], v[94:97], v[110:113], v[60:63]
	v_mfma_f32_16x16x32_bf16 v[52:55], v[102:105], v[110:113], v[52:55]
	v_mfma_f32_16x16x32_bf16 v[44:47], v[94:97], v[118:121], v[44:47]
	v_mfma_f32_16x16x32_bf16 v[36:39], v[102:105], v[118:121], v[36:39]
	v_mfma_f32_16x16x32_bf16 v[28:31], v[94:97], v[126:129], v[28:31]
	v_mfma_f32_16x16x32_bf16 v[20:23], v[102:105], v[126:129], v[20:23]
	v_mfma_f32_16x16x32_bf16 v[12:15], v[94:97], v[134:137], v[12:15]
	v_mfma_f32_16x16x32_bf16 v[4:7], v[102:105], v[134:137], v[4:7]
	v_mfma_f32_16x16x32_bf16 v[60:63], v[98:101], v[114:117], v[60:63]
	v_mfma_f32_16x16x32_bf16 v[52:55], v[106:109], v[114:117], v[52:55]
	v_mfma_f32_16x16x32_bf16 v[44:47], v[98:101], v[122:125], v[44:47]
	v_mfma_f32_16x16x32_bf16 v[36:39], v[106:109], v[122:125], v[36:39]
	v_mfma_f32_16x16x32_bf16 v[28:31], v[98:101], v[130:133], v[28:31]
	v_mfma_f32_16x16x32_bf16 v[20:23], v[106:109], v[130:133], v[20:23]
	v_mfma_f32_16x16x32_bf16 v[12:15], v[98:101], v[138:141], v[12:15]
	v_mfma_f32_16x16x32_bf16 v[4:7], v[106:109], v[138:141], v[4:7]
	s_setprio 0
	s_barrier
	s_mov_b32 m0, s29
	s_nop 0
	global_load_lds_dwordx4 v70, s[6:7]
	s_nop 0
	s_mov_b32 m0, s30
	s_nop 0
	global_load_lds_dwordx4 v72, s[6:7]
	s_add_u32 s6, s6, 0x80000
	s_addc_u32 s7, s7, 0
	s_mov_b32 m0, s41
	s_nop 0
	global_load_lds_dwordx4 v70, s[6:7]
	s_nop 0
	s_mov_b32 m0, s42
	s_nop 0
	global_load_lds_dwordx4 v72, s[6:7]
	s_mov_b32 m0, s31
	s_nop 0
	global_load_lds_dwordx4 v2, s[4:5]
	s_nop 0
	s_mov_b32 m0, s40
	s_nop 0
	global_load_lds_dwordx4 v71, s[4:5]
	s_waitcnt vmcnt(8)
	s_waitcnt lgkmcnt(0)
	s_barrier
	s_barrier
	s_add_i32 s60, s60, 2
	s_addk_i32 s61, 0x1000
	s_add_u32 s27, s27, 0x100
	s_addc_u32 s52, s52, 0
	s_add_u32 s58, s58, 0x100
	s_addc_u32 s59, s59, 0
	s_cmp_gt_u32 s60, 29
	s_cbranch_scc0 .LBB0_1187
	s_and_b64 vcc, exec, s[62:63]
	s_cbranch_vccz .LBB0_1190
	s_barrier

; #define PG8_STAGE(bufoff, gbase, voff) do { _Pragma("unroll") for (int _i = 0; _i < 2; ++_i) glds16_s((voff)[_i], (const void*)(gbase), ldsbase + (unsigned)((bufoff) + _i * 8192) + ldsw); } while (0)
; template <class Epi, class Sched, bool HM = false>
; __device__ __forceinline__ void gemm_phase(PG8_LAS unsigned char* lds, const Gemm g, const Sched& S, const Epi& E) {
;     ...
;     for (int i = 0; i < 2; ++i) { int R, C; stage_rc(tid * 16 + i * 8192, R, C); const int Rb = Epi::PERM ? ((R & ~31) + perm32(R & 31)) : R;
;         voffA[i] = (unsigned)(R * g.lda + C) * 2u; voffB[i] = (unsigned)(Rb * g.ldb + C) * 2u; }
;     const unsigned voffX = (unsigned)((4 * (wid & 3) + (lane >> 4)) * g.lda + 8 * (lane & 15)) * 2u;
;     const size_t kstep = (size_t)(BK * 2);
;     const size_t hstepA = (size_t)HALF * g.lda * 2, hstepB = (size_t)HALF * g.ldb * 2;
;     const size_t tstepA = (size_t)(HM ? HALF : g.pms) * g.lda * 2, tstepB = 2 * hstepB, xstep = 2 * hstepA; const bool hasx = g.pms != BM;
;     const unsigned ldsw = (unsigned)wid * 1024u, ldsx = (unsigned)(wid & 3) * 1024u;
;     const unsigned ldsbase = (unsigned)__builtin_amdgcn_readfirstlane((int)(unsigned)(__UINTPTR_TYPE__)lds);
;     const int aoff = lds_byte(wr * 64 + fr, fq * 8), boff = lds_byte(wc * 32 + fr, fq * 8);
;     const int xoff = XOFF + fr * 256 + fq * 16;
;     ...
;     Unit cur, nxt; int ui = 0;
;     if (!S.next(0, cur)) return;
;     f32x4 acc[2][2][4][2]; f32x4 accx[2];
; #pragma unroll
;     for (int a = 0; a < 2; ++a)
; #pragma unroll
;         for (int b = 0; b < 2; ++b)
; #pragma unroll
;             for (int m = 0; m < 4; ++m)
; #pragma unroll
;                 for (int n = 0; n < 2; ++n) acc[a][b][m][n] = (f32x4){0.f, 0.f, 0.f, 0.f};
;     accx[0] = (f32x4){0.f, 0.f, 0.f, 0.f}; accx[1] = accx[0];
;     bf16x8 At[4][2], B0[2][2], B1[2][2], Ax[2];
;     const char* cA = PG8_APTR(cur); const char* cB = PG8_BPTR(cur);
;     S.a_ready(cur);
;     PG8_STAGE(PG8_SB(0, 0), cB, voffB); PG8_STAGE(PG8_SB(0, 1), cB + hstepB, voffB); PG8_STAGE(PG8_SA(0, 0), cA, voffA); PG8_STAGEX(0, cA + xstep); PG8_STAGE(PG8_SA(0, 1), cA + hstepA, voffA);
;     if (wr == 1) PG8_BAR;
;     PG8_WAIT_V(2); PG8_BAR;
;     PG8_STAGE(PG8_SB(1, 0), cB + kstep, voffB); PG8_STAGE(PG8_SA(1, 0), cA + kstep, voffA); PG8_STAGE(PG8_SB(1, 1), cB + hstepB + kstep, voffB);
;     PG8_WAIT_V(6); PG8_BAR;
.LBB0_1250:
	s_mov_b64 s[4:5], s[30:31]
	s_mov_b64 s[0:1], s[30:31]
	s_mov_b64 s[8:9], s[30:31]
	v_mov_b32_e32 v4, v0
	s_andn2_b64 vcc, exec, s[96:97]
	v_readfirstlane_b32 s20, v4
	s_cbranch_vccnz .LBB0_1249
	v_bfe_i32 v7, v4, 27, 1
	v_lshlrev_b32_e32 v5, 4, v4
	v_lshrrev_b32_e32 v7, 22, v7
	v_add_u32_e32 v7, v5, v7
	v_and_b32_e32 v7, 0xfffffc00, v7
	v_sub_u32_e32 v7, v5, v7
	v_lshrrev_b32_e32 v8, 4, v7
	v_ashrrev_i32_e32 v6, 31, v4
	v_bitop3_b32 v7, v8, v7, 32 bitop3:0x6c
	s_add_u32 s13, s4, 0x30084000
	v_lshrrev_b32_e32 v6, 26, v6
	v_ashrrev_i32_e32 v9, 31, v7
	s_addc_u32 s14, s5, 0
	v_readlane_b32 s5, v255, 17
	v_add_u32_e32 v6, v4, v6
	v_lshrrev_b32_e32 v9, 26, v9
	s_mul_i32 s4, s5, 0x1600000
	v_ashrrev_i32_e32 v6, 6, v6
	v_add_u32_e32 v9, v7, v9
	s_add_u32 s0, s0, s4
	s_mul_hi_u32 s4, s5, 0x1600000
	v_lshlrev_b32_e32 v8, 3, v6
	v_ashrrev_i32_e32 v10, 6, v9
	v_and_b32_e32 v9, 0xc0, v9
	s_addc_u32 s1, s1, s4
	v_and_b32_e32 v8, -16, v8
	v_lshlrev_b32_e32 v6, 5, v6
	v_sub_u32_e32 v7, v7, v9
	s_add_u32 s15, s0, 0x102a0000
	v_add_u32_e32 v8, v10, v8
	v_and_b32_e32 v6, 32, v6
	v_ashrrev_i16_sdwa v7, v1, sext(v7) dst_sel:DWORD dst_unused:UNUSED_PAD src0_sel:DWORD src1_sel:BYTE_0
	s_addc_u32 s16, s1, 0
	v_add_u32_sdwa v6, v6, sext(v7) dst_sel:DWORD dst_unused:UNUSED_PAD src0_sel:DWORD src1_sel:WORD_0
	v_lshlrev_b32_e32 v7, 1, v8
	v_lshrrev_b32_e32 v9, 2, v8
	v_and_b32_e32 v10, 3, v10
	s_mov_b32 s1, 0x7fffe0
	v_and_b32_e32 v7, 24, v7
	v_and_b32_e32 v9, 4, v9
	v_and_or_b32 v10, v8, s1, v10
	v_or3_b32 v7, v10, v9, v7
	s_movk_i32 s4, 0x1600
	v_mul_lo_u32 v8, v8, s4
	v_mul_u32_u24_e32 v7, 0x1600, v7
	v_add_u32_e32 v5, 0x2000, v5
	v_add_lshl_u32 v225, v6, v8, 1
	v_add_lshl_u32 v226, v7, v6, 1
	v_ashrrev_i32_e32 v6, 31, v5
	v_lshrrev_b32_e32 v6, 22, v6
	v_add_u32_e32 v6, v5, v6
	v_ashrrev_i32_e32 v6, 10, v6
	v_mul_i32_i24_e32 v7, 0x400, v6
	v_sub_u32_e32 v5, v5, v7
	v_lshrrev_b32_e32 v7, 4, v5
	v_bitop3_b32 v5, v7, v5, 32 bitop3:0x6c
	v_ashrrev_i32_e32 v8, 31, v5
	v_lshrrev_b32_e32 v8, 26, v8
	v_add_u32_e32 v8, v5, v8
	v_lshlrev_b32_e32 v7, 3, v6
	v_ashrrev_i32_e32 v9, 6, v8
	v_and_b32_e32 v8, 0xc0, v8
	s_ashr_i32 s0, s20, 6
	v_and_b32_e32 v7, -16, v7
	v_lshlrev_b32_e32 v6, 5, v6
	v_sub_u32_e32 v5, v5, v8
	s_and_b32 s21, s0, 3
	v_add_u32_e32 v7, v9, v7
	v_and_b32_e32 v6, 32, v6
	v_ashrrev_i16_sdwa v5, v1, sext(v5) dst_sel:DWORD dst_unused:UNUSED_PAD src0_sel:DWORD src1_sel:BYTE_0
	v_and_b32_e32 v9, 3, v9
	v_add_u32_sdwa v5, v6, sext(v5) dst_sel:DWORD dst_unused:UNUSED_PAD src0_sel:DWORD src1_sel:WORD_0
	v_lshlrev_b32_e32 v6, 1, v7
	v_lshrrev_b32_e32 v8, 2, v7
	v_and_or_b32 v9, v7, s1, v9
	s_ashr_i32 s22, s20, 8
	s_lshl_b32 s0, s0, 10
	s_lshl_b32 s23, s21, 10
	v_readlane_b32 s1, v254, 50
	v_and_b32_e32 v6, 24, v6
	v_and_b32_e32 v8, 4, v8
	v_mul_lo_u32 v7, v7, s4
	s_add_u32 s4, s15, s1
	v_readlane_b32 s1, v254, 51
	v_or3_b32 v6, v9, v8, v6
	s_addc_u32 s5, s16, s1
	s_add_i32 s17, s0, 0
	v_mul_u32_u24_e32 v6, 0x1600, v6
	s_add_i32 s18, s17, 0x10000
	s_mov_b32 m0, s18
	s_nop 0
	global_load_lds_dwordx4 v226, s[4:5]
	v_add_lshl_u32 v228, v6, v5, 1
	s_add_i32 s19, s17, 0x12000
	s_mov_b32 m0, s19
	s_nop 0
	global_load_lds_dwordx4 v228, s[4:5]
	v_readlane_b32 s1, v254, 23
	s_mul_i32 s0, s1, s10
	s_add_u32 s6, s13, s0
	s_mul_hi_i32 s0, s1, s10
	s_addc_u32 s7, s14, s0
	s_add_u32 s0, s4, 0x160000
	s_addc_u32 s1, s5, 0
	s_add_i32 s24, s17, 0x14000
	s_mov_b32 m0, s24
	s_nop 0
	global_load_lds_dwordx4 v226, s[0:1]
	s_add_i32 s25, s17, 0x16000
	s_mov_b32 m0, s25
	s_nop 0
	global_load_lds_dwordx4 v228, s[0:1]
	v_readlane_b32 s0, v254, 37
	s_add_u32 s6, s6, s0
	v_readlane_b32 s0, v254, 36
	s_addc_u32 s7, s7, s0
	s_mov_b32 m0, s17
	s_nop 0
	global_load_lds_dwordx4 v225, s[6:7]
	v_add_lshl_u32 v227, v5, v7, 1
	s_add_i32 s28, s17, 0x2000
	s_mov_b32 m0, s28
	s_nop 0
	global_load_lds_dwordx4 v227, s[6:7]
	v_bfe_u32 v2, v4, 4, 2
	s_add_u32 s0, s6, 0x2c0000
	v_lshl_or_b32 v5, s21, 2, v2
	v_lshlrev_b32_e32 v232, 4, v5
	s_addc_u32 s1, s7, 0
	s_add_i32 s29, s23, 0
	v_and_b32_e32 v4, 15, v4
	v_mul_u32_u24_e32 v5, 0x2c00, v5
	s_add_i32 s23, s29, 0x20400
	v_lshl_or_b32 v229, v4, 4, v5
	v_xor_b32_e32 v229, v229, v232
	s_mov_b32 m0, s23
	s_nop 0
	global_load_lds_dwordx4 v229, s[0:1]
	s_add_u32 s0, s6, 0x160000
	s_addc_u32 s1, s7, 0
	s_add_i32 s30, s17, 0x4000
	s_mov_b32 m0, s30
	s_nop 0
	global_load_lds_dwordx4 v225, s[0:1]
	s_add_i32 s31, s17, 0x6000
	s_mov_b32 m0, s31
	s_nop 0
	global_load_lds_dwordx4 v227, s[0:1]
	s_cmp_eq_u32 s22, 1
	s_cselect_b64 s[0:1], -1, 0
	s_cmp_lg_u32 s22, 1
	s_cbranch_scc1 .LBB0_1253
	s_barrier
.LBB0_1253:
	s_add_u32 s42, s8, 0x2de84000
	v_lshlrev_b32_e32 v5, 3, v2
	v_lshlrev_b32_e32 v2, 4, v2
	v_lshlrev_b32_e32 v7, 2, v4
	s_addc_u32 s43, s9, 0
	v_lshl_or_b32 v6, v4, 6, v2
	s_lshl_b32 s8, s22, 13
	v_and_b32_e32 v7, 32, v7
	v_bitop3_b32 v8, v6, s8, v7 bitop3:0xde
	s_lshl_b32 s8, s21, 12
	v_bitop3_b32 v6, v6, s8, v7 bitop3:0xde
	s_add_u32 s8, s4, 0x80
	s_waitcnt vmcnt(2)
	s_barrier
	s_addc_u32 s9, s5, 0
	s_add_i32 s51, s17, 0x18000
	s_mov_b32 m0, s51
	s_nop 0
	global_load_lds_dwordx4 v226, s[8:9]
	s_add_i32 s52, s17, 0x1a000
	s_mov_b32 m0, s52
	s_nop 0
	global_load_lds_dwordx4 v228, s[8:9]
	s_add_u32 s8, s6, 0x80
	s_addc_u32 s9, s7, 0
	s_add_i32 s62, s17, 0x8000
	s_mov_b32 m0, s62
	s_nop 0
	global_load_lds_dwordx4 v225, s[8:9]
	s_add_i32 s63, s17, 0xa000
	s_mov_b32 m0, s63
	s_nop 0
	global_load_lds_dwordx4 v227, s[8:9]
	s_add_u32 s8, s4, 0x160080
	s_addc_u32 s9, s5, 0
	s_add_i32 s74, s17, 0x1c000
	s_mov_b32 m0, s74
	s_nop 0
	global_load_lds_dwordx4 v226, s[8:9]
	s_add_i32 s75, s17, 0x1e000
	s_add_i32 s76, s17, 0xc000
	s_mov_b32 m0, s75
	s_nop 0
	global_load_lds_dwordx4 v228, s[8:9]
	s_cmpk_lt_u32 s20, 0x100
	s_waitcnt vmcnt(6)
	s_cselect_b64 s[44:45], -1, 0
	s_cmpk_gt_u32 s20, 0xff
	v_lshl_or_b32 v231, s21, 5, v5
	v_lshl_add_u32 v5, v4, 8, 0
	s_mov_b32 s8, 0x20400
	s_cselect_b64 s[46:47], -1, 0
	s_lshl_b32 s56, s22, 2
	v_lshl_or_b32 v230, s22, 6, v4
	v_lshlrev_b32_e32 v232, 4, v4
	v_xor_b32_e32 v232, v232, v2
	v_add3_u32 v232, v5, v232, s8
	v_or_b32_e32 v233, 0x100, v4
	s_ashr_i32 s57, s56, 31
	s_add_i32 s77, s17, 0xe000
	s_mov_b32 s78, 0
	v_add_u32_e32 v234, 0, v6
	v_add_u32_e32 v235, 0, v8
	v_readlane_b32 s84, v254, 40
	v_readlane_b32 s85, v254, 23
	s_barrier
	s_branch .LBB0_1256

; #define PG8_STAGE(bufoff, gbase, voff) do { _Pragma("unroll") for (int _i = 0; _i < 2; ++_i) glds16_s((voff)[_i], (const void*)(gbase), ldsbase + (unsigned)((bufoff) + _i * 8192) + ldsw); } while (0)
; #define PG8_LDA(dst, b, h) do { _Pragma("unroll") for (int m = 0; m < 4; ++m) _Pragma("unroll") for (int k = 0; k < 2; ++k) dst[m][k] = *(const PG8_LAS bf16x8*)(lds + PG8_SA(b, h) + aoff + m * 2048 + k * 1024); } while (0)
; #define PG8_MMA(ai, bj, At, Bt) do { __builtin_amdgcn_s_setprio(1); _Pragma("unroll") for (int m = 0; m < 4; ++m) _Pragma("unroll") for (int n = 0; n < 2; ++n) _Pragma("unroll") for (int k = 0; k < 2; ++k) \
;         acc[ai][bj][m][n] = __builtin_amdgcn_mfma_f32_16x16x32_bf16(Bt[n][k], At[m][k], acc[ai][bj][m][n], 0, 0, 0); __builtin_amdgcn_s_setprio(0); } while (0)
; #define PG8_WAIT_V(n) asm volatile("s_waitcnt vmcnt(" #n ")" ::: "memory")
; #define PG8_WAIT_L(n) asm volatile("s_waitcnt lgkmcnt(" #n ")" ::: "memory")
; #define PG8_BAR __builtin_amdgcn_s_barrier()
; #define PG8_SCHED __builtin_amdgcn_sched_barrier(0)
; template <class Epi, class Sched, bool HM = false>
; __device__ __forceinline__ void gemm_phase(PG8_LAS unsigned char* lds, const Gemm g, const Sched& S, const Epi& E) {
;     ...
;             if (!HM) PG8_LDA(At, 1, 1); PG8_STAGE(PG8_SB(1, 0), b3, voffB); PG8_STAGE(PG8_SB(1, 1), b3 + hstepB, voffB); PG8_STAGE(PG8_SA(1, 0), a3, voffA);
;             PG8_WAIT_V(8); PG8_WAIT_L(0); PG8_BAR; if (!HM) { PG8_MMA(1, 0, At, B0); PG8_MMA(1, 1, At, B1); } PG8_BAR; PG8_SCHED;
;         }
.LBB0_1267:
.LBB0_1268:
	s_barrier
	ds_read_b128 v[182:185], v235 offset:49152
	ds_read_b128 v[186:189], v235 offset:50176
	ds_read_b128 v[190:193], v235 offset:51200
	ds_read_b128 v[194:197], v235 offset:52224
	ds_read_b128 v[198:201], v235 offset:53248
	ds_read_b128 v[202:205], v235 offset:54272
	ds_read_b128 v[206:209], v235 offset:55296
	ds_read_b128 v[210:213], v235 offset:56320
	s_mov_b32 m0, s51
	s_nop 0
	global_load_lds_dwordx4 v226, s[6:7]
	s_nop 0
	s_mov_b32 m0, s52
	s_nop 0
	global_load_lds_dwordx4 v228, s[6:7]
	s_add_u32 s6, s6, 0x160000
	s_addc_u32 s7, s7, 0
	s_mov_b32 m0, s74
	s_nop 0
	global_load_lds_dwordx4 v226, s[6:7]
	s_nop 0
	s_mov_b32 m0, s75
	s_nop 0
	global_load_lds_dwordx4 v228, s[6:7]
	s_mov_b32 m0, s62
	s_nop 0
	global_load_lds_dwordx4 v225, s[4:5]
	s_nop 0
	s_mov_b32 m0, s63
	s_nop 0
	global_load_lds_dwordx4 v227, s[4:5]
	s_waitcnt vmcnt(8)
	s_waitcnt lgkmcnt(0)
	s_barrier
	s_setprio 1
	s_waitcnt lgkmcnt(7)
	v_mfma_f32_16x16x32_bf16 v[82:85], v[166:169], v[182:185], v[82:85]
	v_mfma_f32_16x16x32_bf16 v[78:81], v[174:177], v[182:185], v[78:81]
	s_waitcnt lgkmcnt(5)
	v_mfma_f32_16x16x32_bf16 v[74:77], v[166:169], v[190:193], v[74:77]
	v_mfma_f32_16x16x32_bf16 v[66:69], v[174:177], v[190:193], v[66:69]
	s_waitcnt lgkmcnt(3)
	v_mfma_f32_16x16x32_bf16 v[58:61], v[166:169], v[198:201], v[58:61]
	v_mfma_f32_16x16x32_bf16 v[50:53], v[174:177], v[198:201], v[50:53]
	s_waitcnt lgkmcnt(1)
	v_mfma_f32_16x16x32_bf16 v[42:45], v[166:169], v[206:209], v[42:45]
	v_mfma_f32_16x16x32_bf16 v[34:37], v[174:177], v[206:209], v[34:37]
	v_mfma_f32_16x16x32_bf16 v[82:85], v[170:173], v[186:189], v[82:85]
	v_mfma_f32_16x16x32_bf16 v[78:81], v[178:181], v[186:189], v[78:81]
	v_mfma_f32_16x16x32_bf16 v[74:77], v[170:173], v[194:197], v[74:77]
	v_mfma_f32_16x16x32_bf16 v[66:69], v[178:181], v[194:197], v[66:69]
	v_mfma_f32_16x16x32_bf16 v[58:61], v[170:173], v[202:205], v[58:61]
	v_mfma_f32_16x16x32_bf16 v[50:53], v[178:181], v[202:205], v[50:53]
	s_waitcnt lgkmcnt(0)
	v_mfma_f32_16x16x32_bf16 v[42:45], v[170:173], v[210:213], v[42:45]
	v_mfma_f32_16x16x32_bf16 v[34:37], v[178:181], v[210:213], v[34:37]
	s_setprio 0
	s_setprio 1
	v_mfma_f32_16x16x32_bf16 v[70:73], v[150:153], v[182:185], v[70:73]
	v_mfma_f32_16x16x32_bf16 v[62:65], v[158:161], v[182:185], v[62:65]
	v_mfma_f32_16x16x32_bf16 v[54:57], v[150:153], v[190:193], v[54:57]
	v_mfma_f32_16x16x32_bf16 v[46:49], v[158:161], v[190:193], v[46:49]
	v_mfma_f32_16x16x32_bf16 v[38:41], v[150:153], v[198:201], v[38:41]
	v_mfma_f32_16x16x32_bf16 v[30:33], v[158:161], v[198:201], v[30:33]
	v_mfma_f32_16x16x32_bf16 v[26:29], v[150:153], v[206:209], v[26:29]
	v_mfma_f32_16x16x32_bf16 v[22:25], v[158:161], v[206:209], v[22:25]
	v_mfma_f32_16x16x32_bf16 v[70:73], v[154:157], v[186:189], v[70:73]
	v_mfma_f32_16x16x32_bf16 v[62:65], v[162:165], v[186:189], v[62:65]
	v_mfma_f32_16x16x32_bf16 v[54:57], v[154:157], v[194:197], v[54:57]
	v_mfma_f32_16x16x32_bf16 v[46:49], v[162:165], v[194:197], v[46:49]
	v_mfma_f32_16x16x32_bf16 v[38:41], v[154:157], v[202:205], v[38:41]
	v_mfma_f32_16x16x32_bf16 v[30:33], v[162:165], v[202:205], v[30:33]
	v_mfma_f32_16x16x32_bf16 v[26:29], v[154:157], v[210:213], v[26:29]
	v_mfma_f32_16x16x32_bf16 v[22:25], v[162:165], v[210:213], v[22:25]
	s_setprio 0
	s_barrier
	s_add_i32 s23, s23, 2
	s_addk_i32 s22, 0x1000
	s_add_u32 s88, s88, 0x100
	s_addc_u32 s89, s89, 0
	s_add_u32 s27, s27, 0x100
	s_addc_u32 s82, s82, 0
	s_cmpk_gt_u32 s23, 0x55
	s_cbranch_scc1 .LBB0_1284

; #define PG8_STAGE(bufoff, gbase, voff) do { _Pragma("unroll") for (int _i = 0; _i < 2; ++_i) glds16_s((voff)[_i], (const void*)(gbase), ldsbase + (unsigned)((bufoff) + _i * 8192) + ldsw); } while (0)
; #define PG8_STAGEX(pb, gbase) glds16_s(voffX, (const void*)(gbase), ldsbase + (unsigned)(XOFF + (pb) * 4096) + ldsx)
; #define PG8_LDA(dst, b, h) do { _Pragma("unroll") for (int m = 0; m < 4; ++m) _Pragma("unroll") for (int k = 0; k < 2; ++k) dst[m][k] = *(const PG8_LAS bf16x8*)(lds + PG8_SA(b, h) + aoff + m * 2048 + k * 1024); } while (0)
; #define PG8_LDB(dst, b, h) do { _Pragma("unroll") for (int n = 0; n < 2; ++n) _Pragma("unroll") for (int k = 0; k < 2; ++k) dst[n][k] = *(const PG8_LAS bf16x8*)(lds + PG8_SB(b, h) + boff + n * 2048 + k * 1024); } while (0)
; #define PG8_LDX(pb, tp) do { _Pragma("unroll") for (int k = 0; k < 2; ++k) Ax[k] = *(const PG8_LAS bf16x8*)(lds + xoff + (pb) * 4096 + (tp) * 128 + k * 64); } while (0)
; #define PG8_MMA(ai, bj, At, Bt) do { __builtin_amdgcn_s_setprio(1); _Pragma("unroll") for (int m = 0; m < 4; ++m) _Pragma("unroll") for (int n = 0; n < 2; ++n) _Pragma("unroll") for (int k = 0; k < 2; ++k) \
;         acc[ai][bj][m][n] = __builtin_amdgcn_mfma_f32_16x16x32_bf16(Bt[n][k], At[m][k], acc[ai][bj][m][n], 0, 0, 0); __builtin_amdgcn_s_setprio(0); } while (0)
; #define PG8_WAIT_V(n) asm volatile("s_waitcnt vmcnt(" #n ")" ::: "memory")
; #define PG8_WAIT_L(n) asm volatile("s_waitcnt lgkmcnt(" #n ")" ::: "memory")
; #define PG8_BAR __builtin_amdgcn_s_barrier()
; #define PG8_SCHED __builtin_amdgcn_sched_barrier(0)
; template <class Epi, class Sched, bool HM = false>
; __device__ __forceinline__ void gemm_phase(PG8_LAS unsigned char* lds, const Gemm g, const Sched& S, const Epi& E) {
;     ...
;             PG8_LDB(B0, 0, 0); PG8_LDB(B1, 0, 1); PG8_SCHED; PG8_LDA(At, 0, 0); if (hasx) PG8_LDX(pb, 0); PG8_STAGE(PG8_SA(1, 1), a1 + hstepA, voffA); PG8_STAGEX(pb ^ 1, a2 + xstep);
;             PG8_WAIT_V(9); PG8_WAIT_L(0); PG8_BAR; PG8_MMA(0, 0, At, B0); PG8_MMA(0, 1, At, B1); if (hasx) PG8_MMAX(); PG8_BAR; PG8_SCHED;
.LBB0_1271:
	s_add_u32 s40, s40, 0x160000
	s_addc_u32 s41, s41, 0
	s_mov_b32 m0, s76
	s_nop 0
	global_load_lds_dwordx4 v225, s[40:41]
	s_nop 0
	s_mov_b32 m0, s77
	s_nop 0
	global_load_lds_dwordx4 v227, s[40:41]
	s_add_u32 s40, s8, 0x2c0000
	s_addc_u32 s41, s9, 0
	s_xor_b32 s20, s20, 0x21400
	s_add_i32 s20, s29, s20
	s_mov_b32 m0, s20
	s_nop 0
	global_load_lds_dwordx4 v229, s[40:41]
	s_waitcnt vmcnt(9)
	s_waitcnt lgkmcnt(0)
	s_barrier
	s_setprio 1
	s_waitcnt lgkmcnt(7)
	v_mfma_f32_16x16x32_bf16 v[146:149], v[166:169], v[206:209], v[146:149]
	v_mfma_f32_16x16x32_bf16 v[142:145], v[174:177], v[206:209], v[142:145]
	s_waitcnt lgkmcnt(5)
	v_mfma_f32_16x16x32_bf16 v[138:141], v[166:169], v[198:201], v[138:141]
	v_mfma_f32_16x16x32_bf16 v[130:133], v[174:177], v[198:201], v[130:133]
	s_waitcnt lgkmcnt(3)
	v_mfma_f32_16x16x32_bf16 v[122:125], v[166:169], v[190:193], v[122:125]
	v_mfma_f32_16x16x32_bf16 v[114:117], v[174:177], v[190:193], v[114:117]
	s_waitcnt lgkmcnt(1)
	v_mfma_f32_16x16x32_bf16 v[106:109], v[166:169], v[182:185], v[106:109]
	v_mfma_f32_16x16x32_bf16 v[98:101], v[174:177], v[182:185], v[98:101]
	v_mfma_f32_16x16x32_bf16 v[146:149], v[170:173], v[210:213], v[146:149]
	v_mfma_f32_16x16x32_bf16 v[142:145], v[178:181], v[210:213], v[142:145]
	v_mfma_f32_16x16x32_bf16 v[138:141], v[170:173], v[202:205], v[138:141]
	v_mfma_f32_16x16x32_bf16 v[130:133], v[178:181], v[202:205], v[130:133]
	v_mfma_f32_16x16x32_bf16 v[122:125], v[170:173], v[194:197], v[122:125]
	v_mfma_f32_16x16x32_bf16 v[114:117], v[178:181], v[194:197], v[114:117]
	s_waitcnt lgkmcnt(0)
	v_mfma_f32_16x16x32_bf16 v[106:109], v[170:173], v[186:189], v[106:109]
	v_mfma_f32_16x16x32_bf16 v[98:101], v[178:181], v[186:189], v[98:101]
	s_setprio 0
	s_setprio 1
	v_mfma_f32_16x16x32_bf16 v[134:137], v[150:153], v[206:209], v[134:137]
	v_mfma_f32_16x16x32_bf16 v[126:129], v[158:161], v[206:209], v[126:129]
	v_mfma_f32_16x16x32_bf16 v[118:121], v[150:153], v[198:201], v[118:121]
	v_mfma_f32_16x16x32_bf16 v[110:113], v[158:161], v[198:201], v[110:113]
	v_mfma_f32_16x16x32_bf16 v[102:105], v[150:153], v[190:193], v[102:105]
	v_mfma_f32_16x16x32_bf16 v[94:97], v[158:161], v[190:193], v[94:97]
	v_mfma_f32_16x16x32_bf16 v[90:93], v[150:153], v[182:185], v[90:93]
	v_mfma_f32_16x16x32_bf16 v[86:89], v[158:161], v[182:185], v[86:89]
	v_mfma_f32_16x16x32_bf16 v[134:137], v[154:157], v[210:213], v[134:137]
	v_mfma_f32_16x16x32_bf16 v[126:129], v[162:165], v[210:213], v[126:129]
	v_mfma_f32_16x16x32_bf16 v[118:121], v[154:157], v[202:205], v[118:121]
	v_mfma_f32_16x16x32_bf16 v[110:113], v[162:165], v[202:205], v[110:113]
	v_mfma_f32_16x16x32_bf16 v[102:105], v[154:157], v[194:197], v[102:105]
	v_mfma_f32_16x16x32_bf16 v[94:97], v[162:165], v[194:197], v[94:97]
	v_mfma_f32_16x16x32_bf16 v[90:93], v[154:157], v[186:189], v[90:93]
	v_mfma_f32_16x16x32_bf16 v[86:89], v[162:165], v[186:189], v[86:89]
	s_setprio 0
	v_cndmask_b32_e64 v4, 0, 1, s[46:47]
	s_and_b64 vcc, exec, s[38:39]
	v_cmp_ne_u32_e64 s[40:41], 1, v4
	s_cbranch_vccnz .LBB0_1277
	s_and_b64 vcc, exec, s[40:41]
	s_mov_b64 s[20:21], -1
	s_cbranch_vccnz .LBB0_1274
	v_mfma_f32_16x16x32_bf16 v[18:21], v[174:177], v[6:9], v[18:21]
	s_mov_b64 s[20:21], 0
	v_mfma_f32_16x16x32_bf16 v[14:17], v[158:161], v[6:9], v[14:17]
	v_mfma_f32_16x16x32_bf16 v[18:21], v[178:181], v[10:13], v[18:21]
	v_mfma_f32_16x16x32_bf16 v[14:17], v[162:165], v[10:13], v[14:17]

; #define PG8_STAGE(bufoff, gbase, voff) do { _Pragma("unroll") for (int _i = 0; _i < 2; ++_i) glds16_s((voff)[_i], (const void*)(gbase), ldsbase + (unsigned)((bufoff) + _i * 8192) + ldsw); } while (0)
; #define PG8_LDA(dst, b, h) do { _Pragma("unroll") for (int m = 0; m < 4; ++m) _Pragma("unroll") for (int k = 0; k < 2; ++k) dst[m][k] = *(const PG8_LAS bf16x8*)(lds + PG8_SA(b, h) + aoff + m * 2048 + k * 1024); } while (0)
; #define PG8_LDB(dst, b, h) do { _Pragma("unroll") for (int n = 0; n < 2; ++n) _Pragma("unroll") for (int k = 0; k < 2; ++k) dst[n][k] = *(const PG8_LAS bf16x8*)(lds + PG8_SB(b, h) + boff + n * 2048 + k * 1024); } while (0)
; #define PG8_LDX(pb, tp) do { _Pragma("unroll") for (int k = 0; k < 2; ++k) Ax[k] = *(const PG8_LAS bf16x8*)(lds + xoff + (pb) * 4096 + (tp) * 128 + k * 64); } while (0)
; #define PG8_MMA(ai, bj, At, Bt) do { __builtin_amdgcn_s_setprio(1); _Pragma("unroll") for (int m = 0; m < 4; ++m) _Pragma("unroll") for (int n = 0; n < 2; ++n) _Pragma("unroll") for (int k = 0; k < 2; ++k) \
;         acc[ai][bj][m][n] = __builtin_amdgcn_mfma_f32_16x16x32_bf16(Bt[n][k], At[m][k], acc[ai][bj][m][n], 0, 0, 0); __builtin_amdgcn_s_setprio(0); } while (0)
; #define PG8_WAIT_V(n) asm volatile("s_waitcnt vmcnt(" #n ")" ::: "memory")
; #define PG8_WAIT_L(n) asm volatile("s_waitcnt lgkmcnt(" #n ")" ::: "memory")
; #define PG8_BAR __builtin_amdgcn_s_barrier()
; #define PG8_SCHED __builtin_amdgcn_sched_barrier(0)
; template <class Epi, class Sched, bool HM = false>
; __device__ __forceinline__ void gemm_phase(PG8_LAS unsigned char* lds, const Gemm g, const Sched& S, const Epi& E) {
;     ...
;             if (!HM) PG8_LDA(At, 0, 1); PG8_STAGE(PG8_SB(0, 0), b2, voffB); PG8_STAGE(PG8_SB(0, 1), b2 + hstepB, voffB); PG8_STAGE(PG8_SA(0, 0), a2, voffA);
;             PG8_WAIT_V(9); PG8_WAIT_L(0); PG8_BAR; if (!HM) { PG8_MMA(1, 0, At, B0); PG8_MMA(1, 1, At, B1); } PG8_BAR; PG8_SCHED;
;             PG8_LDB(B0, 1, 0); PG8_LDB(B1, 1, 1); PG8_SCHED; PG8_LDA(At, 1, 0); if (hasx) PG8_LDX(pb, 1); PG8_STAGE(PG8_SA(0, 1), a2 + hstepA, voffA);
.LBB0_1276:
.LBB0_1277:
	s_barrier
	ds_read_b128 v[182:185], v235 offset:16384
	ds_read_b128 v[186:189], v235 offset:17408
	ds_read_b128 v[190:193], v235 offset:18432
	ds_read_b128 v[194:197], v235 offset:19456
	ds_read_b128 v[198:201], v235 offset:20480
	ds_read_b128 v[202:205], v235 offset:21504
	ds_read_b128 v[206:209], v235 offset:22528
	ds_read_b128 v[210:213], v235 offset:23552
	s_mov_b32 m0, s18
	s_nop 0
	global_load_lds_dwordx4 v226, s[34:35]
	s_nop 0
	s_mov_b32 m0, s19
	s_nop 0
	global_load_lds_dwordx4 v228, s[34:35]
	s_add_u32 s20, s34, 0x160000
	s_addc_u32 s21, s35, 0
	s_mov_b32 m0, s24
	s_nop 0
	global_load_lds_dwordx4 v226, s[20:21]
	s_nop 0
	s_mov_b32 m0, s25
	s_nop 0
	global_load_lds_dwordx4 v228, s[20:21]
	s_mov_b32 m0, s17
	s_nop 0
	global_load_lds_dwordx4 v225, s[8:9]
	s_nop 0
	s_mov_b32 m0, s28
	s_nop 0
	global_load_lds_dwordx4 v227, s[8:9]
	s_waitcnt vmcnt(9)
	s_waitcnt lgkmcnt(0)
	s_barrier
	s_setprio 1
	s_waitcnt lgkmcnt(7)
	v_mfma_f32_16x16x32_bf16 v[82:85], v[166:169], v[182:185], v[82:85]
	v_mfma_f32_16x16x32_bf16 v[78:81], v[174:177], v[182:185], v[78:81]
	s_waitcnt lgkmcnt(5)
	v_mfma_f32_16x16x32_bf16 v[74:77], v[166:169], v[190:193], v[74:77]
	v_mfma_f32_16x16x32_bf16 v[66:69], v[174:177], v[190:193], v[66:69]
	s_waitcnt lgkmcnt(3)
	v_mfma_f32_16x16x32_bf16 v[58:61], v[166:169], v[198:201], v[58:61]
	v_mfma_f32_16x16x32_bf16 v[50:53], v[174:177], v[198:201], v[50:53]
	s_waitcnt lgkmcnt(1)
	v_mfma_f32_16x16x32_bf16 v[42:45], v[166:169], v[206:209], v[42:45]
	v_mfma_f32_16x16x32_bf16 v[34:37], v[174:177], v[206:209], v[34:37]
	v_mfma_f32_16x16x32_bf16 v[82:85], v[170:173], v[186:189], v[82:85]
	v_mfma_f32_16x16x32_bf16 v[78:81], v[178:181], v[186:189], v[78:81]
	v_mfma_f32_16x16x32_bf16 v[74:77], v[170:173], v[194:197], v[74:77]
	v_mfma_f32_16x16x32_bf16 v[66:69], v[178:181], v[194:197], v[66:69]
	v_mfma_f32_16x16x32_bf16 v[58:61], v[170:173], v[202:205], v[58:61]
	v_mfma_f32_16x16x32_bf16 v[50:53], v[178:181], v[202:205], v[50:53]
	s_waitcnt lgkmcnt(0)
	v_mfma_f32_16x16x32_bf16 v[42:45], v[170:173], v[210:213], v[42:45]
	v_mfma_f32_16x16x32_bf16 v[34:37], v[178:181], v[210:213], v[34:37]
	s_setprio 0
	s_setprio 1
	v_mfma_f32_16x16x32_bf16 v[70:73], v[150:153], v[182:185], v[70:73]
	v_mfma_f32_16x16x32_bf16 v[62:65], v[158:161], v[182:185], v[62:65]
	v_mfma_f32_16x16x32_bf16 v[54:57], v[150:153], v[190:193], v[54:57]
	v_mfma_f32_16x16x32_bf16 v[46:49], v[158:161], v[190:193], v[46:49]
	v_mfma_f32_16x16x32_bf16 v[38:41], v[150:153], v[198:201], v[38:41]
	v_mfma_f32_16x16x32_bf16 v[30:33], v[158:161], v[198:201], v[30:33]
	v_mfma_f32_16x16x32_bf16 v[26:29], v[150:153], v[206:209], v[26:29]
	v_mfma_f32_16x16x32_bf16 v[22:25], v[158:161], v[206:209], v[22:25]
	v_mfma_f32_16x16x32_bf16 v[70:73], v[154:157], v[186:189], v[70:73]
	v_mfma_f32_16x16x32_bf16 v[62:65], v[162:165], v[186:189], v[62:65]
	v_mfma_f32_16x16x32_bf16 v[54:57], v[154:157], v[194:197], v[54:57]
	v_mfma_f32_16x16x32_bf16 v[46:49], v[162:165], v[194:197], v[46:49]
	v_mfma_f32_16x16x32_bf16 v[38:41], v[154:157], v[202:205], v[38:41]
	v_mfma_f32_16x16x32_bf16 v[30:33], v[162:165], v[202:205], v[30:33]
	v_mfma_f32_16x16x32_bf16 v[26:29], v[154:157], v[210:213], v[26:29]
	v_mfma_f32_16x16x32_bf16 v[22:25], v[162:165], v[210:213], v[22:25]
	s_setprio 0
	s_barrier
	v_add_u32_e32 v4, 0x18000, v234
	ds_read_b128 v[166:169], v4
	ds_read_b128 v[170:173], v4 offset:1024
	ds_read_b128 v[174:177], v4 offset:2048
	ds_read_b128 v[178:181], v4 offset:3072
	v_add_u32_e32 v4, 0x1c000, v234
	ds_read_b128 v[150:153], v4
	ds_read_b128 v[154:157], v4 offset:1024
	ds_read_b128 v[158:161], v4 offset:2048
	ds_read_b128 v[162:165], v4 offset:3072
	ds_read_b128 v[206:209], v235 offset:32768
	ds_read_b128 v[210:213], v235 offset:33792
	ds_read_b128 v[198:201], v235 offset:34816
	ds_read_b128 v[202:205], v235 offset:35840
	ds_read_b128 v[190:193], v235 offset:36864
	ds_read_b128 v[194:197], v235 offset:37888
	ds_read_b128 v[182:185], v235 offset:38912
	ds_read_b128 v[186:189], v235 offset:39936
	s_and_b64 vcc, exec, s[38:39]
	s_cbranch_vccnz .LBB0_1279
	v_xor_b32_e32 v6, 0x80, v2
	ds_read_b128 v[6:9], v6
	v_xor_b32_e32 v10, 0xc0, v2
	ds_read_b128 v[10:13], v10
; #define PG8_STAGE(bufoff, gbase, voff) do { _Pragma("unroll") for (int _i = 0; _i < 2; ++_i) glds16_s((voff)[_i], (const void*)(gbase), ldsbase + (unsigned)((bufoff) + _i * 8192) + ldsw); } while (0)
; #define PG8_LDA(dst, b, h) do { _Pragma("unroll") for (int m = 0; m < 4; ++m) _Pragma("unroll") for (int k = 0; k < 2; ++k) dst[m][k] = *(const PG8_LAS bf16x8*)(lds + PG8_SA(b, h) + aoff + m * 2048 + k * 1024); } while (0)
; #define PG8_LDB(dst, b, h) do { _Pragma("unroll") for (int n = 0; n < 2; ++n) _Pragma("unroll") for (int k = 0; k < 2; ++k) dst[n][k] = *(const PG8_LAS bf16x8*)(lds + PG8_SB(b, h) + boff + n * 2048 + k * 1024); } while (0)
; #define PG8_LDX(pb, tp) do { _Pragma("unroll") for (int k = 0; k < 2; ++k) Ax[k] = *(const PG8_LAS bf16x8*)(lds + xoff + (pb) * 4096 + (tp) * 128 + k * 64); } while (0)
; #define PG8_MMA(ai, bj, At, Bt) do { __builtin_amdgcn_s_setprio(1); _Pragma("unroll") for (int m = 0; m < 4; ++m) _Pragma("unroll") for (int n = 0; n < 2; ++n) _Pragma("unroll") for (int k = 0; k < 2; ++k) \
;         acc[ai][bj][m][n] = __builtin_amdgcn_mfma_f32_16x16x32_bf16(Bt[n][k], At[m][k], acc[ai][bj][m][n], 0, 0, 0); __builtin_amdgcn_s_setprio(0); } while (0)
; #define PG8_WAIT_V(n) asm volatile("s_waitcnt vmcnt(" #n ")" ::: "memory")
; #define PG8_WAIT_L(n) asm volatile("s_waitcnt lgkmcnt(" #n ")" ::: "memory")
; #define PG8_BAR __builtin_amdgcn_s_barrier()
; #define PG8_SCHED __builtin_amdgcn_sched_barrier(0)
; template <class Epi, class Sched, bool HM = false>
; __device__ __forceinline__ void gemm_phase(PG8_LAS unsigned char* lds, const Gemm g, const Sched& S, const Epi& E) {
;     ...
;             PG8_LDB(B0, 1, 0); PG8_LDB(B1, 1, 1); PG8_SCHED; PG8_LDA(At, 1, 0); if (hasx) PG8_LDX(pb, 1); PG8_STAGE(PG8_SA(0, 1), a2 + hstepA, voffA);
;             PG8_WAIT_V(9); PG8_WAIT_L(0); PG8_BAR; PG8_MMA(0, 0, At, B0); PG8_MMA(0, 1, At, B1); if (hasx) PG8_MMAX(); PG8_BAR; PG8_SCHED;
.LBB0_1279:
	s_add_u32 s8, s8, 0x160000
	s_addc_u32 s9, s9, 0
	s_mov_b32 m0, s30
	s_nop 0
	global_load_lds_dwordx4 v225, s[8:9]
	s_nop 0
	s_mov_b32 m0, s31
	s_nop 0
	global_load_lds_dwordx4 v227, s[8:9]
	s_waitcnt vmcnt(9)
	s_waitcnt lgkmcnt(0)
	s_barrier
	s_setprio 1
	s_waitcnt lgkmcnt(7)
	v_mfma_f32_16x16x32_bf16 v[146:149], v[166:169], v[206:209], v[146:149]
	v_mfma_f32_16x16x32_bf16 v[142:145], v[174:177], v[206:209], v[142:145]
	s_waitcnt lgkmcnt(5)
	v_mfma_f32_16x16x32_bf16 v[138:141], v[166:169], v[198:201], v[138:141]
	v_mfma_f32_16x16x32_bf16 v[130:133], v[174:177], v[198:201], v[130:133]
	s_waitcnt lgkmcnt(3)
	v_mfma_f32_16x16x32_bf16 v[122:125], v[166:169], v[190:193], v[122:125]
	v_mfma_f32_16x16x32_bf16 v[114:117], v[174:177], v[190:193], v[114:117]
	s_waitcnt lgkmcnt(1)
	v_mfma_f32_16x16x32_bf16 v[106:109], v[166:169], v[182:185], v[106:109]
	v_mfma_f32_16x16x32_bf16 v[98:101], v[174:177], v[182:185], v[98:101]
	v_mfma_f32_16x16x32_bf16 v[146:149], v[170:173], v[210:213], v[146:149]
	v_mfma_f32_16x16x32_bf16 v[142:145], v[178:181], v[210:213], v[142:145]
	v_mfma_f32_16x16x32_bf16 v[138:141], v[170:173], v[202:205], v[138:141]
	v_mfma_f32_16x16x32_bf16 v[130:133], v[178:181], v[202:205], v[130:133]
	v_mfma_f32_16x16x32_bf16 v[122:125], v[170:173], v[194:197], v[122:125]
	v_mfma_f32_16x16x32_bf16 v[114:117], v[178:181], v[194:197], v[114:117]
	s_waitcnt lgkmcnt(0)
	v_mfma_f32_16x16x32_bf16 v[106:109], v[170:173], v[186:189], v[106:109]
	v_mfma_f32_16x16x32_bf16 v[98:101], v[178:181], v[186:189], v[98:101]
	s_setprio 0
	s_setprio 1
	v_mfma_f32_16x16x32_bf16 v[134:137], v[150:153], v[206:209], v[134:137]
	v_mfma_f32_16x16x32_bf16 v[126:129], v[158:161], v[206:209], v[126:129]
	v_mfma_f32_16x16x32_bf16 v[118:121], v[150:153], v[198:201], v[118:121]
	v_mfma_f32_16x16x32_bf16 v[110:113], v[158:161], v[198:201], v[110:113]
	v_mfma_f32_16x16x32_bf16 v[102:105], v[150:153], v[190:193], v[102:105]
	v_mfma_f32_16x16x32_bf16 v[94:97], v[158:161], v[190:193], v[94:97]
	v_mfma_f32_16x16x32_bf16 v[90:93], v[150:153], v[182:185], v[90:93]
	v_mfma_f32_16x16x32_bf16 v[86:89], v[158:161], v[182:185], v[86:89]
	v_mfma_f32_16x16x32_bf16 v[134:137], v[154:157], v[210:213], v[134:137]
	v_mfma_f32_16x16x32_bf16 v[126:129], v[162:165], v[210:213], v[126:129]
	v_mfma_f32_16x16x32_bf16 v[118:121], v[154:157], v[202:205], v[118:121]
	v_mfma_f32_16x16x32_bf16 v[110:113], v[162:165], v[202:205], v[110:113]
	v_mfma_f32_16x16x32_bf16 v[102:105], v[154:157], v[194:197], v[102:105]
	v_mfma_f32_16x16x32_bf16 v[94:97], v[162:165], v[194:197], v[94:97]
	v_mfma_f32_16x16x32_bf16 v[90:93], v[154:157], v[186:189], v[90:93]
	v_mfma_f32_16x16x32_bf16 v[86:89], v[162:165], v[186:189], v[86:89]
	s_setprio 0
	s_and_b64 vcc, exec, s[38:39]
	s_cbranch_vccnz .LBB0_1268
	s_and_b64 vcc, exec, s[40:41]
	s_mov_b64 s[8:9], -1
	s_cbranch_vccnz .LBB0_1282
	v_mfma_f32_16x16x32_bf16 v[18:21], v[174:177], v[6:9], v[18:21]
	s_mov_b64 s[8:9], 0
	v_mfma_f32_16x16x32_bf16 v[14:17], v[158:161], v[6:9], v[14:17]
	v_mfma_f32_16x16x32_bf16 v[18:21], v[178:181], v[10:13], v[18:21]
	v_mfma_f32_16x16x32_bf16 v[14:17], v[162:165], v[10:13], v[14:17]
